# weight transpose/staging loops: all 32 row loads of a block in flight (P0, quant phase unrolled x2 on a second register set; P4b FFN2 staging loops rewritten as streaming loads + counted waits)
# speedup vs baseline: 1.0068x; 1.0068x over previous
.LBB0_176:
	s_lshl_b32 s12, s5, 1
	s_lshl_b32 s14, s8, 1
	v_or_b32_e32 v24, s14, v18
	s_add_i32 s16, s12, 4
	s_add_i32 s17, s14, 4
	s_add_i32 s18, s12, 8
	s_add_i32 s19, s14, 8
	s_add_i32 s23, s12, 12
	s_add_i32 s26, s14, 12
	s_add_i32 s27, s12, 16
	s_add_i32 s28, s14, 16
	s_add_i32 s29, s12, 20
	s_add_i32 s30, s14, 20
	s_add_i32 s31, s12, 24
	s_add_i32 s33, s14, 24
	s_add_i32 s34, s12, 28
	s_add_i32 s35, s14, 28
	v_or_b32_e32 v22, s12, v3
	v_ashrrev_i32_e32 v25, 31, v24
	v_or_b32_e32 v26, s16, v3
	v_or_b32_e32 v28, s17, v18
	v_or_b32_e32 v32, s18, v3
	v_or_b32_e32 v34, s19, v18
	v_or_b32_e32 v36, s23, v3
	v_or_b32_e32 v38, s26, v18
	v_or_b32_e32 v40, s27, v3
	v_or_b32_e32 v42, s28, v18
	v_or_b32_e32 v44, s29, v3
	v_or_b32_e32 v46, s30, v18
	v_or_b32_e32 v48, s31, v3
	v_or_b32_e32 v50, s33, v18
	v_or_b32_e32 v52, s34, v3
	v_or_b32_e32 v54, s35, v18
	v_ashrrev_i32_e32 v23, 31, v22
	v_lshlrev_b64 v[24:25], 13, v[24:25]
	v_ashrrev_i32_e32 v29, 31, v28
	v_ashrrev_i32_e32 v27, 31, v26
	v_ashrrev_i32_e32 v35, 31, v34
	v_ashrrev_i32_e32 v33, 31, v32
	v_ashrrev_i32_e32 v39, 31, v38
	v_ashrrev_i32_e32 v37, 31, v36
	v_ashrrev_i32_e32 v43, 31, v42
	v_ashrrev_i32_e32 v41, 31, v40
	v_ashrrev_i32_e32 v47, 31, v46
	v_ashrrev_i32_e32 v45, 31, v44
	v_ashrrev_i32_e32 v51, 31, v50
	v_ashrrev_i32_e32 v49, 31, v48
	v_ashrrev_i32_e32 v55, 31, v54
	v_ashrrev_i32_e32 v53, 31, v52
	v_lshlrev_b64 v[22:23], 13, v[22:23]
	v_lshl_add_u64 v[24:25], v[16:17], 0, v[24:25]
	v_lshlrev_b64 v[26:27], 13, v[26:27]
	v_lshlrev_b64 v[28:29], 13, v[28:29]
	v_lshlrev_b64 v[32:33], 13, v[32:33]
	v_lshlrev_b64 v[34:35], 13, v[34:35]
	v_lshlrev_b64 v[36:37], 13, v[36:37]
	v_lshlrev_b64 v[38:39], 13, v[38:39]
	v_lshlrev_b64 v[40:41], 13, v[40:41]
	v_lshlrev_b64 v[42:43], 13, v[42:43]
	v_lshlrev_b64 v[44:45], 13, v[44:45]
	v_lshlrev_b64 v[46:47], 13, v[46:47]
	v_lshlrev_b64 v[48:49], 13, v[48:49]
	v_lshlrev_b64 v[50:51], 13, v[50:51]
	v_lshlrev_b64 v[52:53], 13, v[52:53]
	v_lshlrev_b64 v[54:55], 13, v[54:55]
	v_lshl_add_u64 v[22:23], v[16:17], 0, v[22:23]
	v_lshl_add_u64 v[28:29], v[16:17], 0, v[28:29]
	v_lshl_add_u64 v[26:27], v[16:17], 0, v[26:27]
	v_lshl_add_u64 v[34:35], v[16:17], 0, v[34:35]
	v_lshl_add_u64 v[32:33], v[16:17], 0, v[32:33]
	v_lshl_add_u64 v[38:39], v[16:17], 0, v[38:39]
	v_lshl_add_u64 v[36:37], v[16:17], 0, v[36:37]
	v_lshl_add_u64 v[42:43], v[16:17], 0, v[42:43]
	v_lshl_add_u64 v[40:41], v[16:17], 0, v[40:41]
	v_lshl_add_u64 v[46:47], v[16:17], 0, v[46:47]
	v_lshl_add_u64 v[44:45], v[16:17], 0, v[44:45]
	v_lshl_add_u64 v[50:51], v[16:17], 0, v[50:51]
	v_lshl_add_u64 v[48:49], v[16:17], 0, v[48:49]
	v_lshl_add_u64 v[54:55], v[16:17], 0, v[54:55]
	v_lshl_add_u64 v[52:53], v[16:17], 0, v[52:53]
	global_load_dword v21, v[24:25], off
	global_load_dword v30, v[22:23], off
	global_load_dword v56, v[28:29], off
	global_load_dword v57, v[26:27], off
	global_load_dword v58, v[34:35], off
	global_load_dword v59, v[32:33], off
	global_load_dword v60, v[38:39], off
	global_load_dword v61, v[36:37], off
	global_load_dword v62, v[42:43], off
	global_load_dword v63, v[40:41], off
	global_load_dword v64, v[46:47], off
	global_load_dword v65, v[44:45], off
	global_load_dword v66, v[50:51], off
	global_load_dword v67, v[48:49], off
	global_load_dword v68, v[54:55], off
	global_load_dword v69, v[52:53], off
	v_or_b32_e32 v24, s12, v1
	v_or_b32_e32 v22, s14, v2
	s_add_i32 s8, s8, 16
	s_add_i32 s5, s5, 16
	s_add_i32 s9, s9, -16
	v_mad_u64_u32 v[22:23], s[24:25], v22, s3, v[12:13]
	v_mad_u64_u32 v[24:25], s[24:25], v24, s3, v[12:13]
	v_or_b32_e32 v23, s16, v1
	v_or_b32_e32 v25, s17, v2
	v_or_b32_e32 v34, s18, v1
	v_or_b32_e32 v32, s19, v2
	v_or_b32_e32 v38, s23, v1
	v_or_b32_e32 v36, s26, v2
	v_or_b32_e32 v42, s27, v1
	v_or_b32_e32 v40, s28, v2
	v_or_b32_e32 v46, s29, v1
	v_or_b32_e32 v44, s30, v2
	v_or_b32_e32 v50, s31, v1
	v_or_b32_e32 v48, s33, v2
	v_or_b32_e32 v54, s34, v1
	v_or_b32_e32 v52, s35, v2
	s_cmp_lg_u32 s9, 0
	v_mad_u64_u32 v[26:27], s[16:17], v25, s3, v[12:13]
	v_mad_u64_u32 v[28:29], s[16:17], v23, s3, v[12:13]
	v_mad_u64_u32 v[32:33], s[16:17], v32, s3, v[12:13]
	v_mad_u64_u32 v[34:35], s[16:17], v34, s3, v[12:13]
	v_mad_u64_u32 v[36:37], s[16:17], v36, s3, v[12:13]
	v_mad_u64_u32 v[38:39], s[16:17], v38, s3, v[12:13]
	v_mad_u64_u32 v[40:41], s[16:17], v40, s3, v[12:13]
	v_mad_u64_u32 v[42:43], s[16:17], v42, s3, v[12:13]
	v_mad_u64_u32 v[44:45], s[16:17], v44, s3, v[12:13]
	v_mad_u64_u32 v[46:47], s[16:17], v46, s3, v[12:13]
	v_mad_u64_u32 v[48:49], s[16:17], v48, s3, v[12:13]
	v_mad_u64_u32 v[50:51], s[16:17], v50, s3, v[12:13]
	v_mad_u64_u32 v[52:53], s[16:17], v52, s3, v[12:13]
	v_mad_u64_u32 v[54:55], s[16:17], v54, s3, v[12:13]
	s_lshl_b32 s12, s5, 1
	s_lshl_b32 s14, s8, 1
	v_or_b32_e32 v100, s14, v18
	s_add_i32 s16, s12, 4
	s_add_i32 s17, s14, 4
	s_add_i32 s18, s12, 8
	s_add_i32 s19, s14, 8
	s_add_i32 s23, s12, 12
	s_add_i32 s26, s14, 12
	s_add_i32 s27, s12, 16
	s_add_i32 s28, s14, 16
	s_add_i32 s29, s12, 20
	s_add_i32 s30, s14, 20
	s_add_i32 s31, s12, 24
	s_add_i32 s33, s14, 24
	s_add_i32 s34, s12, 28
	s_add_i32 s35, s14, 28
	v_or_b32_e32 v98, s12, v3
	v_ashrrev_i32_e32 v101, 31, v100
	v_or_b32_e32 v102, s16, v3
	v_or_b32_e32 v104, s17, v18
	v_or_b32_e32 v108, s18, v3
	v_or_b32_e32 v110, s19, v18
	v_or_b32_e32 v112, s23, v3
	v_or_b32_e32 v114, s26, v18
	v_or_b32_e32 v116, s27, v3
	v_or_b32_e32 v118, s28, v18
	v_or_b32_e32 v120, s29, v3
	v_or_b32_e32 v122, s30, v18
	v_or_b32_e32 v124, s31, v3
	v_or_b32_e32 v126, s33, v18
	v_or_b32_e32 v128, s34, v3
	v_or_b32_e32 v130, s35, v18
	v_ashrrev_i32_e32 v99, 31, v98
	v_lshlrev_b64 v[100:101], 13, v[100:101]
	v_ashrrev_i32_e32 v105, 31, v104
	v_ashrrev_i32_e32 v103, 31, v102
	v_ashrrev_i32_e32 v111, 31, v110
	v_ashrrev_i32_e32 v109, 31, v108
	v_ashrrev_i32_e32 v115, 31, v114
	v_ashrrev_i32_e32 v113, 31, v112
	v_ashrrev_i32_e32 v119, 31, v118
	v_ashrrev_i32_e32 v117, 31, v116
	v_ashrrev_i32_e32 v123, 31, v122
	v_ashrrev_i32_e32 v121, 31, v120
	v_ashrrev_i32_e32 v127, 31, v126
	v_ashrrev_i32_e32 v125, 31, v124
	v_ashrrev_i32_e32 v131, 31, v130
	v_ashrrev_i32_e32 v129, 31, v128
	v_lshlrev_b64 v[98:99], 13, v[98:99]
	v_lshl_add_u64 v[100:101], v[16:17], 0, v[100:101]
	v_lshlrev_b64 v[102:103], 13, v[102:103]
	v_lshlrev_b64 v[104:105], 13, v[104:105]
	v_lshlrev_b64 v[108:109], 13, v[108:109]
	v_lshlrev_b64 v[110:111], 13, v[110:111]
	v_lshlrev_b64 v[112:113], 13, v[112:113]
	v_lshlrev_b64 v[114:115], 13, v[114:115]
	v_lshlrev_b64 v[116:117], 13, v[116:117]
	v_lshlrev_b64 v[118:119], 13, v[118:119]
	v_lshlrev_b64 v[120:121], 13, v[120:121]
	v_lshlrev_b64 v[122:123], 13, v[122:123]
	v_lshlrev_b64 v[124:125], 13, v[124:125]
	v_lshlrev_b64 v[126:127], 13, v[126:127]
	v_lshlrev_b64 v[128:129], 13, v[128:129]
	v_lshlrev_b64 v[130:131], 13, v[130:131]
	v_lshl_add_u64 v[98:99], v[16:17], 0, v[98:99]
	v_lshl_add_u64 v[104:105], v[16:17], 0, v[104:105]
	v_lshl_add_u64 v[102:103], v[16:17], 0, v[102:103]
	v_lshl_add_u64 v[110:111], v[16:17], 0, v[110:111]
	v_lshl_add_u64 v[108:109], v[16:17], 0, v[108:109]
	v_lshl_add_u64 v[114:115], v[16:17], 0, v[114:115]
	v_lshl_add_u64 v[112:113], v[16:17], 0, v[112:113]
	v_lshl_add_u64 v[118:119], v[16:17], 0, v[118:119]
	v_lshl_add_u64 v[116:117], v[16:17], 0, v[116:117]
	v_lshl_add_u64 v[122:123], v[16:17], 0, v[122:123]
	v_lshl_add_u64 v[120:121], v[16:17], 0, v[120:121]
	v_lshl_add_u64 v[126:127], v[16:17], 0, v[126:127]
	v_lshl_add_u64 v[124:125], v[16:17], 0, v[124:125]
	v_lshl_add_u64 v[130:131], v[16:17], 0, v[130:131]
	v_lshl_add_u64 v[128:129], v[16:17], 0, v[128:129]
	global_load_dword v97, v[100:101], off
	global_load_dword v106, v[98:99], off
	global_load_dword v132, v[104:105], off
	global_load_dword v133, v[102:103], off
	global_load_dword v134, v[110:111], off
	global_load_dword v135, v[108:109], off
	global_load_dword v136, v[114:115], off
	global_load_dword v137, v[112:113], off
	global_load_dword v138, v[118:119], off
	global_load_dword v139, v[116:117], off
	global_load_dword v140, v[122:123], off
	global_load_dword v141, v[120:121], off
	global_load_dword v142, v[126:127], off
	global_load_dword v143, v[124:125], off
	global_load_dword v144, v[130:131], off
	global_load_dword v145, v[128:129], off
	v_or_b32_e32 v100, s12, v1
	v_or_b32_e32 v98, s14, v2
	s_add_i32 s8, s8, 16
	s_add_i32 s5, s5, 16
	s_add_i32 s9, s9, -16
	v_mad_u64_u32 v[98:99], s[24:25], v98, s3, v[12:13]
	v_mad_u64_u32 v[100:101], s[24:25], v100, s3, v[12:13]
	v_or_b32_e32 v99, s16, v1
	v_or_b32_e32 v101, s17, v2
	v_or_b32_e32 v110, s18, v1
	v_or_b32_e32 v108, s19, v2
	v_or_b32_e32 v114, s23, v1
	v_or_b32_e32 v112, s26, v2
	v_or_b32_e32 v118, s27, v1
	v_or_b32_e32 v116, s28, v2
	v_or_b32_e32 v122, s29, v1
	v_or_b32_e32 v120, s30, v2
	v_or_b32_e32 v126, s31, v1
	v_or_b32_e32 v124, s33, v2
	v_or_b32_e32 v130, s34, v1
	v_or_b32_e32 v128, s35, v2
	s_cmp_lg_u32 s9, 0
	v_mad_u64_u32 v[102:103], s[16:17], v101, s3, v[12:13]
	v_mad_u64_u32 v[104:105], s[16:17], v99, s3, v[12:13]
	v_mad_u64_u32 v[108:109], s[16:17], v108, s3, v[12:13]
	v_mad_u64_u32 v[110:111], s[16:17], v110, s3, v[12:13]
	v_mad_u64_u32 v[112:113], s[16:17], v112, s3, v[12:13]
	v_mad_u64_u32 v[114:115], s[16:17], v114, s3, v[12:13]
	v_mad_u64_u32 v[116:117], s[16:17], v116, s3, v[12:13]
	v_mad_u64_u32 v[118:119], s[16:17], v118, s3, v[12:13]
	v_mad_u64_u32 v[120:121], s[16:17], v120, s3, v[12:13]
	v_mad_u64_u32 v[122:123], s[16:17], v122, s3, v[12:13]
	v_mad_u64_u32 v[124:125], s[16:17], v124, s3, v[12:13]
	v_mad_u64_u32 v[126:127], s[16:17], v126, s3, v[12:13]
	v_mad_u64_u32 v[128:129], s[16:17], v128, s3, v[12:13]
	v_mad_u64_u32 v[130:131], s[16:17], v130, s3, v[12:13]
	s_waitcnt vmcnt(31)
	ds_write_b32 v22, v21
	s_waitcnt vmcnt(30)
	ds_write_b32 v24, v30
	s_waitcnt vmcnt(29)
	ds_write_b32 v26, v56
	s_waitcnt vmcnt(28)
	ds_write_b32 v28, v57
	s_waitcnt vmcnt(27)
	ds_write_b32 v32, v58
	s_waitcnt vmcnt(26)
	ds_write_b32 v34, v59
	s_waitcnt vmcnt(25)
	ds_write_b32 v36, v60
	s_waitcnt vmcnt(24)
	ds_write_b32 v38, v61
	s_waitcnt vmcnt(23)
	ds_write_b32 v40, v62
	s_waitcnt vmcnt(22)
	ds_write_b32 v42, v63
	s_waitcnt vmcnt(21)
	ds_write_b32 v44, v64
	s_waitcnt vmcnt(20)
	ds_write_b32 v46, v65
	s_waitcnt vmcnt(19)
	ds_write_b32 v48, v66
	s_waitcnt vmcnt(18)
	ds_write_b32 v50, v67
	s_waitcnt vmcnt(17)
	ds_write_b32 v52, v68
	s_waitcnt vmcnt(16)
	ds_write_b32 v54, v69
	s_waitcnt vmcnt(15)
	ds_write_b32 v98, v97
	s_waitcnt vmcnt(14)
	ds_write_b32 v100, v106
	s_waitcnt vmcnt(13)
	ds_write_b32 v102, v132
	s_waitcnt vmcnt(12)
	ds_write_b32 v104, v133
	s_waitcnt vmcnt(11)
	ds_write_b32 v108, v134
	s_waitcnt vmcnt(10)
	ds_write_b32 v110, v135
	s_waitcnt vmcnt(9)
	ds_write_b32 v112, v136
	s_waitcnt vmcnt(8)
	ds_write_b32 v114, v137
	s_waitcnt vmcnt(7)
	ds_write_b32 v116, v138
	s_waitcnt vmcnt(6)
	ds_write_b32 v118, v139
	s_waitcnt vmcnt(5)
	ds_write_b32 v120, v140
	s_waitcnt vmcnt(4)
	ds_write_b32 v122, v141
	s_waitcnt vmcnt(3)
	ds_write_b32 v124, v142
	s_waitcnt vmcnt(2)
	ds_write_b32 v126, v143
	s_waitcnt vmcnt(1)
	ds_write_b32 v128, v144
	s_waitcnt vmcnt(0)
	ds_write_b32 v130, v145
	s_cbranch_scc1 .LBB0_176
	s_waitcnt lgkmcnt(0)
	ds_read2_b32 v[16:17], v5 offset0:33 offset1:41
	ds_read2_b32 v[26:27], v5 offset1:8
	ds_read2_b32 v[28:29], v5 offset0:66 offset1:74
	ds_read2_b32 v[32:33], v5 offset0:99 offset1:107
	ds_read2_b32 v[34:35], v5 offset0:132 offset1:140
	ds_read2_b32 v[36:37], v5 offset0:165 offset1:173
	ds_read2_b32 v[38:39], v5 offset0:198 offset1:206
	ds_read2_b32 v[40:41], v5 offset0:231 offset1:239
	v_or_b32_e32 v3, s4, v7
	s_ashr_i32 s23, s22, 31
	v_mul_lo_u32 v44, v3, s6
	v_lshl_add_u64 v[42:43], s[22:23], 1, v[14:15]
	v_ashrrev_i32_e32 v45, 31, v44
	s_waitcnt lgkmcnt(6)
	v_cvt_pk_bf16_f32 v22, v26, v16
	s_waitcnt lgkmcnt(4)
	v_cvt_pk_bf16_f32 v23, v28, v32
	s_waitcnt lgkmcnt(2)
	v_cvt_pk_bf16_f32 v24, v34, v36
	s_waitcnt lgkmcnt(0)
	v_cvt_pk_bf16_f32 v25, v38, v40
	v_lshl_add_u64 v[44:45], v[44:45], 1, v[42:43]
	global_store_dwordx4 v[44:45], v[22:25], off
	v_or_b32_e32 v3, s4, v13
	v_mul_lo_u32 v16, v3, s6
	v_cvt_pk_bf16_f32 v22, v27, v17
	v_cvt_pk_bf16_f32 v23, v29, v33
	v_cvt_pk_bf16_f32 v24, v35, v37
	v_cvt_pk_bf16_f32 v25, v39, v41
	ds_read2_b32 v[26:27], v5 offset0:49 offset1:57
	ds_read2_b32 v[28:29], v5 offset0:16 offset1:24
	ds_read2_b32 v[32:33], v5 offset0:82 offset1:90
	ds_read2_b32 v[34:35], v5 offset0:115 offset1:123
	ds_read2_b32 v[36:37], v5 offset0:148 offset1:156
	ds_read2_b32 v[38:39], v5 offset0:181 offset1:189
	ds_read2_b32 v[40:41], v5 offset0:214 offset1:222
	ds_read2_b32 v[44:45], v5 offset0:247 offset1:255
	v_ashrrev_i32_e32 v17, 31, v16
	v_lshl_add_u64 v[16:17], v[16:17], 1, v[42:43]
	v_or_b32_e32 v3, s4, v19
	global_store_dwordx4 v[16:17], v[22:25], off
	v_mul_lo_u32 v16, v3, s6
	v_ashrrev_i32_e32 v17, 31, v16
	s_waitcnt lgkmcnt(6)
	v_cvt_pk_bf16_f32 v22, v28, v26
	s_waitcnt lgkmcnt(4)
	v_cvt_pk_bf16_f32 v23, v32, v34
	s_waitcnt lgkmcnt(2)
	v_cvt_pk_bf16_f32 v24, v36, v38
	s_waitcnt lgkmcnt(0)
	v_cvt_pk_bf16_f32 v25, v40, v44
	v_lshl_add_u64 v[16:17], v[16:17], 1, v[42:43]
	v_or_b32_e32 v3, s4, v20
	global_store_dwordx4 v[16:17], v[22:25], off
	v_mul_lo_u32 v16, v3, s6
	v_ashrrev_i32_e32 v17, 31, v16
	v_cvt_pk_bf16_f32 v22, v29, v27
	v_cvt_pk_bf16_f32 v23, v33, v35
	v_cvt_pk_bf16_f32 v24, v37, v39
	v_cvt_pk_bf16_f32 v25, v41, v45
	v_lshl_add_u64 v[16:17], v[16:17], 1, v[42:43]
	global_store_dwordx4 v[16:17], v[22:25], off
	s_waitcnt lgkmcnt(0)
	s_add_i32 s7, s7, s10
	s_cmpk_lt_i32 s7, 0x1600
	s_cbranch_scc1 .LBB0_175

.LBB0_181:
	s_lshl_b32 s12, s9, 1
	s_lshl_b32 s14, s8, 1
	v_or_b32_e32 v21, s12, v3
	v_or_b32_e32 v22, s14, v18
	s_add_i32 s18, s12, 4
	s_add_i32 s19, s14, 4
	s_add_i32 s23, s12, 8
	s_add_i32 s24, s14, 8
	s_add_i32 s25, s12, 12
	s_add_i32 s26, s14, 12
	s_add_i32 s27, s12, 16
	s_add_i32 s28, s14, 16
	s_add_i32 s29, s12, 20
	s_add_i32 s30, s14, 20
	s_add_i32 s31, s12, 24
	s_add_i32 s33, s14, 24
	s_add_i32 s34, s12, 28
	s_add_i32 s35, s14, 28
	v_mad_i64_i32 v[22:23], s[16:17], v22, s6, v[16:17]
	v_mad_i64_i32 v[24:25], s[16:17], v21, s6, v[16:17]
	v_or_b32_e32 v21, s18, v3
	v_or_b32_e32 v26, s19, v18
	v_or_b32_e32 v30, s23, v3
	v_or_b32_e32 v32, s24, v18
	v_or_b32_e32 v38, s25, v3
	v_or_b32_e32 v36, s26, v18
	v_or_b32_e32 v42, s27, v3
	v_or_b32_e32 v40, s28, v18
	v_or_b32_e32 v46, s29, v3
	v_or_b32_e32 v44, s30, v18
	v_or_b32_e32 v50, s31, v3
	v_or_b32_e32 v48, s33, v18
	v_or_b32_e32 v54, s34, v3
	v_or_b32_e32 v52, s35, v18
	v_mad_i64_i32 v[26:27], s[16:17], v26, s6, v[16:17]
	v_mad_i64_i32 v[28:29], s[16:17], v21, s6, v[16:17]
	v_mad_i64_i32 v[32:33], s[16:17], v32, s6, v[16:17]
	v_mad_i64_i32 v[34:35], s[16:17], v30, s6, v[16:17]
	v_mad_i64_i32 v[36:37], s[16:17], v36, s6, v[16:17]
	v_mad_i64_i32 v[38:39], s[16:17], v38, s6, v[16:17]
	v_mad_i64_i32 v[40:41], s[16:17], v40, s6, v[16:17]
	v_mad_i64_i32 v[42:43], s[16:17], v42, s6, v[16:17]
	v_mad_i64_i32 v[44:45], s[16:17], v44, s6, v[16:17]
	v_mad_i64_i32 v[46:47], s[16:17], v46, s6, v[16:17]
	v_mad_i64_i32 v[48:49], s[16:17], v48, s6, v[16:17]
	v_mad_i64_i32 v[50:51], s[16:17], v50, s6, v[16:17]
	v_mad_i64_i32 v[52:53], s[16:17], v52, s6, v[16:17]
	v_mad_i64_i32 v[54:55], s[16:17], v54, s6, v[16:17]
	global_load_dword v21, v[22:23], off
	global_load_dword v30, v[24:25], off
	global_load_dword v56, v[26:27], off
	global_load_dword v57, v[28:29], off
	global_load_dword v58, v[32:33], off
	global_load_dword v59, v[34:35], off
	global_load_dword v60, v[36:37], off
	global_load_dword v61, v[38:39], off
	global_load_dword v62, v[40:41], off
	global_load_dword v63, v[42:43], off
	global_load_dword v64, v[44:45], off
	global_load_dword v65, v[46:47], off
	global_load_dword v66, v[48:49], off
	global_load_dword v67, v[50:51], off
	global_load_dword v68, v[52:53], off
	global_load_dword v69, v[54:55], off
	v_or_b32_e32 v24, s12, v1
	v_or_b32_e32 v22, s14, v2
	s_add_i32 s8, s8, 16
	s_add_i32 s9, s9, 16
	s_add_i32 s5, s5, -16
	v_mad_u64_u32 v[22:23], s[16:17], v22, s3, v[12:13]
	v_mad_u64_u32 v[24:25], s[16:17], v24, s3, v[12:13]
	v_or_b32_e32 v23, s18, v1
	v_or_b32_e32 v25, s19, v2
	v_or_b32_e32 v34, s23, v1
	v_or_b32_e32 v32, s24, v2
	v_or_b32_e32 v38, s25, v1
	v_or_b32_e32 v36, s26, v2
	v_or_b32_e32 v42, s27, v1
	v_or_b32_e32 v40, s28, v2
	v_or_b32_e32 v46, s29, v1
	v_or_b32_e32 v44, s30, v2
	v_or_b32_e32 v50, s31, v1
	v_or_b32_e32 v48, s33, v2
	v_or_b32_e32 v54, s34, v1
	v_or_b32_e32 v52, s35, v2
	s_cmp_lg_u32 s5, 0
	v_mad_u64_u32 v[26:27], s[16:17], v25, s3, v[12:13]
	v_mad_u64_u32 v[28:29], s[16:17], v23, s3, v[12:13]
	v_mad_u64_u32 v[32:33], s[16:17], v32, s3, v[12:13]
	v_mad_u64_u32 v[34:35], s[16:17], v34, s3, v[12:13]
	v_mad_u64_u32 v[36:37], s[16:17], v36, s3, v[12:13]
	v_mad_u64_u32 v[38:39], s[16:17], v38, s3, v[12:13]
	v_mad_u64_u32 v[40:41], s[16:17], v40, s3, v[12:13]
	v_mad_u64_u32 v[42:43], s[16:17], v42, s3, v[12:13]
	v_mad_u64_u32 v[44:45], s[16:17], v44, s3, v[12:13]
	v_mad_u64_u32 v[46:47], s[16:17], v46, s3, v[12:13]
	v_mad_u64_u32 v[48:49], s[16:17], v48, s3, v[12:13]
	v_mad_u64_u32 v[50:51], s[16:17], v50, s3, v[12:13]
	v_mad_u64_u32 v[52:53], s[16:17], v52, s3, v[12:13]
	v_mad_u64_u32 v[54:55], s[16:17], v54, s3, v[12:13]
	s_lshl_b32 s12, s9, 1
	s_lshl_b32 s14, s8, 1
	v_or_b32_e32 v97, s12, v3
	v_or_b32_e32 v98, s14, v18
	s_add_i32 s18, s12, 4
	s_add_i32 s19, s14, 4
	s_add_i32 s23, s12, 8
	s_add_i32 s24, s14, 8
	s_add_i32 s25, s12, 12
	s_add_i32 s26, s14, 12
	s_add_i32 s27, s12, 16
	s_add_i32 s28, s14, 16
	s_add_i32 s29, s12, 20
	s_add_i32 s30, s14, 20
	s_add_i32 s31, s12, 24
	s_add_i32 s33, s14, 24
	s_add_i32 s34, s12, 28
	s_add_i32 s35, s14, 28
	v_mad_i64_i32 v[98:99], s[16:17], v98, s6, v[16:17]
	v_mad_i64_i32 v[100:101], s[16:17], v97, s6, v[16:17]
	v_or_b32_e32 v97, s18, v3
	v_or_b32_e32 v102, s19, v18
	v_or_b32_e32 v106, s23, v3
	v_or_b32_e32 v108, s24, v18
	v_or_b32_e32 v114, s25, v3
	v_or_b32_e32 v112, s26, v18
	v_or_b32_e32 v118, s27, v3
	v_or_b32_e32 v116, s28, v18
	v_or_b32_e32 v122, s29, v3
	v_or_b32_e32 v120, s30, v18
	v_or_b32_e32 v126, s31, v3
	v_or_b32_e32 v124, s33, v18
	v_or_b32_e32 v130, s34, v3
	v_or_b32_e32 v128, s35, v18
	v_mad_i64_i32 v[102:103], s[16:17], v102, s6, v[16:17]
	v_mad_i64_i32 v[104:105], s[16:17], v97, s6, v[16:17]
	v_mad_i64_i32 v[108:109], s[16:17], v108, s6, v[16:17]
	v_mad_i64_i32 v[110:111], s[16:17], v106, s6, v[16:17]
	v_mad_i64_i32 v[112:113], s[16:17], v112, s6, v[16:17]
	v_mad_i64_i32 v[114:115], s[16:17], v114, s6, v[16:17]
	v_mad_i64_i32 v[116:117], s[16:17], v116, s6, v[16:17]
	v_mad_i64_i32 v[118:119], s[16:17], v118, s6, v[16:17]
	v_mad_i64_i32 v[120:121], s[16:17], v120, s6, v[16:17]
	v_mad_i64_i32 v[122:123], s[16:17], v122, s6, v[16:17]
	v_mad_i64_i32 v[124:125], s[16:17], v124, s6, v[16:17]
	v_mad_i64_i32 v[126:127], s[16:17], v126, s6, v[16:17]
	v_mad_i64_i32 v[128:129], s[16:17], v128, s6, v[16:17]
	v_mad_i64_i32 v[130:131], s[16:17], v130, s6, v[16:17]
	global_load_dword v97, v[98:99], off
	global_load_dword v106, v[100:101], off
	global_load_dword v132, v[102:103], off
	global_load_dword v133, v[104:105], off
	global_load_dword v134, v[108:109], off
	global_load_dword v135, v[110:111], off
	global_load_dword v136, v[112:113], off
	global_load_dword v137, v[114:115], off
	global_load_dword v138, v[116:117], off
	global_load_dword v139, v[118:119], off
	global_load_dword v140, v[120:121], off
	global_load_dword v141, v[122:123], off
	global_load_dword v142, v[124:125], off
	global_load_dword v143, v[126:127], off
	global_load_dword v144, v[128:129], off
	global_load_dword v145, v[130:131], off
	v_or_b32_e32 v100, s12, v1
	v_or_b32_e32 v98, s14, v2
	s_add_i32 s8, s8, 16
	s_add_i32 s9, s9, 16
	s_add_i32 s5, s5, -16
	v_mad_u64_u32 v[98:99], s[16:17], v98, s3, v[12:13]
	v_mad_u64_u32 v[100:101], s[16:17], v100, s3, v[12:13]
	v_or_b32_e32 v99, s18, v1
	v_or_b32_e32 v101, s19, v2
	v_or_b32_e32 v110, s23, v1
	v_or_b32_e32 v108, s24, v2
	v_or_b32_e32 v114, s25, v1
	v_or_b32_e32 v112, s26, v2
	v_or_b32_e32 v118, s27, v1
	v_or_b32_e32 v116, s28, v2
	v_or_b32_e32 v122, s29, v1
	v_or_b32_e32 v120, s30, v2
	v_or_b32_e32 v126, s31, v1
	v_or_b32_e32 v124, s33, v2
	v_or_b32_e32 v130, s34, v1
	v_or_b32_e32 v128, s35, v2
	s_cmp_lg_u32 s5, 0
	v_mad_u64_u32 v[102:103], s[16:17], v101, s3, v[12:13]
	v_mad_u64_u32 v[104:105], s[16:17], v99, s3, v[12:13]
	v_mad_u64_u32 v[108:109], s[16:17], v108, s3, v[12:13]
	v_mad_u64_u32 v[110:111], s[16:17], v110, s3, v[12:13]
	v_mad_u64_u32 v[112:113], s[16:17], v112, s3, v[12:13]
	v_mad_u64_u32 v[114:115], s[16:17], v114, s3, v[12:13]
	v_mad_u64_u32 v[116:117], s[16:17], v116, s3, v[12:13]
	v_mad_u64_u32 v[118:119], s[16:17], v118, s3, v[12:13]
	v_mad_u64_u32 v[120:121], s[16:17], v120, s3, v[12:13]
	v_mad_u64_u32 v[122:123], s[16:17], v122, s3, v[12:13]
	v_mad_u64_u32 v[124:125], s[16:17], v124, s3, v[12:13]
	v_mad_u64_u32 v[126:127], s[16:17], v126, s3, v[12:13]
	v_mad_u64_u32 v[128:129], s[16:17], v128, s3, v[12:13]
	v_mad_u64_u32 v[130:131], s[16:17], v130, s3, v[12:13]
	s_waitcnt vmcnt(31)
	ds_write_b32 v22, v21
	s_waitcnt vmcnt(30)
	ds_write_b32 v24, v30
	s_waitcnt vmcnt(29)
	ds_write_b32 v26, v56
	s_waitcnt vmcnt(28)
	ds_write_b32 v28, v57
	s_waitcnt vmcnt(27)
	ds_write_b32 v32, v58
	s_waitcnt vmcnt(26)
	ds_write_b32 v34, v59
	s_waitcnt vmcnt(25)
	ds_write_b32 v36, v60
	s_waitcnt vmcnt(24)
	ds_write_b32 v38, v61
	s_waitcnt vmcnt(23)
	ds_write_b32 v40, v62
	s_waitcnt vmcnt(22)
	ds_write_b32 v42, v63
	s_waitcnt vmcnt(21)
	ds_write_b32 v44, v64
	s_waitcnt vmcnt(20)
	ds_write_b32 v46, v65
	s_waitcnt vmcnt(19)
	ds_write_b32 v48, v66
	s_waitcnt vmcnt(18)
	ds_write_b32 v50, v67
	s_waitcnt vmcnt(17)
	ds_write_b32 v52, v68
	s_waitcnt vmcnt(16)
	ds_write_b32 v54, v69
	s_waitcnt vmcnt(15)
	ds_write_b32 v98, v97
	s_waitcnt vmcnt(14)
	ds_write_b32 v100, v106
	s_waitcnt vmcnt(13)
	ds_write_b32 v102, v132
	s_waitcnt vmcnt(12)
	ds_write_b32 v104, v133
	s_waitcnt vmcnt(11)
	ds_write_b32 v108, v134
	s_waitcnt vmcnt(10)
	ds_write_b32 v110, v135
	s_waitcnt vmcnt(9)
	ds_write_b32 v112, v136
	s_waitcnt vmcnt(8)
	ds_write_b32 v114, v137
	s_waitcnt vmcnt(7)
	ds_write_b32 v116, v138
	s_waitcnt vmcnt(6)
	ds_write_b32 v118, v139
	s_waitcnt vmcnt(5)
	ds_write_b32 v120, v140
	s_waitcnt vmcnt(4)
	ds_write_b32 v122, v141
	s_waitcnt vmcnt(3)
	ds_write_b32 v124, v142
	s_waitcnt vmcnt(2)
	ds_write_b32 v126, v143
	s_waitcnt vmcnt(1)
	ds_write_b32 v128, v144
	s_waitcnt vmcnt(0)
	ds_write_b32 v130, v145
	s_cbranch_scc1 .LBB0_181
	s_waitcnt lgkmcnt(0)
	ds_read2_b32 v[16:17], v5 offset0:33 offset1:41
	ds_read2_b32 v[26:27], v5 offset1:8
	ds_read2_b32 v[28:29], v5 offset0:66 offset1:74
	ds_read2_b32 v[32:33], v5 offset0:99 offset1:107
	ds_read2_b32 v[34:35], v5 offset0:132 offset1:140
	ds_read2_b32 v[36:37], v5 offset0:165 offset1:173
	ds_read2_b32 v[38:39], v5 offset0:198 offset1:206
	ds_read2_b32 v[40:41], v5 offset0:231 offset1:239
	v_or_b32_e32 v44, s4, v7
	s_ashr_i32 s23, s22, 31
	v_ashrrev_i32_e32 v45, 31, v44
	v_lshl_add_u64 v[42:43], s[22:23], 1, v[14:15]
	v_lshlrev_b64 v[44:45], 12, v[44:45]
	s_waitcnt lgkmcnt(6)
	v_cvt_pk_bf16_f32 v22, v26, v16
	s_waitcnt lgkmcnt(4)
	v_cvt_pk_bf16_f32 v23, v28, v32
	s_waitcnt lgkmcnt(2)
	v_cvt_pk_bf16_f32 v24, v34, v36
	s_waitcnt lgkmcnt(0)
	v_cvt_pk_bf16_f32 v25, v38, v40
	v_lshl_add_u64 v[44:45], v[42:43], 0, v[44:45]
	v_or_b32_e32 v16, s4, v13
	global_store_dwordx4 v[44:45], v[22:25], off
	s_add_i32 s7, s7, s10
	s_cmpk_lt_i32 s7, 0x2000
	v_cvt_pk_bf16_f32 v22, v27, v17
	v_ashrrev_i32_e32 v17, 31, v16
	v_cvt_pk_bf16_f32 v23, v29, v33
	v_cvt_pk_bf16_f32 v24, v35, v37
	v_cvt_pk_bf16_f32 v25, v39, v41
	v_lshlrev_b64 v[16:17], 12, v[16:17]
	ds_read2_b32 v[26:27], v5 offset0:49 offset1:57
	ds_read2_b32 v[28:29], v5 offset0:16 offset1:24
	ds_read2_b32 v[32:33], v5 offset0:82 offset1:90
	ds_read2_b32 v[34:35], v5 offset0:115 offset1:123
	ds_read2_b32 v[36:37], v5 offset0:148 offset1:156
	ds_read2_b32 v[38:39], v5 offset0:181 offset1:189
	ds_read2_b32 v[40:41], v5 offset0:214 offset1:222
	ds_read2_b32 v[44:45], v5 offset0:247 offset1:255
	v_lshl_add_u64 v[16:17], v[42:43], 0, v[16:17]
	global_store_dwordx4 v[16:17], v[22:25], off
	v_or_b32_e32 v16, s4, v19
	v_ashrrev_i32_e32 v17, 31, v16
	v_lshlrev_b64 v[16:17], 12, v[16:17]
	s_waitcnt lgkmcnt(6)
	v_cvt_pk_bf16_f32 v22, v28, v26
	s_waitcnt lgkmcnt(4)
	v_cvt_pk_bf16_f32 v23, v32, v34
	s_waitcnt lgkmcnt(2)
	v_cvt_pk_bf16_f32 v24, v36, v38
	s_waitcnt lgkmcnt(0)
	v_cvt_pk_bf16_f32 v25, v40, v44
	v_lshl_add_u64 v[16:17], v[42:43], 0, v[16:17]
	global_store_dwordx4 v[16:17], v[22:25], off
	v_or_b32_e32 v16, s4, v20
	v_ashrrev_i32_e32 v17, 31, v16
	v_lshlrev_b64 v[16:17], 12, v[16:17]
	v_cvt_pk_bf16_f32 v22, v29, v27
	v_cvt_pk_bf16_f32 v23, v33, v35
	v_cvt_pk_bf16_f32 v24, v37, v39
	v_cvt_pk_bf16_f32 v25, v41, v45
	v_lshl_add_u64 v[16:17], v[42:43], 0, v[16:17]
	global_store_dwordx4 v[16:17], v[22:25], off
	s_waitcnt lgkmcnt(0)
	s_cbranch_scc1 .LBB0_180

.LBB0_186:
	s_lshl_b32 s12, s9, 1
	s_lshl_b32 s14, s8, 1
	v_or_b32_e32 v24, s14, v18
	s_add_i32 s16, s12, 4
	s_add_i32 s17, s14, 4
	s_add_i32 s18, s12, 8
	s_add_i32 s19, s14, 8
	s_add_i32 s23, s12, 12
	s_add_i32 s25, s14, 12
	s_add_i32 s28, s12, 16
	s_add_i32 s29, s14, 16
	s_add_i32 s30, s12, 20
	s_add_i32 s31, s14, 20
	s_add_i32 s33, s12, 24
	s_add_i32 s34, s14, 24
	s_add_i32 s35, s12, 28
	s_add_i32 s36, s14, 28
	v_or_b32_e32 v22, s12, v3
	v_ashrrev_i32_e32 v25, 31, v24
	v_or_b32_e32 v26, s16, v3
	v_or_b32_e32 v28, s17, v18
	v_or_b32_e32 v32, s18, v3
	v_or_b32_e32 v34, s19, v18
	v_or_b32_e32 v36, s23, v3
	v_or_b32_e32 v38, s25, v18
	v_or_b32_e32 v40, s28, v3
	v_or_b32_e32 v42, s29, v18
	v_or_b32_e32 v44, s30, v3
	v_or_b32_e32 v46, s31, v18
	v_or_b32_e32 v48, s33, v3
	v_or_b32_e32 v50, s34, v18
	v_or_b32_e32 v52, s35, v3
	v_or_b32_e32 v54, s36, v18
	v_ashrrev_i32_e32 v23, 31, v22
	v_lshlrev_b64 v[24:25], 13, v[24:25]
	v_ashrrev_i32_e32 v29, 31, v28
	v_ashrrev_i32_e32 v27, 31, v26
	v_ashrrev_i32_e32 v35, 31, v34
	v_ashrrev_i32_e32 v33, 31, v32
	v_ashrrev_i32_e32 v39, 31, v38
	v_ashrrev_i32_e32 v37, 31, v36
	v_ashrrev_i32_e32 v43, 31, v42
	v_ashrrev_i32_e32 v41, 31, v40
	v_ashrrev_i32_e32 v47, 31, v46
	v_ashrrev_i32_e32 v45, 31, v44
	v_ashrrev_i32_e32 v51, 31, v50
	v_ashrrev_i32_e32 v49, 31, v48
	v_ashrrev_i32_e32 v55, 31, v54
	v_ashrrev_i32_e32 v53, 31, v52
	v_lshlrev_b64 v[22:23], 13, v[22:23]
	v_lshl_add_u64 v[24:25], v[16:17], 0, v[24:25]
	v_lshlrev_b64 v[26:27], 13, v[26:27]
	v_lshlrev_b64 v[28:29], 13, v[28:29]
	v_lshlrev_b64 v[32:33], 13, v[32:33]
	v_lshlrev_b64 v[34:35], 13, v[34:35]
	v_lshlrev_b64 v[36:37], 13, v[36:37]
	v_lshlrev_b64 v[38:39], 13, v[38:39]
	v_lshlrev_b64 v[40:41], 13, v[40:41]
	v_lshlrev_b64 v[42:43], 13, v[42:43]
	v_lshlrev_b64 v[44:45], 13, v[44:45]
	v_lshlrev_b64 v[46:47], 13, v[46:47]
	v_lshlrev_b64 v[48:49], 13, v[48:49]
	v_lshlrev_b64 v[50:51], 13, v[50:51]
	v_lshlrev_b64 v[52:53], 13, v[52:53]
	v_lshlrev_b64 v[54:55], 13, v[54:55]
	v_lshl_add_u64 v[22:23], v[16:17], 0, v[22:23]
	v_lshl_add_u64 v[28:29], v[16:17], 0, v[28:29]
	v_lshl_add_u64 v[26:27], v[16:17], 0, v[26:27]
	v_lshl_add_u64 v[34:35], v[16:17], 0, v[34:35]
	v_lshl_add_u64 v[32:33], v[16:17], 0, v[32:33]
	v_lshl_add_u64 v[38:39], v[16:17], 0, v[38:39]
	v_lshl_add_u64 v[36:37], v[16:17], 0, v[36:37]
	v_lshl_add_u64 v[42:43], v[16:17], 0, v[42:43]
	v_lshl_add_u64 v[40:41], v[16:17], 0, v[40:41]
	v_lshl_add_u64 v[46:47], v[16:17], 0, v[46:47]
	v_lshl_add_u64 v[44:45], v[16:17], 0, v[44:45]
	v_lshl_add_u64 v[50:51], v[16:17], 0, v[50:51]
	v_lshl_add_u64 v[48:49], v[16:17], 0, v[48:49]
	v_lshl_add_u64 v[54:55], v[16:17], 0, v[54:55]
	v_lshl_add_u64 v[52:53], v[16:17], 0, v[52:53]
	global_load_dword v21, v[24:25], off
	global_load_dword v30, v[22:23], off
	global_load_dword v56, v[28:29], off
	global_load_dword v57, v[26:27], off
	global_load_dword v58, v[34:35], off
	global_load_dword v59, v[32:33], off
	global_load_dword v60, v[38:39], off
	global_load_dword v61, v[36:37], off
	global_load_dword v62, v[42:43], off
	global_load_dword v63, v[40:41], off
	global_load_dword v64, v[46:47], off
	global_load_dword v65, v[44:45], off
	global_load_dword v66, v[50:51], off
	global_load_dword v67, v[48:49], off
	global_load_dword v68, v[54:55], off
	global_load_dword v69, v[52:53], off
	v_or_b32_e32 v24, s12, v1
	v_or_b32_e32 v22, s14, v2
	s_add_i32 s8, s8, 16
	s_add_i32 s9, s9, 16
	s_add_i32 s7, s7, -16
	v_mad_u64_u32 v[22:23], s[26:27], v22, s3, v[12:13]
	v_mad_u64_u32 v[24:25], s[26:27], v24, s3, v[12:13]
	v_or_b32_e32 v23, s16, v1
	v_or_b32_e32 v25, s17, v2
	v_or_b32_e32 v34, s18, v1
	v_or_b32_e32 v32, s19, v2
	v_or_b32_e32 v38, s23, v1
	v_or_b32_e32 v36, s25, v2
	v_or_b32_e32 v42, s28, v1
	v_or_b32_e32 v40, s29, v2
	v_or_b32_e32 v46, s30, v1
	v_or_b32_e32 v44, s31, v2
	v_or_b32_e32 v50, s33, v1
	v_or_b32_e32 v48, s34, v2
	v_or_b32_e32 v54, s35, v1
	v_or_b32_e32 v52, s36, v2
	s_cmp_lg_u32 s7, 0
	v_mad_u64_u32 v[26:27], s[16:17], v25, s3, v[12:13]
	v_mad_u64_u32 v[28:29], s[16:17], v23, s3, v[12:13]
	v_mad_u64_u32 v[32:33], s[16:17], v32, s3, v[12:13]
	v_mad_u64_u32 v[34:35], s[16:17], v34, s3, v[12:13]
	v_mad_u64_u32 v[36:37], s[16:17], v36, s3, v[12:13]
	v_mad_u64_u32 v[38:39], s[16:17], v38, s3, v[12:13]
	v_mad_u64_u32 v[40:41], s[16:17], v40, s3, v[12:13]
	v_mad_u64_u32 v[42:43], s[16:17], v42, s3, v[12:13]
	v_mad_u64_u32 v[44:45], s[16:17], v44, s3, v[12:13]
	v_mad_u64_u32 v[46:47], s[16:17], v46, s3, v[12:13]
	v_mad_u64_u32 v[48:49], s[16:17], v48, s3, v[12:13]
	v_mad_u64_u32 v[50:51], s[16:17], v50, s3, v[12:13]
	v_mad_u64_u32 v[52:53], s[16:17], v52, s3, v[12:13]
	v_mad_u64_u32 v[54:55], s[16:17], v54, s3, v[12:13]
	s_lshl_b32 s12, s9, 1
	s_lshl_b32 s14, s8, 1
	v_or_b32_e32 v100, s14, v18
	s_add_i32 s16, s12, 4
	s_add_i32 s17, s14, 4
	s_add_i32 s18, s12, 8
	s_add_i32 s19, s14, 8
	s_add_i32 s23, s12, 12
	s_add_i32 s25, s14, 12
	s_add_i32 s28, s12, 16
	s_add_i32 s29, s14, 16
	s_add_i32 s30, s12, 20
	s_add_i32 s31, s14, 20
	s_add_i32 s33, s12, 24
	s_add_i32 s34, s14, 24
	s_add_i32 s35, s12, 28
	s_add_i32 s36, s14, 28
	v_or_b32_e32 v98, s12, v3
	v_ashrrev_i32_e32 v101, 31, v100
	v_or_b32_e32 v102, s16, v3
	v_or_b32_e32 v104, s17, v18
	v_or_b32_e32 v108, s18, v3
	v_or_b32_e32 v110, s19, v18
	v_or_b32_e32 v112, s23, v3
	v_or_b32_e32 v114, s25, v18
	v_or_b32_e32 v116, s28, v3
	v_or_b32_e32 v118, s29, v18
	v_or_b32_e32 v120, s30, v3
	v_or_b32_e32 v122, s31, v18
	v_or_b32_e32 v124, s33, v3
	v_or_b32_e32 v126, s34, v18
	v_or_b32_e32 v128, s35, v3
	v_or_b32_e32 v130, s36, v18
	v_ashrrev_i32_e32 v99, 31, v98
	v_lshlrev_b64 v[100:101], 13, v[100:101]
	v_ashrrev_i32_e32 v105, 31, v104
	v_ashrrev_i32_e32 v103, 31, v102
	v_ashrrev_i32_e32 v111, 31, v110
	v_ashrrev_i32_e32 v109, 31, v108
	v_ashrrev_i32_e32 v115, 31, v114
	v_ashrrev_i32_e32 v113, 31, v112
	v_ashrrev_i32_e32 v119, 31, v118
	v_ashrrev_i32_e32 v117, 31, v116
	v_ashrrev_i32_e32 v123, 31, v122
	v_ashrrev_i32_e32 v121, 31, v120
	v_ashrrev_i32_e32 v127, 31, v126
	v_ashrrev_i32_e32 v125, 31, v124
	v_ashrrev_i32_e32 v131, 31, v130
	v_ashrrev_i32_e32 v129, 31, v128
	v_lshlrev_b64 v[98:99], 13, v[98:99]
	v_lshl_add_u64 v[100:101], v[16:17], 0, v[100:101]
	v_lshlrev_b64 v[102:103], 13, v[102:103]
	v_lshlrev_b64 v[104:105], 13, v[104:105]
	v_lshlrev_b64 v[108:109], 13, v[108:109]
	v_lshlrev_b64 v[110:111], 13, v[110:111]
	v_lshlrev_b64 v[112:113], 13, v[112:113]
	v_lshlrev_b64 v[114:115], 13, v[114:115]
	v_lshlrev_b64 v[116:117], 13, v[116:117]
	v_lshlrev_b64 v[118:119], 13, v[118:119]
	v_lshlrev_b64 v[120:121], 13, v[120:121]
	v_lshlrev_b64 v[122:123], 13, v[122:123]
	v_lshlrev_b64 v[124:125], 13, v[124:125]
	v_lshlrev_b64 v[126:127], 13, v[126:127]
	v_lshlrev_b64 v[128:129], 13, v[128:129]
	v_lshlrev_b64 v[130:131], 13, v[130:131]
	v_lshl_add_u64 v[98:99], v[16:17], 0, v[98:99]
	v_lshl_add_u64 v[104:105], v[16:17], 0, v[104:105]
	v_lshl_add_u64 v[102:103], v[16:17], 0, v[102:103]
	v_lshl_add_u64 v[110:111], v[16:17], 0, v[110:111]
	v_lshl_add_u64 v[108:109], v[16:17], 0, v[108:109]
	v_lshl_add_u64 v[114:115], v[16:17], 0, v[114:115]
	v_lshl_add_u64 v[112:113], v[16:17], 0, v[112:113]
	v_lshl_add_u64 v[118:119], v[16:17], 0, v[118:119]
	v_lshl_add_u64 v[116:117], v[16:17], 0, v[116:117]
	v_lshl_add_u64 v[122:123], v[16:17], 0, v[122:123]
	v_lshl_add_u64 v[120:121], v[16:17], 0, v[120:121]
	v_lshl_add_u64 v[126:127], v[16:17], 0, v[126:127]
	v_lshl_add_u64 v[124:125], v[16:17], 0, v[124:125]
	v_lshl_add_u64 v[130:131], v[16:17], 0, v[130:131]
	v_lshl_add_u64 v[128:129], v[16:17], 0, v[128:129]
	global_load_dword v97, v[100:101], off
	global_load_dword v106, v[98:99], off
	global_load_dword v132, v[104:105], off
	global_load_dword v133, v[102:103], off
	global_load_dword v134, v[110:111], off
	global_load_dword v135, v[108:109], off
	global_load_dword v136, v[114:115], off
	global_load_dword v137, v[112:113], off
	global_load_dword v138, v[118:119], off
	global_load_dword v139, v[116:117], off
	global_load_dword v140, v[122:123], off
	global_load_dword v141, v[120:121], off
	global_load_dword v142, v[126:127], off
	global_load_dword v143, v[124:125], off
	global_load_dword v144, v[130:131], off
	global_load_dword v145, v[128:129], off
	v_or_b32_e32 v100, s12, v1
	v_or_b32_e32 v98, s14, v2
	s_add_i32 s8, s8, 16
	s_add_i32 s9, s9, 16
	s_add_i32 s7, s7, -16
	v_mad_u64_u32 v[98:99], s[26:27], v98, s3, v[12:13]
	v_mad_u64_u32 v[100:101], s[26:27], v100, s3, v[12:13]
	v_or_b32_e32 v99, s16, v1
	v_or_b32_e32 v101, s17, v2
	v_or_b32_e32 v110, s18, v1
	v_or_b32_e32 v108, s19, v2
	v_or_b32_e32 v114, s23, v1
	v_or_b32_e32 v112, s25, v2
	v_or_b32_e32 v118, s28, v1
	v_or_b32_e32 v116, s29, v2
	v_or_b32_e32 v122, s30, v1
	v_or_b32_e32 v120, s31, v2
	v_or_b32_e32 v126, s33, v1
	v_or_b32_e32 v124, s34, v2
	v_or_b32_e32 v130, s35, v1
	v_or_b32_e32 v128, s36, v2
	s_cmp_lg_u32 s7, 0
	v_mad_u64_u32 v[102:103], s[16:17], v101, s3, v[12:13]
	v_mad_u64_u32 v[104:105], s[16:17], v99, s3, v[12:13]
	v_mad_u64_u32 v[108:109], s[16:17], v108, s3, v[12:13]
	v_mad_u64_u32 v[110:111], s[16:17], v110, s3, v[12:13]
	v_mad_u64_u32 v[112:113], s[16:17], v112, s3, v[12:13]
	v_mad_u64_u32 v[114:115], s[16:17], v114, s3, v[12:13]
	v_mad_u64_u32 v[116:117], s[16:17], v116, s3, v[12:13]
	v_mad_u64_u32 v[118:119], s[16:17], v118, s3, v[12:13]
	v_mad_u64_u32 v[120:121], s[16:17], v120, s3, v[12:13]
	v_mad_u64_u32 v[122:123], s[16:17], v122, s3, v[12:13]
	v_mad_u64_u32 v[124:125], s[16:17], v124, s3, v[12:13]
	v_mad_u64_u32 v[126:127], s[16:17], v126, s3, v[12:13]
	v_mad_u64_u32 v[128:129], s[16:17], v128, s3, v[12:13]
	v_mad_u64_u32 v[130:131], s[16:17], v130, s3, v[12:13]
	s_waitcnt vmcnt(31)
	ds_write_b32 v22, v21
	s_waitcnt vmcnt(30)
	ds_write_b32 v24, v30
	s_waitcnt vmcnt(29)
	ds_write_b32 v26, v56
	s_waitcnt vmcnt(28)
	ds_write_b32 v28, v57
	s_waitcnt vmcnt(27)
	ds_write_b32 v32, v58
	s_waitcnt vmcnt(26)
	ds_write_b32 v34, v59
	s_waitcnt vmcnt(25)
	ds_write_b32 v36, v60
	s_waitcnt vmcnt(24)
	ds_write_b32 v38, v61
	s_waitcnt vmcnt(23)
	ds_write_b32 v40, v62
	s_waitcnt vmcnt(22)
	ds_write_b32 v42, v63
	s_waitcnt vmcnt(21)
	ds_write_b32 v44, v64
	s_waitcnt vmcnt(20)
	ds_write_b32 v46, v65
	s_waitcnt vmcnt(19)
	ds_write_b32 v48, v66
	s_waitcnt vmcnt(18)
	ds_write_b32 v50, v67
	s_waitcnt vmcnt(17)
	ds_write_b32 v52, v68
	s_waitcnt vmcnt(16)
	ds_write_b32 v54, v69
	s_waitcnt vmcnt(15)
	ds_write_b32 v98, v97
	s_waitcnt vmcnt(14)
	ds_write_b32 v100, v106
	s_waitcnt vmcnt(13)
	ds_write_b32 v102, v132
	s_waitcnt vmcnt(12)
	ds_write_b32 v104, v133
	s_waitcnt vmcnt(11)
	ds_write_b32 v108, v134
	s_waitcnt vmcnt(10)
	ds_write_b32 v110, v135
	s_waitcnt vmcnt(9)
	ds_write_b32 v112, v136
	s_waitcnt vmcnt(8)
	ds_write_b32 v114, v137
	s_waitcnt vmcnt(7)
	ds_write_b32 v116, v138
	s_waitcnt vmcnt(6)
	ds_write_b32 v118, v139
	s_waitcnt vmcnt(5)
	ds_write_b32 v120, v140
	s_waitcnt vmcnt(4)
	ds_write_b32 v122, v141
	s_waitcnt vmcnt(3)
	ds_write_b32 v124, v142
	s_waitcnt vmcnt(2)
	ds_write_b32 v126, v143
	s_waitcnt vmcnt(1)
	ds_write_b32 v128, v144
	s_waitcnt vmcnt(0)
	ds_write_b32 v130, v145
	s_cbranch_scc1 .LBB0_186
	s_waitcnt lgkmcnt(0)
	ds_read2_b32 v[16:17], v5 offset0:33 offset1:41
	ds_read2_b32 v[26:27], v5 offset1:8
	ds_read2_b32 v[28:29], v5 offset0:66 offset1:74
	ds_read2_b32 v[32:33], v5 offset0:99 offset1:107
	ds_read2_b32 v[34:35], v5 offset0:132 offset1:140
	ds_read2_b32 v[36:37], v5 offset0:165 offset1:173
	ds_read2_b32 v[38:39], v5 offset0:198 offset1:206
	ds_read2_b32 v[40:41], v5 offset0:231 offset1:239
	v_or_b32_e32 v44, s22, v7
	s_ashr_i32 s25, s24, 31
	v_ashrrev_i32_e32 v45, 31, v44
	v_lshl_add_u64 v[42:43], s[24:25], 1, v[14:15]
	v_lshlrev_b64 v[44:45], 12, v[44:45]
	s_waitcnt lgkmcnt(6)
	v_cvt_pk_bf16_f32 v22, v26, v16
	s_waitcnt lgkmcnt(4)
	v_cvt_pk_bf16_f32 v23, v28, v32
	s_waitcnt lgkmcnt(2)
	v_cvt_pk_bf16_f32 v24, v34, v36
	s_waitcnt lgkmcnt(0)
	v_cvt_pk_bf16_f32 v25, v38, v40
	v_lshl_add_u64 v[44:45], v[42:43], 0, v[44:45]
	v_or_b32_e32 v16, s22, v13
	global_store_dwordx4 v[44:45], v[22:25], off
	s_add_i32 s6, s6, s10
	s_cmpk_lt_i32 s6, 0x800
	v_cvt_pk_bf16_f32 v22, v27, v17
	v_ashrrev_i32_e32 v17, 31, v16
	v_cvt_pk_bf16_f32 v23, v29, v33
	v_cvt_pk_bf16_f32 v24, v35, v37
	v_cvt_pk_bf16_f32 v25, v39, v41
	v_lshlrev_b64 v[16:17], 12, v[16:17]
	ds_read2_b32 v[26:27], v5 offset0:49 offset1:57
	ds_read2_b32 v[28:29], v5 offset0:16 offset1:24
	ds_read2_b32 v[32:33], v5 offset0:82 offset1:90
	ds_read2_b32 v[34:35], v5 offset0:115 offset1:123
	ds_read2_b32 v[36:37], v5 offset0:148 offset1:156
	ds_read2_b32 v[38:39], v5 offset0:181 offset1:189
	ds_read2_b32 v[40:41], v5 offset0:214 offset1:222
	ds_read2_b32 v[44:45], v5 offset0:247 offset1:255
	v_lshl_add_u64 v[16:17], v[42:43], 0, v[16:17]
	global_store_dwordx4 v[16:17], v[22:25], off
	v_or_b32_e32 v16, s22, v19
	v_ashrrev_i32_e32 v17, 31, v16
	v_lshlrev_b64 v[16:17], 12, v[16:17]
	s_waitcnt lgkmcnt(6)
	v_cvt_pk_bf16_f32 v22, v28, v26
	s_waitcnt lgkmcnt(4)
	v_cvt_pk_bf16_f32 v23, v32, v34
	s_waitcnt lgkmcnt(2)
	v_cvt_pk_bf16_f32 v24, v36, v38
	s_waitcnt lgkmcnt(0)
	v_cvt_pk_bf16_f32 v25, v40, v44
	v_lshl_add_u64 v[16:17], v[42:43], 0, v[16:17]
	global_store_dwordx4 v[16:17], v[22:25], off
	v_or_b32_e32 v16, s22, v20
	v_ashrrev_i32_e32 v17, 31, v16
	v_lshlrev_b64 v[16:17], 12, v[16:17]
	v_cvt_pk_bf16_f32 v22, v29, v27
	v_cvt_pk_bf16_f32 v23, v33, v35
	v_cvt_pk_bf16_f32 v24, v37, v39
	v_cvt_pk_bf16_f32 v25, v41, v45
	v_lshl_add_u64 v[16:17], v[42:43], 0, v[16:17]
	global_store_dwordx4 v[16:17], v[22:25], off
	s_waitcnt lgkmcnt(0)
	s_cbranch_scc1 .LBB0_185

.LBB0_191:
	s_lshl_b32 s12, s9, 1
	s_lshl_b32 s14, s8, 1
	v_or_b32_e32 v26, s14, v18
	s_add_i32 s16, s12, 4
	s_add_i32 s17, s14, 4
	s_add_i32 s18, s12, 8
	s_add_i32 s19, s14, 8
	s_add_i32 s25, s12, 12
	s_add_i32 s27, s14, 12
	s_add_i32 s30, s12, 16
	s_add_i32 s31, s14, 16
	s_add_i32 s33, s12, 20
	s_add_i32 s34, s14, 20
	s_add_i32 s35, s12, 24
	s_add_i32 s36, s14, 24
	s_add_i32 s37, s12, 28
	s_add_i32 s38, s14, 28
	v_or_b32_e32 v24, s12, v3
	v_ashrrev_i32_e32 v27, 31, v26
	v_or_b32_e32 v28, s16, v3
	v_or_b32_e32 v32, s17, v18
	v_or_b32_e32 v34, s18, v3
	v_or_b32_e32 v36, s19, v18
	v_or_b32_e32 v38, s25, v3
	v_or_b32_e32 v40, s27, v18
	v_or_b32_e32 v42, s30, v3
	v_or_b32_e32 v44, s31, v18
	v_or_b32_e32 v46, s33, v3
	v_or_b32_e32 v48, s34, v18
	v_or_b32_e32 v50, s35, v3
	v_or_b32_e32 v52, s36, v18
	v_or_b32_e32 v54, s37, v3
	v_or_b32_e32 v56, s38, v18
	v_ashrrev_i32_e32 v25, 31, v24
	v_lshlrev_b64 v[26:27], 13, v[26:27]
	v_ashrrev_i32_e32 v33, 31, v32
	v_ashrrev_i32_e32 v29, 31, v28
	v_ashrrev_i32_e32 v37, 31, v36
	v_ashrrev_i32_e32 v35, 31, v34
	v_ashrrev_i32_e32 v41, 31, v40
	v_ashrrev_i32_e32 v39, 31, v38
	v_ashrrev_i32_e32 v45, 31, v44
	v_ashrrev_i32_e32 v43, 31, v42
	v_ashrrev_i32_e32 v49, 31, v48
	v_ashrrev_i32_e32 v47, 31, v46
	v_ashrrev_i32_e32 v53, 31, v52
	v_ashrrev_i32_e32 v51, 31, v50
	v_ashrrev_i32_e32 v57, 31, v56
	v_ashrrev_i32_e32 v55, 31, v54
	v_lshlrev_b64 v[24:25], 13, v[24:25]
	v_lshl_add_u64 v[26:27], v[16:17], 0, v[26:27]
	v_lshlrev_b64 v[28:29], 13, v[28:29]
	v_lshlrev_b64 v[32:33], 13, v[32:33]
	v_lshlrev_b64 v[34:35], 13, v[34:35]
	v_lshlrev_b64 v[36:37], 13, v[36:37]
	v_lshlrev_b64 v[38:39], 13, v[38:39]
	v_lshlrev_b64 v[40:41], 13, v[40:41]
	v_lshlrev_b64 v[42:43], 13, v[42:43]
	v_lshlrev_b64 v[44:45], 13, v[44:45]
	v_lshlrev_b64 v[46:47], 13, v[46:47]
	v_lshlrev_b64 v[48:49], 13, v[48:49]
	v_lshlrev_b64 v[50:51], 13, v[50:51]
	v_lshlrev_b64 v[52:53], 13, v[52:53]
	v_lshlrev_b64 v[54:55], 13, v[54:55]
	v_lshlrev_b64 v[56:57], 13, v[56:57]
	v_lshl_add_u64 v[24:25], v[16:17], 0, v[24:25]
	v_lshl_add_u64 v[32:33], v[16:17], 0, v[32:33]
	v_lshl_add_u64 v[28:29], v[16:17], 0, v[28:29]
	v_lshl_add_u64 v[36:37], v[16:17], 0, v[36:37]
	v_lshl_add_u64 v[34:35], v[16:17], 0, v[34:35]
	v_lshl_add_u64 v[40:41], v[16:17], 0, v[40:41]
	v_lshl_add_u64 v[38:39], v[16:17], 0, v[38:39]
	v_lshl_add_u64 v[44:45], v[16:17], 0, v[44:45]
	v_lshl_add_u64 v[42:43], v[16:17], 0, v[42:43]
	v_lshl_add_u64 v[48:49], v[16:17], 0, v[48:49]
	v_lshl_add_u64 v[46:47], v[16:17], 0, v[46:47]
	v_lshl_add_u64 v[52:53], v[16:17], 0, v[52:53]
	v_lshl_add_u64 v[50:51], v[16:17], 0, v[50:51]
	v_lshl_add_u64 v[56:57], v[16:17], 0, v[56:57]
	v_lshl_add_u64 v[54:55], v[16:17], 0, v[54:55]
	global_load_dword v5, v[26:27], off
	global_load_dword v19, v[24:25], off
	global_load_dword v23, v[32:33], off
	global_load_dword v30, v[28:29], off
	global_load_dword v58, v[36:37], off
	global_load_dword v59, v[34:35], off
	global_load_dword v60, v[40:41], off
	global_load_dword v61, v[38:39], off
	global_load_dword v62, v[44:45], off
	global_load_dword v63, v[42:43], off
	global_load_dword v64, v[48:49], off
	global_load_dword v65, v[46:47], off
	global_load_dword v66, v[52:53], off
	global_load_dword v67, v[50:51], off
	global_load_dword v68, v[56:57], off
	global_load_dword v69, v[54:55], off
	v_or_b32_e32 v26, s12, v1
	v_or_b32_e32 v24, s14, v2
	s_add_i32 s8, s8, 16
	s_add_i32 s9, s9, 16
	s_add_i32 s7, s7, -16
	v_mad_u64_u32 v[24:25], s[28:29], v24, s3, v[10:11]
	v_mad_u64_u32 v[26:27], s[28:29], v26, s3, v[10:11]
	v_or_b32_e32 v25, s16, v1
	v_or_b32_e32 v27, s17, v2
	v_or_b32_e32 v36, s18, v1
	v_or_b32_e32 v34, s19, v2
	v_or_b32_e32 v40, s25, v1
	v_or_b32_e32 v38, s27, v2
	v_or_b32_e32 v44, s30, v1
	v_or_b32_e32 v42, s31, v2
	v_or_b32_e32 v48, s33, v1
	v_or_b32_e32 v46, s34, v2
	v_or_b32_e32 v52, s35, v1
	v_or_b32_e32 v50, s36, v2
	v_or_b32_e32 v56, s37, v1
	v_or_b32_e32 v54, s38, v2
	s_cmp_lg_u32 s7, 0
	v_mad_u64_u32 v[28:29], s[16:17], v27, s3, v[10:11]
	v_mad_u64_u32 v[32:33], s[16:17], v25, s3, v[10:11]
	v_mad_u64_u32 v[34:35], s[16:17], v34, s3, v[10:11]
	v_mad_u64_u32 v[36:37], s[16:17], v36, s3, v[10:11]
	v_mad_u64_u32 v[38:39], s[16:17], v38, s3, v[10:11]
	v_mad_u64_u32 v[40:41], s[16:17], v40, s3, v[10:11]
	v_mad_u64_u32 v[42:43], s[16:17], v42, s3, v[10:11]
	v_mad_u64_u32 v[44:45], s[16:17], v44, s3, v[10:11]
	v_mad_u64_u32 v[46:47], s[16:17], v46, s3, v[10:11]
	v_mad_u64_u32 v[48:49], s[16:17], v48, s3, v[10:11]
	v_mad_u64_u32 v[50:51], s[16:17], v50, s3, v[10:11]
	v_mad_u64_u32 v[52:53], s[16:17], v52, s3, v[10:11]
	v_mad_u64_u32 v[54:55], s[16:17], v54, s3, v[10:11]
	v_mad_u64_u32 v[56:57], s[16:17], v56, s3, v[10:11]
	s_lshl_b32 s12, s9, 1
	s_lshl_b32 s14, s8, 1
	v_or_b32_e32 v104, s14, v18
	s_add_i32 s16, s12, 4
	s_add_i32 s17, s14, 4
	s_add_i32 s18, s12, 8
	s_add_i32 s19, s14, 8
	s_add_i32 s25, s12, 12
	s_add_i32 s27, s14, 12
	s_add_i32 s30, s12, 16
	s_add_i32 s31, s14, 16
	s_add_i32 s33, s12, 20
	s_add_i32 s34, s14, 20
	s_add_i32 s35, s12, 24
	s_add_i32 s36, s14, 24
	s_add_i32 s37, s12, 28
	s_add_i32 s38, s14, 28
	v_or_b32_e32 v102, s12, v3
	v_ashrrev_i32_e32 v105, 31, v104
	v_or_b32_e32 v106, s16, v3
	v_or_b32_e32 v110, s17, v18
	v_or_b32_e32 v112, s18, v3
	v_or_b32_e32 v114, s19, v18
	v_or_b32_e32 v116, s25, v3
	v_or_b32_e32 v118, s27, v18
	v_or_b32_e32 v120, s30, v3
	v_or_b32_e32 v122, s31, v18
	v_or_b32_e32 v124, s33, v3
	v_or_b32_e32 v126, s34, v18
	v_or_b32_e32 v128, s35, v3
	v_or_b32_e32 v130, s36, v18
	v_or_b32_e32 v132, s37, v3
	v_or_b32_e32 v134, s38, v18
	v_ashrrev_i32_e32 v103, 31, v102
	v_lshlrev_b64 v[104:105], 13, v[104:105]
	v_ashrrev_i32_e32 v111, 31, v110
	v_ashrrev_i32_e32 v107, 31, v106
	v_ashrrev_i32_e32 v115, 31, v114
	v_ashrrev_i32_e32 v113, 31, v112
	v_ashrrev_i32_e32 v119, 31, v118
	v_ashrrev_i32_e32 v117, 31, v116
	v_ashrrev_i32_e32 v123, 31, v122
	v_ashrrev_i32_e32 v121, 31, v120
	v_ashrrev_i32_e32 v127, 31, v126
	v_ashrrev_i32_e32 v125, 31, v124
	v_ashrrev_i32_e32 v131, 31, v130
	v_ashrrev_i32_e32 v129, 31, v128
	v_ashrrev_i32_e32 v135, 31, v134
	v_ashrrev_i32_e32 v133, 31, v132
	v_lshlrev_b64 v[102:103], 13, v[102:103]
	v_lshl_add_u64 v[104:105], v[16:17], 0, v[104:105]
	v_lshlrev_b64 v[106:107], 13, v[106:107]
	v_lshlrev_b64 v[110:111], 13, v[110:111]
	v_lshlrev_b64 v[112:113], 13, v[112:113]
	v_lshlrev_b64 v[114:115], 13, v[114:115]
	v_lshlrev_b64 v[116:117], 13, v[116:117]
	v_lshlrev_b64 v[118:119], 13, v[118:119]
	v_lshlrev_b64 v[120:121], 13, v[120:121]
	v_lshlrev_b64 v[122:123], 13, v[122:123]
	v_lshlrev_b64 v[124:125], 13, v[124:125]
	v_lshlrev_b64 v[126:127], 13, v[126:127]
	v_lshlrev_b64 v[128:129], 13, v[128:129]
	v_lshlrev_b64 v[130:131], 13, v[130:131]
	v_lshlrev_b64 v[132:133], 13, v[132:133]
	v_lshlrev_b64 v[134:135], 13, v[134:135]
	v_lshl_add_u64 v[102:103], v[16:17], 0, v[102:103]
	v_lshl_add_u64 v[110:111], v[16:17], 0, v[110:111]
	v_lshl_add_u64 v[106:107], v[16:17], 0, v[106:107]
	v_lshl_add_u64 v[114:115], v[16:17], 0, v[114:115]
	v_lshl_add_u64 v[112:113], v[16:17], 0, v[112:113]
	v_lshl_add_u64 v[118:119], v[16:17], 0, v[118:119]
	v_lshl_add_u64 v[116:117], v[16:17], 0, v[116:117]
	v_lshl_add_u64 v[122:123], v[16:17], 0, v[122:123]
	v_lshl_add_u64 v[120:121], v[16:17], 0, v[120:121]
	v_lshl_add_u64 v[126:127], v[16:17], 0, v[126:127]
	v_lshl_add_u64 v[124:125], v[16:17], 0, v[124:125]
	v_lshl_add_u64 v[130:131], v[16:17], 0, v[130:131]
	v_lshl_add_u64 v[128:129], v[16:17], 0, v[128:129]
	v_lshl_add_u64 v[134:135], v[16:17], 0, v[134:135]
	v_lshl_add_u64 v[132:133], v[16:17], 0, v[132:133]
	global_load_dword v97, v[104:105], off
	global_load_dword v99, v[102:103], off
	global_load_dword v101, v[110:111], off
	global_load_dword v108, v[106:107], off
	global_load_dword v136, v[114:115], off
	global_load_dword v137, v[112:113], off
	global_load_dword v138, v[118:119], off
	global_load_dword v139, v[116:117], off
	global_load_dword v140, v[122:123], off
	global_load_dword v141, v[120:121], off
	global_load_dword v142, v[126:127], off
	global_load_dword v143, v[124:125], off
	global_load_dword v144, v[130:131], off
	global_load_dword v145, v[128:129], off
	global_load_dword v146, v[134:135], off
	global_load_dword v147, v[132:133], off
	v_or_b32_e32 v104, s12, v1
	v_or_b32_e32 v102, s14, v2
	s_add_i32 s8, s8, 16
	s_add_i32 s9, s9, 16
	s_add_i32 s7, s7, -16
	v_mad_u64_u32 v[102:103], s[28:29], v102, s3, v[10:11]
	v_mad_u64_u32 v[104:105], s[28:29], v104, s3, v[10:11]
	v_or_b32_e32 v103, s16, v1
	v_or_b32_e32 v105, s17, v2
	v_or_b32_e32 v114, s18, v1
	v_or_b32_e32 v112, s19, v2
	v_or_b32_e32 v118, s25, v1
	v_or_b32_e32 v116, s27, v2
	v_or_b32_e32 v122, s30, v1
	v_or_b32_e32 v120, s31, v2
	v_or_b32_e32 v126, s33, v1
	v_or_b32_e32 v124, s34, v2
	v_or_b32_e32 v130, s35, v1
	v_or_b32_e32 v128, s36, v2
	v_or_b32_e32 v134, s37, v1
	v_or_b32_e32 v132, s38, v2
	s_cmp_lg_u32 s7, 0
	v_mad_u64_u32 v[106:107], s[16:17], v105, s3, v[10:11]
	v_mad_u64_u32 v[110:111], s[16:17], v103, s3, v[10:11]
	v_mad_u64_u32 v[112:113], s[16:17], v112, s3, v[10:11]
	v_mad_u64_u32 v[114:115], s[16:17], v114, s3, v[10:11]
	v_mad_u64_u32 v[116:117], s[16:17], v116, s3, v[10:11]
	v_mad_u64_u32 v[118:119], s[16:17], v118, s3, v[10:11]
	v_mad_u64_u32 v[120:121], s[16:17], v120, s3, v[10:11]
	v_mad_u64_u32 v[122:123], s[16:17], v122, s3, v[10:11]
	v_mad_u64_u32 v[124:125], s[16:17], v124, s3, v[10:11]
	v_mad_u64_u32 v[126:127], s[16:17], v126, s3, v[10:11]
	v_mad_u64_u32 v[128:129], s[16:17], v128, s3, v[10:11]
	v_mad_u64_u32 v[130:131], s[16:17], v130, s3, v[10:11]
	v_mad_u64_u32 v[132:133], s[16:17], v132, s3, v[10:11]
	v_mad_u64_u32 v[134:135], s[16:17], v134, s3, v[10:11]
	s_waitcnt vmcnt(31)
	ds_write_b32 v24, v5
	s_waitcnt vmcnt(30)
	ds_write_b32 v26, v19
	s_waitcnt vmcnt(29)
	ds_write_b32 v28, v23
	s_waitcnt vmcnt(28)
	ds_write_b32 v32, v30
	s_waitcnt vmcnt(27)
	ds_write_b32 v34, v58
	s_waitcnt vmcnt(26)
	ds_write_b32 v36, v59
	s_waitcnt vmcnt(25)
	ds_write_b32 v38, v60
	s_waitcnt vmcnt(24)
	ds_write_b32 v40, v61
	s_waitcnt vmcnt(23)
	ds_write_b32 v42, v62
	s_waitcnt vmcnt(22)
	ds_write_b32 v44, v63
	s_waitcnt vmcnt(21)
	ds_write_b32 v46, v64
	s_waitcnt vmcnt(20)
	ds_write_b32 v48, v65
	s_waitcnt vmcnt(19)
	ds_write_b32 v50, v66
	s_waitcnt vmcnt(18)
	ds_write_b32 v52, v67
	s_waitcnt vmcnt(17)
	ds_write_b32 v54, v68
	s_waitcnt vmcnt(16)
	ds_write_b32 v56, v69
	s_waitcnt vmcnt(15)
	ds_write_b32 v102, v97
	s_waitcnt vmcnt(14)
	ds_write_b32 v104, v99
	s_waitcnt vmcnt(13)
	ds_write_b32 v106, v101
	s_waitcnt vmcnt(12)
	ds_write_b32 v110, v108
	s_waitcnt vmcnt(11)
	ds_write_b32 v112, v136
	s_waitcnt vmcnt(10)
	ds_write_b32 v114, v137
	s_waitcnt vmcnt(9)
	ds_write_b32 v116, v138
	s_waitcnt vmcnt(8)
	ds_write_b32 v118, v139
	s_waitcnt vmcnt(7)
	ds_write_b32 v120, v140
	s_waitcnt vmcnt(6)
	ds_write_b32 v122, v141
	s_waitcnt vmcnt(5)
	ds_write_b32 v124, v142
	s_waitcnt vmcnt(4)
	ds_write_b32 v126, v143
	s_waitcnt vmcnt(3)
	ds_write_b32 v128, v144
	s_waitcnt vmcnt(2)
	ds_write_b32 v130, v145
	s_waitcnt vmcnt(1)
	ds_write_b32 v132, v146
	s_waitcnt vmcnt(0)
	ds_write_b32 v134, v147
	s_cbranch_scc1 .LBB0_191
	s_waitcnt lgkmcnt(0)
	ds_read2_b32 v[24:25], v11 offset0:33 offset1:41
	ds_read2_b32 v[26:27], v11 offset1:8
	ds_read2_b32 v[28:29], v11 offset0:66 offset1:74
	ds_read2_b32 v[32:33], v11 offset0:99 offset1:107
	ds_read2_b32 v[34:35], v11 offset0:132 offset1:140
	ds_read2_b32 v[36:37], v11 offset0:165 offset1:173
	ds_read2_b32 v[38:39], v11 offset0:198 offset1:206
	ds_read2_b32 v[40:41], v11 offset0:231 offset1:239
	v_or_b32_e32 v44, s24, v7
	s_ashr_i32 s27, s26, 31
	v_ashrrev_i32_e32 v45, 31, v44
	v_lshl_add_u64 v[42:43], s[26:27], 1, v[12:13]
	v_lshlrev_b64 v[44:45], 11, v[44:45]
	s_waitcnt lgkmcnt(6)
	v_cvt_pk_bf16_f32 v16, v26, v24
	s_waitcnt lgkmcnt(4)
	v_cvt_pk_bf16_f32 v17, v28, v32
	s_waitcnt lgkmcnt(2)
	v_cvt_pk_bf16_f32 v18, v34, v36
	s_waitcnt lgkmcnt(0)
	v_cvt_pk_bf16_f32 v19, v38, v40
	v_lshl_add_u64 v[44:45], v[42:43], 0, v[44:45]
	v_or_b32_e32 v24, s24, v20
	global_store_dwordx4 v[44:45], v[16:19], off
	s_add_i32 s6, s6, s10
	s_cmpk_lt_i32 s6, 0x400
	v_cvt_pk_bf16_f32 v16, v27, v25
	v_ashrrev_i32_e32 v25, 31, v24
	v_cvt_pk_bf16_f32 v17, v29, v33
	v_cvt_pk_bf16_f32 v18, v35, v37
	v_cvt_pk_bf16_f32 v19, v39, v41
	v_lshlrev_b64 v[24:25], 11, v[24:25]
	ds_read2_b32 v[26:27], v11 offset0:49 offset1:57
	ds_read2_b32 v[28:29], v11 offset0:16 offset1:24
	ds_read2_b32 v[32:33], v11 offset0:82 offset1:90
	ds_read2_b32 v[34:35], v11 offset0:115 offset1:123
	ds_read2_b32 v[36:37], v11 offset0:148 offset1:156
	ds_read2_b32 v[38:39], v11 offset0:181 offset1:189
	ds_read2_b32 v[40:41], v11 offset0:214 offset1:222
	ds_read2_b32 v[44:45], v11 offset0:247 offset1:255
	v_lshl_add_u64 v[24:25], v[42:43], 0, v[24:25]
	global_store_dwordx4 v[24:25], v[16:19], off
	v_or_b32_e32 v24, s24, v21
	v_ashrrev_i32_e32 v25, 31, v24
	v_lshlrev_b64 v[24:25], 11, v[24:25]
	s_waitcnt lgkmcnt(6)
	v_cvt_pk_bf16_f32 v16, v28, v26
	s_waitcnt lgkmcnt(4)
	v_cvt_pk_bf16_f32 v17, v32, v34
	s_waitcnt lgkmcnt(2)
	v_cvt_pk_bf16_f32 v18, v36, v38
	s_waitcnt lgkmcnt(0)
	v_cvt_pk_bf16_f32 v19, v40, v44
	v_lshl_add_u64 v[24:25], v[42:43], 0, v[24:25]
	global_store_dwordx4 v[24:25], v[16:19], off
	v_or_b32_e32 v24, s24, v22
	v_ashrrev_i32_e32 v25, 31, v24
	v_lshlrev_b64 v[24:25], 11, v[24:25]
	v_cvt_pk_bf16_f32 v16, v29, v27
	v_cvt_pk_bf16_f32 v17, v33, v35
	v_cvt_pk_bf16_f32 v18, v37, v39
	v_cvt_pk_bf16_f32 v19, v41, v45
	v_lshl_add_u64 v[24:25], v[42:43], 0, v[24:25]
	global_store_dwordx4 v[24:25], v[16:19], off
	s_waitcnt lgkmcnt(0)
	s_cbranch_scc1 .LBB0_190
	v_mov_b32_e32 v15, 0
	v_readlane_b32 s64, v251, 49
	v_lshlrev_b32_e32 v4, 2, v4
	v_mov_b32_e32 v5, v15
	v_readlane_b32 s68, v251, 53
	v_readlane_b32 s69, v251, 54
	s_movk_i32 s3, 0x84
	s_mov_b32 s6, s15
	v_lshl_add_u64 v[16:17], s[68:69], 0, v[4:5]
	v_readlane_b32 s65, v251, 50
	v_readlane_b32 s66, v251, 51
	v_readlane_b32 s67, v251, 52
	v_readlane_b32 s70, v251, 55
	v_readlane_b32 s71, v251, 56
	v_readlane_b32 s72, v251, 57
	v_readlane_b32 s73, v251, 58
	v_readlane_b32 s74, v251, 59
	v_readlane_b32 s75, v251, 60
	v_readlane_b32 s76, v251, 61
	v_readlane_b32 s77, v251, 62
	v_readlane_b32 s78, v251, 63
	v_readlane_b32 s79, v252, 0

.LBB0_195:
	s_lshl_b32 s12, s9, 1
	s_lshl_b32 s14, s8, 1
	v_or_b32_e32 v26, s14, v14
	s_add_i32 s16, s12, 4
	s_add_i32 s17, s14, 4
	s_add_i32 s18, s12, 8
	s_add_i32 s19, s14, 8
	s_add_i32 s25, s12, 12
	s_add_i32 s27, s14, 12
	s_add_i32 s30, s12, 16
	s_add_i32 s31, s14, 16
	s_add_i32 s33, s12, 20
	s_add_i32 s34, s14, 20
	s_add_i32 s35, s12, 24
	s_add_i32 s36, s14, 24
	s_add_i32 s37, s12, 28
	s_add_i32 s38, s14, 28
	v_or_b32_e32 v24, s12, v3
	v_ashrrev_i32_e32 v27, 31, v26
	v_or_b32_e32 v28, s16, v3
	v_or_b32_e32 v32, s17, v14
	v_or_b32_e32 v34, s18, v3
	v_or_b32_e32 v36, s19, v14
	v_or_b32_e32 v38, s25, v3
	v_or_b32_e32 v40, s27, v14
	v_or_b32_e32 v42, s30, v3
	v_or_b32_e32 v44, s31, v14
	v_or_b32_e32 v46, s33, v3
	v_or_b32_e32 v48, s34, v14
	v_or_b32_e32 v50, s35, v3
	v_or_b32_e32 v52, s36, v14
	v_or_b32_e32 v54, s37, v3
	v_or_b32_e32 v56, s38, v14
	v_ashrrev_i32_e32 v25, 31, v24
	v_lshlrev_b64 v[26:27], 13, v[26:27]
	v_ashrrev_i32_e32 v33, 31, v32
	v_ashrrev_i32_e32 v29, 31, v28
	v_ashrrev_i32_e32 v37, 31, v36
	v_ashrrev_i32_e32 v35, 31, v34
	v_ashrrev_i32_e32 v41, 31, v40
	v_ashrrev_i32_e32 v39, 31, v38
	v_ashrrev_i32_e32 v45, 31, v44
	v_ashrrev_i32_e32 v43, 31, v42
	v_ashrrev_i32_e32 v49, 31, v48
	v_ashrrev_i32_e32 v47, 31, v46
	v_ashrrev_i32_e32 v53, 31, v52
	v_ashrrev_i32_e32 v51, 31, v50
	v_ashrrev_i32_e32 v57, 31, v56
	v_ashrrev_i32_e32 v55, 31, v54
	v_lshlrev_b64 v[24:25], 13, v[24:25]
	v_lshl_add_u64 v[26:27], v[18:19], 0, v[26:27]
	v_lshlrev_b64 v[28:29], 13, v[28:29]
	v_lshlrev_b64 v[32:33], 13, v[32:33]
	v_lshlrev_b64 v[34:35], 13, v[34:35]
	v_lshlrev_b64 v[36:37], 13, v[36:37]
	v_lshlrev_b64 v[38:39], 13, v[38:39]
	v_lshlrev_b64 v[40:41], 13, v[40:41]
	v_lshlrev_b64 v[42:43], 13, v[42:43]
	v_lshlrev_b64 v[44:45], 13, v[44:45]
	v_lshlrev_b64 v[46:47], 13, v[46:47]
	v_lshlrev_b64 v[48:49], 13, v[48:49]
	v_lshlrev_b64 v[50:51], 13, v[50:51]
	v_lshlrev_b64 v[52:53], 13, v[52:53]
	v_lshlrev_b64 v[54:55], 13, v[54:55]
	v_lshlrev_b64 v[56:57], 13, v[56:57]
	v_lshl_add_u64 v[24:25], v[18:19], 0, v[24:25]
	v_lshl_add_u64 v[32:33], v[18:19], 0, v[32:33]
	v_lshl_add_u64 v[28:29], v[18:19], 0, v[28:29]
	v_lshl_add_u64 v[36:37], v[18:19], 0, v[36:37]
	v_lshl_add_u64 v[34:35], v[18:19], 0, v[34:35]
	v_lshl_add_u64 v[40:41], v[18:19], 0, v[40:41]
	v_lshl_add_u64 v[38:39], v[18:19], 0, v[38:39]
	v_lshl_add_u64 v[44:45], v[18:19], 0, v[44:45]
	v_lshl_add_u64 v[42:43], v[18:19], 0, v[42:43]
	v_lshl_add_u64 v[48:49], v[18:19], 0, v[48:49]
	v_lshl_add_u64 v[46:47], v[18:19], 0, v[46:47]
	v_lshl_add_u64 v[52:53], v[18:19], 0, v[52:53]
	v_lshl_add_u64 v[50:51], v[18:19], 0, v[50:51]
	v_lshl_add_u64 v[56:57], v[18:19], 0, v[56:57]
	v_lshl_add_u64 v[54:55], v[18:19], 0, v[54:55]
	global_load_dword v5, v[26:27], off
	global_load_dword v23, v[24:25], off
	global_load_dword v30, v[32:33], off
	global_load_dword v58, v[28:29], off
	global_load_dword v59, v[36:37], off
	global_load_dword v60, v[34:35], off
	global_load_dword v61, v[40:41], off
	global_load_dword v62, v[38:39], off
	global_load_dword v63, v[44:45], off
	global_load_dword v64, v[42:43], off
	global_load_dword v65, v[48:49], off
	global_load_dword v66, v[46:47], off
	global_load_dword v67, v[52:53], off
	global_load_dword v68, v[50:51], off
	global_load_dword v69, v[56:57], off
	global_load_dword v70, v[54:55], off
	v_or_b32_e32 v26, s12, v1
	v_or_b32_e32 v24, s14, v2
	s_add_i32 s8, s8, 16
	s_add_i32 s9, s9, 16
	s_add_i32 s7, s7, -16
	v_mad_u64_u32 v[24:25], s[28:29], v24, s3, v[10:11]
	v_mad_u64_u32 v[26:27], s[28:29], v26, s3, v[10:11]
	v_or_b32_e32 v25, s16, v1
	v_or_b32_e32 v27, s17, v2
	v_or_b32_e32 v36, s18, v1
	v_or_b32_e32 v34, s19, v2
	v_or_b32_e32 v40, s25, v1
	v_or_b32_e32 v38, s27, v2
	v_or_b32_e32 v44, s30, v1
	v_or_b32_e32 v42, s31, v2
	v_or_b32_e32 v48, s33, v1
	v_or_b32_e32 v46, s34, v2
	v_or_b32_e32 v52, s35, v1
	v_or_b32_e32 v50, s36, v2
	v_or_b32_e32 v56, s37, v1
	v_or_b32_e32 v54, s38, v2
	s_cmp_lg_u32 s7, 0
	v_mad_u64_u32 v[28:29], s[16:17], v27, s3, v[10:11]
	v_mad_u64_u32 v[32:33], s[16:17], v25, s3, v[10:11]
	v_mad_u64_u32 v[34:35], s[16:17], v34, s3, v[10:11]
	v_mad_u64_u32 v[36:37], s[16:17], v36, s3, v[10:11]
	v_mad_u64_u32 v[38:39], s[16:17], v38, s3, v[10:11]
	v_mad_u64_u32 v[40:41], s[16:17], v40, s3, v[10:11]
	v_mad_u64_u32 v[42:43], s[16:17], v42, s3, v[10:11]
	v_mad_u64_u32 v[44:45], s[16:17], v44, s3, v[10:11]
	v_mad_u64_u32 v[46:47], s[16:17], v46, s3, v[10:11]
	v_mad_u64_u32 v[48:49], s[16:17], v48, s3, v[10:11]
	v_mad_u64_u32 v[50:51], s[16:17], v50, s3, v[10:11]
	v_mad_u64_u32 v[52:53], s[16:17], v52, s3, v[10:11]
	v_mad_u64_u32 v[54:55], s[16:17], v54, s3, v[10:11]
	v_mad_u64_u32 v[56:57], s[16:17], v56, s3, v[10:11]
	s_lshl_b32 s12, s9, 1
	s_lshl_b32 s14, s8, 1
	v_or_b32_e32 v102, s14, v14
	s_add_i32 s16, s12, 4
	s_add_i32 s17, s14, 4
	s_add_i32 s18, s12, 8
	s_add_i32 s19, s14, 8
	s_add_i32 s25, s12, 12
	s_add_i32 s27, s14, 12
	s_add_i32 s30, s12, 16
	s_add_i32 s31, s14, 16
	s_add_i32 s33, s12, 20
	s_add_i32 s34, s14, 20
	s_add_i32 s35, s12, 24
	s_add_i32 s36, s14, 24
	s_add_i32 s37, s12, 28
	s_add_i32 s38, s14, 28
	v_or_b32_e32 v100, s12, v3
	v_ashrrev_i32_e32 v103, 31, v102
	v_or_b32_e32 v104, s16, v3
	v_or_b32_e32 v108, s17, v14
	v_or_b32_e32 v110, s18, v3
	v_or_b32_e32 v112, s19, v14
	v_or_b32_e32 v114, s25, v3
	v_or_b32_e32 v116, s27, v14
	v_or_b32_e32 v118, s30, v3
	v_or_b32_e32 v120, s31, v14
	v_or_b32_e32 v122, s33, v3
	v_or_b32_e32 v124, s34, v14
	v_or_b32_e32 v126, s35, v3
	v_or_b32_e32 v128, s36, v14
	v_or_b32_e32 v130, s37, v3
	v_or_b32_e32 v132, s38, v14
	v_ashrrev_i32_e32 v101, 31, v100
	v_lshlrev_b64 v[102:103], 13, v[102:103]
	v_ashrrev_i32_e32 v109, 31, v108
	v_ashrrev_i32_e32 v105, 31, v104
	v_ashrrev_i32_e32 v113, 31, v112
	v_ashrrev_i32_e32 v111, 31, v110
	v_ashrrev_i32_e32 v117, 31, v116
	v_ashrrev_i32_e32 v115, 31, v114
	v_ashrrev_i32_e32 v121, 31, v120
	v_ashrrev_i32_e32 v119, 31, v118
	v_ashrrev_i32_e32 v125, 31, v124
	v_ashrrev_i32_e32 v123, 31, v122
	v_ashrrev_i32_e32 v129, 31, v128
	v_ashrrev_i32_e32 v127, 31, v126
	v_ashrrev_i32_e32 v133, 31, v132
	v_ashrrev_i32_e32 v131, 31, v130
	v_lshlrev_b64 v[100:101], 13, v[100:101]
	v_lshl_add_u64 v[102:103], v[18:19], 0, v[102:103]
	v_lshlrev_b64 v[104:105], 13, v[104:105]
	v_lshlrev_b64 v[108:109], 13, v[108:109]
	v_lshlrev_b64 v[110:111], 13, v[110:111]
	v_lshlrev_b64 v[112:113], 13, v[112:113]
	v_lshlrev_b64 v[114:115], 13, v[114:115]
	v_lshlrev_b64 v[116:117], 13, v[116:117]
	v_lshlrev_b64 v[118:119], 13, v[118:119]
	v_lshlrev_b64 v[120:121], 13, v[120:121]
	v_lshlrev_b64 v[122:123], 13, v[122:123]
	v_lshlrev_b64 v[124:125], 13, v[124:125]
	v_lshlrev_b64 v[126:127], 13, v[126:127]
	v_lshlrev_b64 v[128:129], 13, v[128:129]
	v_lshlrev_b64 v[130:131], 13, v[130:131]
	v_lshlrev_b64 v[132:133], 13, v[132:133]
	v_lshl_add_u64 v[100:101], v[18:19], 0, v[100:101]
	v_lshl_add_u64 v[108:109], v[18:19], 0, v[108:109]
	v_lshl_add_u64 v[104:105], v[18:19], 0, v[104:105]
	v_lshl_add_u64 v[112:113], v[18:19], 0, v[112:113]
	v_lshl_add_u64 v[110:111], v[18:19], 0, v[110:111]
	v_lshl_add_u64 v[116:117], v[18:19], 0, v[116:117]
	v_lshl_add_u64 v[114:115], v[18:19], 0, v[114:115]
	v_lshl_add_u64 v[120:121], v[18:19], 0, v[120:121]
	v_lshl_add_u64 v[118:119], v[18:19], 0, v[118:119]
	v_lshl_add_u64 v[124:125], v[18:19], 0, v[124:125]
	v_lshl_add_u64 v[122:123], v[18:19], 0, v[122:123]
	v_lshl_add_u64 v[128:129], v[18:19], 0, v[128:129]
	v_lshl_add_u64 v[126:127], v[18:19], 0, v[126:127]
	v_lshl_add_u64 v[132:133], v[18:19], 0, v[132:133]
	v_lshl_add_u64 v[130:131], v[18:19], 0, v[130:131]
	global_load_dword v97, v[102:103], off
	global_load_dword v99, v[100:101], off
	global_load_dword v106, v[108:109], off
	global_load_dword v134, v[104:105], off
	global_load_dword v135, v[112:113], off
	global_load_dword v136, v[110:111], off
	global_load_dword v137, v[116:117], off
	global_load_dword v138, v[114:115], off
	global_load_dword v139, v[120:121], off
	global_load_dword v140, v[118:119], off
	global_load_dword v141, v[124:125], off
	global_load_dword v142, v[122:123], off
	global_load_dword v143, v[128:129], off
	global_load_dword v144, v[126:127], off
	global_load_dword v145, v[132:133], off
	global_load_dword v146, v[130:131], off
	v_or_b32_e32 v102, s12, v1
	v_or_b32_e32 v100, s14, v2
	s_add_i32 s8, s8, 16
	s_add_i32 s9, s9, 16
	s_add_i32 s7, s7, -16
	v_mad_u64_u32 v[100:101], s[28:29], v100, s3, v[10:11]
	v_mad_u64_u32 v[102:103], s[28:29], v102, s3, v[10:11]
	v_or_b32_e32 v101, s16, v1
	v_or_b32_e32 v103, s17, v2
	v_or_b32_e32 v112, s18, v1
	v_or_b32_e32 v110, s19, v2
	v_or_b32_e32 v116, s25, v1
	v_or_b32_e32 v114, s27, v2
	v_or_b32_e32 v120, s30, v1
	v_or_b32_e32 v118, s31, v2
	v_or_b32_e32 v124, s33, v1
	v_or_b32_e32 v122, s34, v2
	v_or_b32_e32 v128, s35, v1
	v_or_b32_e32 v126, s36, v2
	v_or_b32_e32 v132, s37, v1
	v_or_b32_e32 v130, s38, v2
	s_cmp_lg_u32 s7, 0
	v_mad_u64_u32 v[104:105], s[16:17], v103, s3, v[10:11]
	v_mad_u64_u32 v[108:109], s[16:17], v101, s3, v[10:11]
	v_mad_u64_u32 v[110:111], s[16:17], v110, s3, v[10:11]
	v_mad_u64_u32 v[112:113], s[16:17], v112, s3, v[10:11]
	v_mad_u64_u32 v[114:115], s[16:17], v114, s3, v[10:11]
	v_mad_u64_u32 v[116:117], s[16:17], v116, s3, v[10:11]
	v_mad_u64_u32 v[118:119], s[16:17], v118, s3, v[10:11]
	v_mad_u64_u32 v[120:121], s[16:17], v120, s3, v[10:11]
	v_mad_u64_u32 v[122:123], s[16:17], v122, s3, v[10:11]
	v_mad_u64_u32 v[124:125], s[16:17], v124, s3, v[10:11]
	v_mad_u64_u32 v[126:127], s[16:17], v126, s3, v[10:11]
	v_mad_u64_u32 v[128:129], s[16:17], v128, s3, v[10:11]
	v_mad_u64_u32 v[130:131], s[16:17], v130, s3, v[10:11]
	v_mad_u64_u32 v[132:133], s[16:17], v132, s3, v[10:11]
	s_waitcnt vmcnt(31)
	ds_write_b32 v24, v5
	s_waitcnt vmcnt(30)
	ds_write_b32 v26, v23
	s_waitcnt vmcnt(29)
	ds_write_b32 v28, v30
	s_waitcnt vmcnt(28)
	ds_write_b32 v32, v58
	s_waitcnt vmcnt(27)
	ds_write_b32 v34, v59
	s_waitcnt vmcnt(26)
	ds_write_b32 v36, v60
	s_waitcnt vmcnt(25)
	ds_write_b32 v38, v61
	s_waitcnt vmcnt(24)
	ds_write_b32 v40, v62
	s_waitcnt vmcnt(23)
	ds_write_b32 v42, v63
	s_waitcnt vmcnt(22)
	ds_write_b32 v44, v64
	s_waitcnt vmcnt(21)
	ds_write_b32 v46, v65
	s_waitcnt vmcnt(20)
	ds_write_b32 v48, v66
	s_waitcnt vmcnt(19)
	ds_write_b32 v50, v67
	s_waitcnt vmcnt(18)
	ds_write_b32 v52, v68
	s_waitcnt vmcnt(17)
	ds_write_b32 v54, v69
	s_waitcnt vmcnt(16)
	ds_write_b32 v56, v70
	s_waitcnt vmcnt(15)
	ds_write_b32 v100, v97
	s_waitcnt vmcnt(14)
	ds_write_b32 v102, v99
	s_waitcnt vmcnt(13)
	ds_write_b32 v104, v106
	s_waitcnt vmcnt(12)
	ds_write_b32 v108, v134
	s_waitcnt vmcnt(11)
	ds_write_b32 v110, v135
	s_waitcnt vmcnt(10)
	ds_write_b32 v112, v136
	s_waitcnt vmcnt(9)
	ds_write_b32 v114, v137
	s_waitcnt vmcnt(8)
	ds_write_b32 v116, v138
	s_waitcnt vmcnt(7)
	ds_write_b32 v118, v139
	s_waitcnt vmcnt(6)
	ds_write_b32 v120, v140
	s_waitcnt vmcnt(5)
	ds_write_b32 v122, v141
	s_waitcnt vmcnt(4)
	ds_write_b32 v124, v142
	s_waitcnt vmcnt(3)
	ds_write_b32 v126, v143
	s_waitcnt vmcnt(2)
	ds_write_b32 v128, v144
	s_waitcnt vmcnt(1)
	ds_write_b32 v130, v145
	s_waitcnt vmcnt(0)
	ds_write_b32 v132, v146
	s_cbranch_scc1 .LBB0_195
	s_waitcnt lgkmcnt(0)
	ds_read2_b32 v[18:19], v11 offset0:33 offset1:41
	ds_read2_b32 v[28:29], v11 offset1:8
	ds_read2_b32 v[32:33], v11 offset0:66 offset1:74
	ds_read2_b32 v[34:35], v11 offset0:99 offset1:107
	ds_read2_b32 v[36:37], v11 offset0:132 offset1:140
	ds_read2_b32 v[38:39], v11 offset0:165 offset1:173
	ds_read2_b32 v[40:41], v11 offset0:198 offset1:206
	ds_read2_b32 v[42:43], v11 offset0:231 offset1:239
	s_add_i32 s7, s26, 0x800
	s_ashr_i32 s25, s24, 31
	v_or_b32_e32 v14, s7, v7
	v_lshl_add_u64 v[44:45], s[24:25], 1, v[12:13]
	v_lshlrev_b64 v[46:47], 11, v[14:15]
	s_waitcnt lgkmcnt(6)
	v_cvt_pk_bf16_f32 v24, v28, v18
	s_waitcnt lgkmcnt(4)
	v_cvt_pk_bf16_f32 v25, v32, v34
	s_waitcnt lgkmcnt(2)
	v_cvt_pk_bf16_f32 v26, v36, v38
	s_waitcnt lgkmcnt(0)
	v_cvt_pk_bf16_f32 v27, v40, v42
	v_lshl_add_u64 v[46:47], v[44:45], 0, v[46:47]
	global_store_dwordx4 v[46:47], v[24:27], off
	v_or_b32_e32 v14, s7, v20
	s_add_i32 s6, s6, s10
	v_cvt_pk_bf16_f32 v24, v29, v19
	v_cvt_pk_bf16_f32 v25, v33, v35
	v_cvt_pk_bf16_f32 v26, v37, v39
	v_cvt_pk_bf16_f32 v27, v41, v43
	ds_read2_b32 v[28:29], v11 offset0:49 offset1:57
	ds_read2_b32 v[32:33], v11 offset0:16 offset1:24
	ds_read2_b32 v[34:35], v11 offset0:82 offset1:90
	ds_read2_b32 v[36:37], v11 offset0:115 offset1:123
	ds_read2_b32 v[38:39], v11 offset0:148 offset1:156
	ds_read2_b32 v[40:41], v11 offset0:181 offset1:189
	ds_read2_b32 v[42:43], v11 offset0:214 offset1:222
	ds_read2_b32 v[46:47], v11 offset0:247 offset1:255
	v_lshlrev_b64 v[18:19], 11, v[14:15]
	v_lshl_add_u64 v[18:19], v[44:45], 0, v[18:19]
	v_or_b32_e32 v14, s7, v21
	global_store_dwordx4 v[18:19], v[24:27], off
	v_lshlrev_b64 v[18:19], 11, v[14:15]
	v_lshl_add_u64 v[18:19], v[44:45], 0, v[18:19]
	s_waitcnt lgkmcnt(6)
	v_cvt_pk_bf16_f32 v24, v32, v28
	s_waitcnt lgkmcnt(4)
	v_cvt_pk_bf16_f32 v25, v34, v36
	s_waitcnt lgkmcnt(2)
	v_cvt_pk_bf16_f32 v26, v38, v40
	s_waitcnt lgkmcnt(0)
	v_cvt_pk_bf16_f32 v27, v42, v46
	v_or_b32_e32 v14, s7, v22
	global_store_dwordx4 v[18:19], v[24:27], off
	v_lshlrev_b64 v[18:19], 11, v[14:15]
	v_lshl_add_u64 v[18:19], v[44:45], 0, v[18:19]
	v_cvt_pk_bf16_f32 v24, v33, v29
	v_cvt_pk_bf16_f32 v25, v35, v37
	v_cvt_pk_bf16_f32 v26, v39, v41
	v_cvt_pk_bf16_f32 v27, v43, v47
	global_store_dwordx4 v[18:19], v[24:27], off
	s_waitcnt lgkmcnt(0)
	s_cmpk_lt_i32 s6, 0x400
	s_cbranch_scc1 .LBB0_194
	v_readlane_b32 s64, v251, 49
	v_mov_b32_e32 v5, 0
	v_readlane_b32 s70, v251, 55
	v_readlane_b32 s71, v251, 56
	s_movk_i32 s3, 0x84
	s_mov_b32 s6, s15
	v_lshl_add_u64 v[14:15], s[70:71], 0, v[4:5]
	v_readlane_b32 s65, v251, 50
	v_readlane_b32 s66, v251, 51
	v_readlane_b32 s67, v251, 52
	v_readlane_b32 s68, v251, 53
	v_readlane_b32 s69, v251, 54
	v_readlane_b32 s72, v251, 57
	v_readlane_b32 s73, v251, 58
	v_readlane_b32 s74, v251, 59
	v_readlane_b32 s75, v251, 60
	v_readlane_b32 s76, v251, 61
	v_readlane_b32 s77, v251, 62
	v_readlane_b32 s78, v251, 63
	v_readlane_b32 s79, v252, 0

.LBB0_199:
	s_lshl_b32 s12, s9, 1
	s_lshl_b32 s14, s8, 1
	v_or_b32_e32 v24, s14, v4
	s_add_i32 s16, s12, 4
	s_add_i32 s17, s14, 4
	s_add_i32 s18, s12, 8
	s_add_i32 s19, s14, 8
	s_add_i32 s25, s12, 12
	s_add_i32 s27, s14, 12
	s_add_i32 s30, s12, 16
	s_add_i32 s31, s14, 16
	s_add_i32 s33, s12, 20
	s_add_i32 s34, s14, 20
	s_add_i32 s35, s12, 24
	s_add_i32 s36, s14, 24
	s_add_i32 s37, s12, 28
	s_add_i32 s38, s14, 28
	v_or_b32_e32 v18, s12, v3
	v_ashrrev_i32_e32 v25, 31, v24
	v_or_b32_e32 v26, s16, v3
	v_or_b32_e32 v28, s17, v4
	v_or_b32_e32 v32, s18, v3
	v_or_b32_e32 v34, s19, v4
	v_or_b32_e32 v36, s25, v3
	v_or_b32_e32 v38, s27, v4
	v_or_b32_e32 v40, s30, v3
	v_or_b32_e32 v42, s31, v4
	v_or_b32_e32 v44, s33, v3
	v_or_b32_e32 v46, s34, v4
	v_or_b32_e32 v48, s35, v3
	v_or_b32_e32 v50, s36, v4
	v_or_b32_e32 v52, s37, v3
	v_or_b32_e32 v54, s38, v4
	v_ashrrev_i32_e32 v19, 31, v18
	v_lshlrev_b64 v[24:25], 13, v[24:25]
	v_ashrrev_i32_e32 v29, 31, v28
	v_ashrrev_i32_e32 v27, 31, v26
	v_ashrrev_i32_e32 v35, 31, v34
	v_ashrrev_i32_e32 v33, 31, v32
	v_ashrrev_i32_e32 v39, 31, v38
	v_ashrrev_i32_e32 v37, 31, v36
	v_ashrrev_i32_e32 v43, 31, v42
	v_ashrrev_i32_e32 v41, 31, v40
	v_ashrrev_i32_e32 v47, 31, v46
	v_ashrrev_i32_e32 v45, 31, v44
	v_ashrrev_i32_e32 v51, 31, v50
	v_ashrrev_i32_e32 v49, 31, v48
	v_ashrrev_i32_e32 v55, 31, v54
	v_ashrrev_i32_e32 v53, 31, v52
	v_lshlrev_b64 v[18:19], 13, v[18:19]
	v_lshl_add_u64 v[24:25], v[16:17], 0, v[24:25]
	v_lshlrev_b64 v[26:27], 13, v[26:27]
	v_lshlrev_b64 v[28:29], 13, v[28:29]
	v_lshlrev_b64 v[32:33], 13, v[32:33]
	v_lshlrev_b64 v[34:35], 13, v[34:35]
	v_lshlrev_b64 v[36:37], 13, v[36:37]
	v_lshlrev_b64 v[38:39], 13, v[38:39]
	v_lshlrev_b64 v[40:41], 13, v[40:41]
	v_lshlrev_b64 v[42:43], 13, v[42:43]
	v_lshlrev_b64 v[44:45], 13, v[44:45]
	v_lshlrev_b64 v[46:47], 13, v[46:47]
	v_lshlrev_b64 v[48:49], 13, v[48:49]
	v_lshlrev_b64 v[50:51], 13, v[50:51]
	v_lshlrev_b64 v[52:53], 13, v[52:53]
	v_lshlrev_b64 v[54:55], 13, v[54:55]
	v_lshl_add_u64 v[18:19], v[16:17], 0, v[18:19]
	v_lshl_add_u64 v[28:29], v[16:17], 0, v[28:29]
	v_lshl_add_u64 v[26:27], v[16:17], 0, v[26:27]
	v_lshl_add_u64 v[34:35], v[16:17], 0, v[34:35]
	v_lshl_add_u64 v[32:33], v[16:17], 0, v[32:33]
	v_lshl_add_u64 v[38:39], v[16:17], 0, v[38:39]
	v_lshl_add_u64 v[36:37], v[16:17], 0, v[36:37]
	v_lshl_add_u64 v[42:43], v[16:17], 0, v[42:43]
	v_lshl_add_u64 v[40:41], v[16:17], 0, v[40:41]
	v_lshl_add_u64 v[46:47], v[16:17], 0, v[46:47]
	v_lshl_add_u64 v[44:45], v[16:17], 0, v[44:45]
	v_lshl_add_u64 v[50:51], v[16:17], 0, v[50:51]
	v_lshl_add_u64 v[48:49], v[16:17], 0, v[48:49]
	v_lshl_add_u64 v[54:55], v[16:17], 0, v[54:55]
	v_lshl_add_u64 v[52:53], v[16:17], 0, v[52:53]
	global_load_dword v23, v[24:25], off
	global_load_dword v30, v[18:19], off
	global_load_dword v56, v[28:29], off
	global_load_dword v57, v[26:27], off
	global_load_dword v58, v[34:35], off
	global_load_dword v59, v[32:33], off
	global_load_dword v60, v[38:39], off
	global_load_dword v61, v[36:37], off
	global_load_dword v62, v[42:43], off
	global_load_dword v63, v[40:41], off
	global_load_dword v64, v[46:47], off
	global_load_dword v65, v[44:45], off
	global_load_dword v66, v[50:51], off
	global_load_dword v67, v[48:49], off
	global_load_dword v68, v[54:55], off
	global_load_dword v69, v[52:53], off
	v_or_b32_e32 v24, s12, v1
	v_or_b32_e32 v18, s14, v2
	s_add_i32 s8, s8, 16
	s_add_i32 s9, s9, 16
	s_add_i32 s7, s7, -16
	v_mad_u64_u32 v[18:19], s[28:29], v18, s3, v[10:11]
	v_mad_u64_u32 v[24:25], s[28:29], v24, s3, v[10:11]
	v_or_b32_e32 v19, s16, v1
	v_or_b32_e32 v25, s17, v2
	v_or_b32_e32 v34, s18, v1
	v_or_b32_e32 v32, s19, v2
	v_or_b32_e32 v38, s25, v1
	v_or_b32_e32 v36, s27, v2
	v_or_b32_e32 v42, s30, v1
	v_or_b32_e32 v40, s31, v2
	v_or_b32_e32 v46, s33, v1
	v_or_b32_e32 v44, s34, v2
	v_or_b32_e32 v50, s35, v1
	v_or_b32_e32 v48, s36, v2
	v_or_b32_e32 v54, s37, v1
	v_or_b32_e32 v52, s38, v2
	s_cmp_lg_u32 s7, 0
	v_mad_u64_u32 v[26:27], s[16:17], v25, s3, v[10:11]
	v_mad_u64_u32 v[28:29], s[16:17], v19, s3, v[10:11]
	v_mad_u64_u32 v[32:33], s[16:17], v32, s3, v[10:11]
	v_mad_u64_u32 v[34:35], s[16:17], v34, s3, v[10:11]
	v_mad_u64_u32 v[36:37], s[16:17], v36, s3, v[10:11]
	v_mad_u64_u32 v[38:39], s[16:17], v38, s3, v[10:11]
	v_mad_u64_u32 v[40:41], s[16:17], v40, s3, v[10:11]
	v_mad_u64_u32 v[42:43], s[16:17], v42, s3, v[10:11]
	v_mad_u64_u32 v[44:45], s[16:17], v44, s3, v[10:11]
	v_mad_u64_u32 v[46:47], s[16:17], v46, s3, v[10:11]
	v_mad_u64_u32 v[48:49], s[16:17], v48, s3, v[10:11]
	v_mad_u64_u32 v[50:51], s[16:17], v50, s3, v[10:11]
	v_mad_u64_u32 v[52:53], s[16:17], v52, s3, v[10:11]
	v_mad_u64_u32 v[54:55], s[16:17], v54, s3, v[10:11]
	s_lshl_b32 s12, s9, 1
	s_lshl_b32 s14, s8, 1
	v_or_b32_e32 v100, s14, v4
	s_add_i32 s16, s12, 4
	s_add_i32 s17, s14, 4
	s_add_i32 s18, s12, 8
	s_add_i32 s19, s14, 8
	s_add_i32 s25, s12, 12
	s_add_i32 s27, s14, 12
	s_add_i32 s30, s12, 16
	s_add_i32 s31, s14, 16
	s_add_i32 s33, s12, 20
	s_add_i32 s34, s14, 20
	s_add_i32 s35, s12, 24
	s_add_i32 s36, s14, 24
	s_add_i32 s37, s12, 28
	s_add_i32 s38, s14, 28
	v_or_b32_e32 v96, s12, v3
	v_ashrrev_i32_e32 v101, 31, v100
	v_or_b32_e32 v102, s16, v3
	v_or_b32_e32 v104, s17, v4
	v_or_b32_e32 v108, s18, v3
	v_or_b32_e32 v110, s19, v4
	v_or_b32_e32 v112, s25, v3
	v_or_b32_e32 v114, s27, v4
	v_or_b32_e32 v116, s30, v3
	v_or_b32_e32 v118, s31, v4
	v_or_b32_e32 v120, s33, v3
	v_or_b32_e32 v122, s34, v4
	v_or_b32_e32 v124, s35, v3
	v_or_b32_e32 v126, s36, v4
	v_or_b32_e32 v128, s37, v3
	v_or_b32_e32 v130, s38, v4
	v_ashrrev_i32_e32 v97, 31, v96
	v_lshlrev_b64 v[100:101], 13, v[100:101]
	v_ashrrev_i32_e32 v105, 31, v104
	v_ashrrev_i32_e32 v103, 31, v102
	v_ashrrev_i32_e32 v111, 31, v110
	v_ashrrev_i32_e32 v109, 31, v108
	v_ashrrev_i32_e32 v115, 31, v114
	v_ashrrev_i32_e32 v113, 31, v112
	v_ashrrev_i32_e32 v119, 31, v118
	v_ashrrev_i32_e32 v117, 31, v116
	v_ashrrev_i32_e32 v123, 31, v122
	v_ashrrev_i32_e32 v121, 31, v120
	v_ashrrev_i32_e32 v127, 31, v126
	v_ashrrev_i32_e32 v125, 31, v124
	v_ashrrev_i32_e32 v131, 31, v130
	v_ashrrev_i32_e32 v129, 31, v128
	v_lshlrev_b64 v[96:97], 13, v[96:97]
	v_lshl_add_u64 v[100:101], v[16:17], 0, v[100:101]
	v_lshlrev_b64 v[102:103], 13, v[102:103]
	v_lshlrev_b64 v[104:105], 13, v[104:105]
	v_lshlrev_b64 v[108:109], 13, v[108:109]
	v_lshlrev_b64 v[110:111], 13, v[110:111]
	v_lshlrev_b64 v[112:113], 13, v[112:113]
	v_lshlrev_b64 v[114:115], 13, v[114:115]
	v_lshlrev_b64 v[116:117], 13, v[116:117]
	v_lshlrev_b64 v[118:119], 13, v[118:119]
	v_lshlrev_b64 v[120:121], 13, v[120:121]
	v_lshlrev_b64 v[122:123], 13, v[122:123]
	v_lshlrev_b64 v[124:125], 13, v[124:125]
	v_lshlrev_b64 v[126:127], 13, v[126:127]
	v_lshlrev_b64 v[128:129], 13, v[128:129]
	v_lshlrev_b64 v[130:131], 13, v[130:131]
	v_lshl_add_u64 v[96:97], v[16:17], 0, v[96:97]
	v_lshl_add_u64 v[104:105], v[16:17], 0, v[104:105]
	v_lshl_add_u64 v[102:103], v[16:17], 0, v[102:103]
	v_lshl_add_u64 v[110:111], v[16:17], 0, v[110:111]
	v_lshl_add_u64 v[108:109], v[16:17], 0, v[108:109]
	v_lshl_add_u64 v[114:115], v[16:17], 0, v[114:115]
	v_lshl_add_u64 v[112:113], v[16:17], 0, v[112:113]
	v_lshl_add_u64 v[118:119], v[16:17], 0, v[118:119]
	v_lshl_add_u64 v[116:117], v[16:17], 0, v[116:117]
	v_lshl_add_u64 v[122:123], v[16:17], 0, v[122:123]
	v_lshl_add_u64 v[120:121], v[16:17], 0, v[120:121]
	v_lshl_add_u64 v[126:127], v[16:17], 0, v[126:127]
	v_lshl_add_u64 v[124:125], v[16:17], 0, v[124:125]
	v_lshl_add_u64 v[130:131], v[16:17], 0, v[130:131]
	v_lshl_add_u64 v[128:129], v[16:17], 0, v[128:129]
	global_load_dword v99, v[100:101], off
	global_load_dword v106, v[96:97], off
	global_load_dword v132, v[104:105], off
	global_load_dword v133, v[102:103], off
	global_load_dword v134, v[110:111], off
	global_load_dword v135, v[108:109], off
	global_load_dword v136, v[114:115], off
	global_load_dword v137, v[112:113], off
	global_load_dword v138, v[118:119], off
	global_load_dword v139, v[116:117], off
	global_load_dword v140, v[122:123], off
	global_load_dword v141, v[120:121], off
	global_load_dword v142, v[126:127], off
	global_load_dword v143, v[124:125], off
	global_load_dword v144, v[130:131], off
	global_load_dword v145, v[128:129], off
	v_or_b32_e32 v100, s12, v1
	v_or_b32_e32 v96, s14, v2
	s_add_i32 s8, s8, 16
	s_add_i32 s9, s9, 16
	s_add_i32 s7, s7, -16
	v_mad_u64_u32 v[96:97], s[28:29], v96, s3, v[10:11]
	v_mad_u64_u32 v[100:101], s[28:29], v100, s3, v[10:11]
	v_or_b32_e32 v97, s16, v1
	v_or_b32_e32 v101, s17, v2
	v_or_b32_e32 v110, s18, v1
	v_or_b32_e32 v108, s19, v2
	v_or_b32_e32 v114, s25, v1
	v_or_b32_e32 v112, s27, v2
	v_or_b32_e32 v118, s30, v1
	v_or_b32_e32 v116, s31, v2
	v_or_b32_e32 v122, s33, v1
	v_or_b32_e32 v120, s34, v2
	v_or_b32_e32 v126, s35, v1
	v_or_b32_e32 v124, s36, v2
	v_or_b32_e32 v130, s37, v1
	v_or_b32_e32 v128, s38, v2
	s_cmp_lg_u32 s7, 0
	v_mad_u64_u32 v[102:103], s[16:17], v101, s3, v[10:11]
	v_mad_u64_u32 v[104:105], s[16:17], v97, s3, v[10:11]
	v_mad_u64_u32 v[108:109], s[16:17], v108, s3, v[10:11]
	v_mad_u64_u32 v[110:111], s[16:17], v110, s3, v[10:11]
	v_mad_u64_u32 v[112:113], s[16:17], v112, s3, v[10:11]
	v_mad_u64_u32 v[114:115], s[16:17], v114, s3, v[10:11]
	v_mad_u64_u32 v[116:117], s[16:17], v116, s3, v[10:11]
	v_mad_u64_u32 v[118:119], s[16:17], v118, s3, v[10:11]
	v_mad_u64_u32 v[120:121], s[16:17], v120, s3, v[10:11]
	v_mad_u64_u32 v[122:123], s[16:17], v122, s3, v[10:11]
	v_mad_u64_u32 v[124:125], s[16:17], v124, s3, v[10:11]
	v_mad_u64_u32 v[126:127], s[16:17], v126, s3, v[10:11]
	v_mad_u64_u32 v[128:129], s[16:17], v128, s3, v[10:11]
	v_mad_u64_u32 v[130:131], s[16:17], v130, s3, v[10:11]
	s_waitcnt vmcnt(31)
	ds_write_b32 v18, v23
	s_waitcnt vmcnt(30)
	ds_write_b32 v24, v30
	s_waitcnt vmcnt(29)
	ds_write_b32 v26, v56
	s_waitcnt vmcnt(28)
	ds_write_b32 v28, v57
	s_waitcnt vmcnt(27)
	ds_write_b32 v32, v58
	s_waitcnt vmcnt(26)
	ds_write_b32 v34, v59
	s_waitcnt vmcnt(25)
	ds_write_b32 v36, v60
	s_waitcnt vmcnt(24)
	ds_write_b32 v38, v61
	s_waitcnt vmcnt(23)
	ds_write_b32 v40, v62
	s_waitcnt vmcnt(22)
	ds_write_b32 v42, v63
	s_waitcnt vmcnt(21)
	ds_write_b32 v44, v64
	s_waitcnt vmcnt(20)
	ds_write_b32 v46, v65
	s_waitcnt vmcnt(19)
	ds_write_b32 v48, v66
	s_waitcnt vmcnt(18)
	ds_write_b32 v50, v67
	s_waitcnt vmcnt(17)
	ds_write_b32 v52, v68
	s_waitcnt vmcnt(16)
	ds_write_b32 v54, v69
	s_waitcnt vmcnt(15)
	ds_write_b32 v96, v99
	s_waitcnt vmcnt(14)
	ds_write_b32 v100, v106
	s_waitcnt vmcnt(13)
	ds_write_b32 v102, v132
	s_waitcnt vmcnt(12)
	ds_write_b32 v104, v133
	s_waitcnt vmcnt(11)
	ds_write_b32 v108, v134
	s_waitcnt vmcnt(10)
	ds_write_b32 v110, v135
	s_waitcnt vmcnt(9)
	ds_write_b32 v112, v136
	s_waitcnt vmcnt(8)
	ds_write_b32 v114, v137
	s_waitcnt vmcnt(7)
	ds_write_b32 v116, v138
	s_waitcnt vmcnt(6)
	ds_write_b32 v118, v139
	s_waitcnt vmcnt(5)
	ds_write_b32 v120, v140
	s_waitcnt vmcnt(4)
	ds_write_b32 v122, v141
	s_waitcnt vmcnt(3)
	ds_write_b32 v124, v142
	s_waitcnt vmcnt(2)
	ds_write_b32 v126, v143
	s_waitcnt vmcnt(1)
	ds_write_b32 v128, v144
	s_waitcnt vmcnt(0)
	ds_write_b32 v130, v145
	s_cbranch_scc1 .LBB0_199
	s_waitcnt lgkmcnt(0)
	ds_read2_b32 v[24:25], v11 offset0:33 offset1:41
	ds_read2_b32 v[26:27], v11 offset1:8
	ds_read2_b32 v[28:29], v11 offset0:66 offset1:74
	ds_read2_b32 v[32:33], v11 offset0:99 offset1:107
	ds_read2_b32 v[34:35], v11 offset0:132 offset1:140
	ds_read2_b32 v[36:37], v11 offset0:165 offset1:173
	ds_read2_b32 v[38:39], v11 offset0:198 offset1:206
	ds_read2_b32 v[40:41], v11 offset0:231 offset1:239
	s_add_i32 s7, s26, 0x1000
	s_ashr_i32 s25, s24, 31
	v_or_b32_e32 v4, s7, v7
	v_lshl_add_u64 v[42:43], s[24:25], 1, v[12:13]
	v_lshlrev_b64 v[44:45], 11, v[4:5]
	s_waitcnt lgkmcnt(6)
	v_cvt_pk_bf16_f32 v16, v26, v24
	s_waitcnt lgkmcnt(4)
	v_cvt_pk_bf16_f32 v17, v28, v32
	s_waitcnt lgkmcnt(2)
	v_cvt_pk_bf16_f32 v18, v34, v36
	s_waitcnt lgkmcnt(0)
	v_cvt_pk_bf16_f32 v19, v38, v40
	v_lshl_add_u64 v[44:45], v[42:43], 0, v[44:45]
	global_store_dwordx4 v[44:45], v[16:19], off
	v_or_b32_e32 v4, s7, v20
	s_add_i32 s6, s6, s10
	v_cvt_pk_bf16_f32 v16, v27, v25
	v_cvt_pk_bf16_f32 v17, v29, v33
	v_cvt_pk_bf16_f32 v18, v35, v37
	v_cvt_pk_bf16_f32 v19, v39, v41
	ds_read2_b32 v[26:27], v11 offset0:49 offset1:57
	ds_read2_b32 v[28:29], v11 offset0:16 offset1:24
	ds_read2_b32 v[32:33], v11 offset0:82 offset1:90
	ds_read2_b32 v[34:35], v11 offset0:115 offset1:123
	ds_read2_b32 v[36:37], v11 offset0:148 offset1:156
	ds_read2_b32 v[38:39], v11 offset0:181 offset1:189
	ds_read2_b32 v[40:41], v11 offset0:214 offset1:222
	ds_read2_b32 v[44:45], v11 offset0:247 offset1:255
	v_lshlrev_b64 v[24:25], 11, v[4:5]
	v_lshl_add_u64 v[24:25], v[42:43], 0, v[24:25]
	v_or_b32_e32 v4, s7, v21
	global_store_dwordx4 v[24:25], v[16:19], off
	v_lshlrev_b64 v[24:25], 11, v[4:5]
	v_lshl_add_u64 v[24:25], v[42:43], 0, v[24:25]
	s_waitcnt lgkmcnt(6)
	v_cvt_pk_bf16_f32 v16, v28, v26
	s_waitcnt lgkmcnt(4)
	v_cvt_pk_bf16_f32 v17, v32, v34
	s_waitcnt lgkmcnt(2)
	v_cvt_pk_bf16_f32 v18, v36, v38
	s_waitcnt lgkmcnt(0)
	v_cvt_pk_bf16_f32 v19, v40, v44
	v_or_b32_e32 v4, s7, v22
	global_store_dwordx4 v[24:25], v[16:19], off
	v_lshlrev_b64 v[24:25], 11, v[4:5]
	v_lshl_add_u64 v[24:25], v[42:43], 0, v[24:25]
	v_cvt_pk_bf16_f32 v16, v29, v27
	v_cvt_pk_bf16_f32 v17, v33, v35
	v_cvt_pk_bf16_f32 v18, v37, v39
	v_cvt_pk_bf16_f32 v19, v41, v45
	global_store_dwordx4 v[24:25], v[16:19], off
	s_waitcnt lgkmcnt(0)
	s_cmpk_lt_i32 s6, 0x400
	s_cbranch_scc1 .LBB0_198

.LBB0_204:
	s_lshl_b32 s8, s1, 1
	s_lshl_b32 s9, s7, 1
	v_or_b32_e32 v22, s9, v16
	s_add_i32 s12, s8, 4
	s_add_i32 s14, s9, 4
	s_add_i32 s16, s8, 8
	s_add_i32 s17, s9, 8
	s_add_i32 s18, s8, 12
	s_add_i32 s19, s9, 12
	s_add_i32 s25, s8, 16
	s_add_i32 s26, s9, 16
	s_add_i32 s27, s8, 20
	s_add_i32 s28, s9, 20
	s_add_i32 s29, s8, 24
	s_add_i32 s30, s9, 24
	s_add_i32 s31, s8, 28
	s_add_i32 s33, s9, 28
	v_or_b32_e32 v20, s8, v3
	v_ashrrev_i32_e32 v23, 31, v22
	v_or_b32_e32 v24, s12, v3
	v_or_b32_e32 v26, s14, v16
	v_or_b32_e32 v28, s16, v3
	v_or_b32_e32 v32, s17, v16
	v_or_b32_e32 v34, s18, v3
	v_or_b32_e32 v36, s19, v16
	v_or_b32_e32 v38, s25, v3
	v_or_b32_e32 v40, s26, v16
	v_or_b32_e32 v42, s27, v3
	v_or_b32_e32 v44, s28, v16
	v_or_b32_e32 v46, s29, v3
	v_or_b32_e32 v48, s30, v16
	v_or_b32_e32 v50, s31, v3
	v_or_b32_e32 v52, s33, v16
	v_ashrrev_i32_e32 v21, 31, v20
	v_lshlrev_b64 v[22:23], 13, v[22:23]
	v_ashrrev_i32_e32 v27, 31, v26
	v_ashrrev_i32_e32 v25, 31, v24
	v_ashrrev_i32_e32 v33, 31, v32
	v_ashrrev_i32_e32 v29, 31, v28
	v_ashrrev_i32_e32 v37, 31, v36
	v_ashrrev_i32_e32 v35, 31, v34
	v_ashrrev_i32_e32 v41, 31, v40
	v_ashrrev_i32_e32 v39, 31, v38
	v_ashrrev_i32_e32 v45, 31, v44
	v_ashrrev_i32_e32 v43, 31, v42
	v_ashrrev_i32_e32 v49, 31, v48
	v_ashrrev_i32_e32 v47, 31, v46
	v_ashrrev_i32_e32 v53, 31, v52
	v_ashrrev_i32_e32 v51, 31, v50
	v_lshlrev_b64 v[20:21], 13, v[20:21]
	v_lshl_add_u64 v[22:23], v[14:15], 0, v[22:23]
	v_lshlrev_b64 v[24:25], 13, v[24:25]
	v_lshlrev_b64 v[26:27], 13, v[26:27]
	v_lshlrev_b64 v[28:29], 13, v[28:29]
	v_lshlrev_b64 v[32:33], 13, v[32:33]
	v_lshlrev_b64 v[34:35], 13, v[34:35]
	v_lshlrev_b64 v[36:37], 13, v[36:37]
	v_lshlrev_b64 v[38:39], 13, v[38:39]
	v_lshlrev_b64 v[40:41], 13, v[40:41]
	v_lshlrev_b64 v[42:43], 13, v[42:43]
	v_lshlrev_b64 v[44:45], 13, v[44:45]
	v_lshlrev_b64 v[46:47], 13, v[46:47]
	v_lshlrev_b64 v[48:49], 13, v[48:49]
	v_lshlrev_b64 v[50:51], 13, v[50:51]
	v_lshlrev_b64 v[52:53], 13, v[52:53]
	v_lshl_add_u64 v[20:21], v[14:15], 0, v[20:21]
	v_lshl_add_u64 v[26:27], v[14:15], 0, v[26:27]
	v_lshl_add_u64 v[24:25], v[14:15], 0, v[24:25]
	v_lshl_add_u64 v[32:33], v[14:15], 0, v[32:33]
	v_lshl_add_u64 v[28:29], v[14:15], 0, v[28:29]
	v_lshl_add_u64 v[36:37], v[14:15], 0, v[36:37]
	v_lshl_add_u64 v[34:35], v[14:15], 0, v[34:35]
	v_lshl_add_u64 v[40:41], v[14:15], 0, v[40:41]
	v_lshl_add_u64 v[38:39], v[14:15], 0, v[38:39]
	v_lshl_add_u64 v[44:45], v[14:15], 0, v[44:45]
	v_lshl_add_u64 v[42:43], v[14:15], 0, v[42:43]
	v_lshl_add_u64 v[48:49], v[14:15], 0, v[48:49]
	v_lshl_add_u64 v[46:47], v[14:15], 0, v[46:47]
	v_lshl_add_u64 v[52:53], v[14:15], 0, v[52:53]
	v_lshl_add_u64 v[50:51], v[14:15], 0, v[50:51]
	global_load_dword v19, v[22:23], off
	global_load_dword v30, v[20:21], off
	global_load_dword v54, v[26:27], off
	global_load_dword v55, v[24:25], off
	global_load_dword v56, v[32:33], off
	global_load_dword v57, v[28:29], off
	global_load_dword v58, v[36:37], off
	global_load_dword v59, v[34:35], off
	global_load_dword v60, v[40:41], off
	global_load_dword v61, v[38:39], off
	global_load_dword v62, v[44:45], off
	global_load_dword v63, v[42:43], off
	global_load_dword v64, v[48:49], off
	global_load_dword v65, v[46:47], off
	global_load_dword v66, v[52:53], off
	global_load_dword v67, v[50:51], off
	v_or_b32_e32 v22, s8, v1
	v_or_b32_e32 v20, s9, v2
	s_add_i32 s7, s7, 16
	s_add_i32 s1, s1, 16
	s_add_i32 s6, s6, -16
	v_mad_u64_u32 v[20:21], s[8:9], v20, s3, v[10:11]
	v_mad_u64_u32 v[22:23], s[8:9], v22, s3, v[10:11]
	v_or_b32_e32 v21, s12, v1
	v_or_b32_e32 v23, s14, v2
	v_or_b32_e32 v32, s16, v1
	v_or_b32_e32 v28, s17, v2
	v_or_b32_e32 v36, s18, v1
	v_or_b32_e32 v34, s19, v2
	v_or_b32_e32 v40, s25, v1
	v_or_b32_e32 v38, s26, v2
	v_or_b32_e32 v44, s27, v1
	v_or_b32_e32 v42, s28, v2
	v_or_b32_e32 v48, s29, v1
	v_or_b32_e32 v46, s30, v2
	v_or_b32_e32 v52, s31, v1
	v_or_b32_e32 v50, s33, v2
	s_cmp_lg_u32 s6, 0
	v_mad_u64_u32 v[24:25], s[8:9], v23, s3, v[10:11]
	v_mad_u64_u32 v[26:27], s[8:9], v21, s3, v[10:11]
	v_mad_u64_u32 v[28:29], s[8:9], v28, s3, v[10:11]
	v_mad_u64_u32 v[32:33], s[8:9], v32, s3, v[10:11]
	v_mad_u64_u32 v[34:35], s[8:9], v34, s3, v[10:11]
	v_mad_u64_u32 v[36:37], s[8:9], v36, s3, v[10:11]
	v_mad_u64_u32 v[38:39], s[8:9], v38, s3, v[10:11]
	v_mad_u64_u32 v[40:41], s[8:9], v40, s3, v[10:11]
	v_mad_u64_u32 v[42:43], s[8:9], v42, s3, v[10:11]
	v_mad_u64_u32 v[44:45], s[8:9], v44, s3, v[10:11]
	v_mad_u64_u32 v[46:47], s[8:9], v46, s3, v[10:11]
	v_mad_u64_u32 v[48:49], s[8:9], v48, s3, v[10:11]
	v_mad_u64_u32 v[50:51], s[8:9], v50, s3, v[10:11]
	v_mad_u64_u32 v[52:53], s[8:9], v52, s3, v[10:11]
	s_lshl_b32 s8, s1, 1
	s_lshl_b32 s9, s7, 1
	v_or_b32_e32 v100, s9, v16
	s_add_i32 s12, s8, 4
	s_add_i32 s14, s9, 4
	s_add_i32 s16, s8, 8
	s_add_i32 s17, s9, 8
	s_add_i32 s18, s8, 12
	s_add_i32 s19, s9, 12
	s_add_i32 s25, s8, 16
	s_add_i32 s26, s9, 16
	s_add_i32 s27, s8, 20
	s_add_i32 s28, s9, 20
	s_add_i32 s29, s8, 24
	s_add_i32 s30, s9, 24
	s_add_i32 s31, s8, 28
	s_add_i32 s33, s9, 28
	v_or_b32_e32 v98, s8, v3
	v_ashrrev_i32_e32 v101, 31, v100
	v_or_b32_e32 v102, s12, v3
	v_or_b32_e32 v104, s14, v16
	v_or_b32_e32 v106, s16, v3
	v_or_b32_e32 v110, s17, v16
	v_or_b32_e32 v112, s18, v3
	v_or_b32_e32 v114, s19, v16
	v_or_b32_e32 v116, s25, v3
	v_or_b32_e32 v118, s26, v16
	v_or_b32_e32 v120, s27, v3
	v_or_b32_e32 v122, s28, v16
	v_or_b32_e32 v124, s29, v3
	v_or_b32_e32 v126, s30, v16
	v_or_b32_e32 v128, s31, v3
	v_or_b32_e32 v130, s33, v16
	v_ashrrev_i32_e32 v99, 31, v98
	v_lshlrev_b64 v[100:101], 13, v[100:101]
	v_ashrrev_i32_e32 v105, 31, v104
	v_ashrrev_i32_e32 v103, 31, v102
	v_ashrrev_i32_e32 v111, 31, v110
	v_ashrrev_i32_e32 v107, 31, v106
	v_ashrrev_i32_e32 v115, 31, v114
	v_ashrrev_i32_e32 v113, 31, v112
	v_ashrrev_i32_e32 v119, 31, v118
	v_ashrrev_i32_e32 v117, 31, v116
	v_ashrrev_i32_e32 v123, 31, v122
	v_ashrrev_i32_e32 v121, 31, v120
	v_ashrrev_i32_e32 v127, 31, v126
	v_ashrrev_i32_e32 v125, 31, v124
	v_ashrrev_i32_e32 v131, 31, v130
	v_ashrrev_i32_e32 v129, 31, v128
	v_lshlrev_b64 v[98:99], 13, v[98:99]
	v_lshl_add_u64 v[100:101], v[14:15], 0, v[100:101]
	v_lshlrev_b64 v[102:103], 13, v[102:103]
	v_lshlrev_b64 v[104:105], 13, v[104:105]
	v_lshlrev_b64 v[106:107], 13, v[106:107]
	v_lshlrev_b64 v[110:111], 13, v[110:111]
	v_lshlrev_b64 v[112:113], 13, v[112:113]
	v_lshlrev_b64 v[114:115], 13, v[114:115]
	v_lshlrev_b64 v[116:117], 13, v[116:117]
	v_lshlrev_b64 v[118:119], 13, v[118:119]
	v_lshlrev_b64 v[120:121], 13, v[120:121]
	v_lshlrev_b64 v[122:123], 13, v[122:123]
	v_lshlrev_b64 v[124:125], 13, v[124:125]
	v_lshlrev_b64 v[126:127], 13, v[126:127]
	v_lshlrev_b64 v[128:129], 13, v[128:129]
	v_lshlrev_b64 v[130:131], 13, v[130:131]
	v_lshl_add_u64 v[98:99], v[14:15], 0, v[98:99]
	v_lshl_add_u64 v[104:105], v[14:15], 0, v[104:105]
	v_lshl_add_u64 v[102:103], v[14:15], 0, v[102:103]
	v_lshl_add_u64 v[110:111], v[14:15], 0, v[110:111]
	v_lshl_add_u64 v[106:107], v[14:15], 0, v[106:107]
	v_lshl_add_u64 v[114:115], v[14:15], 0, v[114:115]
	v_lshl_add_u64 v[112:113], v[14:15], 0, v[112:113]
	v_lshl_add_u64 v[118:119], v[14:15], 0, v[118:119]
	v_lshl_add_u64 v[116:117], v[14:15], 0, v[116:117]
	v_lshl_add_u64 v[122:123], v[14:15], 0, v[122:123]
	v_lshl_add_u64 v[120:121], v[14:15], 0, v[120:121]
	v_lshl_add_u64 v[126:127], v[14:15], 0, v[126:127]
	v_lshl_add_u64 v[124:125], v[14:15], 0, v[124:125]
	v_lshl_add_u64 v[130:131], v[14:15], 0, v[130:131]
	v_lshl_add_u64 v[128:129], v[14:15], 0, v[128:129]
	global_load_dword v97, v[100:101], off
	global_load_dword v108, v[98:99], off
	global_load_dword v132, v[104:105], off
	global_load_dword v133, v[102:103], off
	global_load_dword v134, v[110:111], off
	global_load_dword v135, v[106:107], off
	global_load_dword v136, v[114:115], off
	global_load_dword v137, v[112:113], off
	global_load_dword v138, v[118:119], off
	global_load_dword v139, v[116:117], off
	global_load_dword v140, v[122:123], off
	global_load_dword v141, v[120:121], off
	global_load_dword v142, v[126:127], off
	global_load_dword v143, v[124:125], off
	global_load_dword v144, v[130:131], off
	global_load_dword v145, v[128:129], off
	v_or_b32_e32 v100, s8, v1
	v_or_b32_e32 v98, s9, v2
	s_add_i32 s7, s7, 16
	s_add_i32 s1, s1, 16
	s_add_i32 s6, s6, -16
	v_mad_u64_u32 v[98:99], s[8:9], v98, s3, v[10:11]
	v_mad_u64_u32 v[100:101], s[8:9], v100, s3, v[10:11]
	v_or_b32_e32 v99, s12, v1
	v_or_b32_e32 v101, s14, v2
	v_or_b32_e32 v110, s16, v1
	v_or_b32_e32 v106, s17, v2
	v_or_b32_e32 v114, s18, v1
	v_or_b32_e32 v112, s19, v2
	v_or_b32_e32 v118, s25, v1
	v_or_b32_e32 v116, s26, v2
	v_or_b32_e32 v122, s27, v1
	v_or_b32_e32 v120, s28, v2
	v_or_b32_e32 v126, s29, v1
	v_or_b32_e32 v124, s30, v2
	v_or_b32_e32 v130, s31, v1
	v_or_b32_e32 v128, s33, v2
	s_cmp_lg_u32 s6, 0
	v_mad_u64_u32 v[102:103], s[8:9], v101, s3, v[10:11]
	v_mad_u64_u32 v[104:105], s[8:9], v99, s3, v[10:11]
	v_mad_u64_u32 v[106:107], s[8:9], v106, s3, v[10:11]
	v_mad_u64_u32 v[110:111], s[8:9], v110, s3, v[10:11]
	v_mad_u64_u32 v[112:113], s[8:9], v112, s3, v[10:11]
	v_mad_u64_u32 v[114:115], s[8:9], v114, s3, v[10:11]
	v_mad_u64_u32 v[116:117], s[8:9], v116, s3, v[10:11]
	v_mad_u64_u32 v[118:119], s[8:9], v118, s3, v[10:11]
	v_mad_u64_u32 v[120:121], s[8:9], v120, s3, v[10:11]
	v_mad_u64_u32 v[122:123], s[8:9], v122, s3, v[10:11]
	v_mad_u64_u32 v[124:125], s[8:9], v124, s3, v[10:11]
	v_mad_u64_u32 v[126:127], s[8:9], v126, s3, v[10:11]
	v_mad_u64_u32 v[128:129], s[8:9], v128, s3, v[10:11]
	v_mad_u64_u32 v[130:131], s[8:9], v130, s3, v[10:11]
	s_waitcnt vmcnt(31)
	ds_write_b32 v20, v19
	s_waitcnt vmcnt(30)
	ds_write_b32 v22, v30
	s_waitcnt vmcnt(29)
	ds_write_b32 v24, v54
	s_waitcnt vmcnt(28)
	ds_write_b32 v26, v55
	s_waitcnt vmcnt(27)
	ds_write_b32 v28, v56
	s_waitcnt vmcnt(26)
	ds_write_b32 v32, v57
	s_waitcnt vmcnt(25)
	ds_write_b32 v34, v58
	s_waitcnt vmcnt(24)
	ds_write_b32 v36, v59
	s_waitcnt vmcnt(23)
	ds_write_b32 v38, v60
	s_waitcnt vmcnt(22)
	ds_write_b32 v40, v61
	s_waitcnt vmcnt(21)
	ds_write_b32 v42, v62
	s_waitcnt vmcnt(20)
	ds_write_b32 v44, v63
	s_waitcnt vmcnt(19)
	ds_write_b32 v46, v64
	s_waitcnt vmcnt(18)
	ds_write_b32 v48, v65
	s_waitcnt vmcnt(17)
	ds_write_b32 v50, v66
	s_waitcnt vmcnt(16)
	ds_write_b32 v52, v67
	s_waitcnt vmcnt(15)
	ds_write_b32 v98, v97
	s_waitcnt vmcnt(14)
	ds_write_b32 v100, v108
	s_waitcnt vmcnt(13)
	ds_write_b32 v102, v132
	s_waitcnt vmcnt(12)
	ds_write_b32 v104, v133
	s_waitcnt vmcnt(11)
	ds_write_b32 v106, v134
	s_waitcnt vmcnt(10)
	ds_write_b32 v110, v135
	s_waitcnt vmcnt(9)
	ds_write_b32 v112, v136
	s_waitcnt vmcnt(8)
	ds_write_b32 v114, v137
	s_waitcnt vmcnt(7)
	ds_write_b32 v116, v138
	s_waitcnt vmcnt(6)
	ds_write_b32 v118, v139
	s_waitcnt vmcnt(5)
	ds_write_b32 v120, v140
	s_waitcnt vmcnt(4)
	ds_write_b32 v122, v141
	s_waitcnt vmcnt(3)
	ds_write_b32 v124, v142
	s_waitcnt vmcnt(2)
	ds_write_b32 v126, v143
	s_waitcnt vmcnt(1)
	ds_write_b32 v128, v144
	s_waitcnt vmcnt(0)
	ds_write_b32 v130, v145
	s_cbranch_scc1 .LBB0_204
	s_waitcnt lgkmcnt(0)
	ds_read2_b32 v[14:15], v9 offset0:33 offset1:41
	ds_read2_b32 v[24:25], v9 offset1:8
	ds_read2_b32 v[26:27], v9 offset0:66 offset1:74
	ds_read2_b32 v[28:29], v9 offset0:99 offset1:107
	ds_read2_b32 v[32:33], v9 offset0:132 offset1:140
	ds_read2_b32 v[34:35], v9 offset0:165 offset1:173
	ds_read2_b32 v[36:37], v9 offset0:198 offset1:206
	ds_read2_b32 v[38:39], v9 offset0:231 offset1:239
	v_or_b32_e32 v42, s0, v7
	s_ashr_i32 s25, s24, 31
	v_ashrrev_i32_e32 v43, 31, v42
	v_lshl_add_u64 v[40:41], s[24:25], 1, v[12:13]
	v_lshlrev_b64 v[42:43], 12, v[42:43]
	s_waitcnt lgkmcnt(6)
	v_cvt_pk_bf16_f32 v20, v24, v14
	s_waitcnt lgkmcnt(4)
	v_cvt_pk_bf16_f32 v21, v26, v28
	s_waitcnt lgkmcnt(2)
	v_cvt_pk_bf16_f32 v22, v32, v34
	s_waitcnt lgkmcnt(0)
	v_cvt_pk_bf16_f32 v23, v36, v38
	v_lshl_add_u64 v[42:43], v[40:41], 0, v[42:43]
	v_or_b32_e32 v14, s0, v11
	global_store_dwordx4 v[42:43], v[20:23], off
	s_add_i32 s2, s2, s10
	s_cmpk_lt_i32 s2, 0x800
	v_cvt_pk_bf16_f32 v20, v25, v15
	v_ashrrev_i32_e32 v15, 31, v14
	v_cvt_pk_bf16_f32 v21, v27, v29
	v_cvt_pk_bf16_f32 v22, v33, v35
	v_cvt_pk_bf16_f32 v23, v37, v39
	v_lshlrev_b64 v[14:15], 12, v[14:15]
	ds_read2_b32 v[24:25], v9 offset0:49 offset1:57
	ds_read2_b32 v[26:27], v9 offset0:16 offset1:24
	ds_read2_b32 v[28:29], v9 offset0:82 offset1:90
	ds_read2_b32 v[32:33], v9 offset0:115 offset1:123
	ds_read2_b32 v[34:35], v9 offset0:148 offset1:156
	ds_read2_b32 v[36:37], v9 offset0:181 offset1:189
	ds_read2_b32 v[38:39], v9 offset0:214 offset1:222
	ds_read2_b32 v[42:43], v9 offset0:247 offset1:255
	v_lshl_add_u64 v[14:15], v[40:41], 0, v[14:15]
	global_store_dwordx4 v[14:15], v[20:23], off
	v_or_b32_e32 v14, s0, v17
	v_ashrrev_i32_e32 v15, 31, v14
	v_lshlrev_b64 v[14:15], 12, v[14:15]
	s_waitcnt lgkmcnt(6)
	v_cvt_pk_bf16_f32 v20, v26, v24
	s_waitcnt lgkmcnt(4)
	v_cvt_pk_bf16_f32 v21, v28, v32
	s_waitcnt lgkmcnt(2)
	v_cvt_pk_bf16_f32 v22, v34, v36
	s_waitcnt lgkmcnt(0)
	v_cvt_pk_bf16_f32 v23, v38, v42
	v_lshl_add_u64 v[14:15], v[40:41], 0, v[14:15]
	global_store_dwordx4 v[14:15], v[20:23], off
	v_or_b32_e32 v14, s0, v18
	v_ashrrev_i32_e32 v15, 31, v14
	v_lshlrev_b64 v[14:15], 12, v[14:15]
	v_cvt_pk_bf16_f32 v20, v27, v25
	v_cvt_pk_bf16_f32 v21, v29, v33
	v_cvt_pk_bf16_f32 v22, v35, v37
	v_cvt_pk_bf16_f32 v23, v39, v43
	v_lshl_add_u64 v[14:15], v[40:41], 0, v[14:15]
	global_store_dwordx4 v[14:15], v[20:23], off
	s_waitcnt lgkmcnt(0)
	s_cbranch_scc1 .LBB0_203

.LBB0_278:
	s_lshl_b32 s25, s12, 1
	s_lshl_b32 s28, s2, 1
	v_or_b32_e32 v13, s25, v3
	v_or_b32_e32 v24, s28, v12
	s_add_i32 s29, s25, 4
	s_add_i32 s30, s28, 4
	s_add_i32 s31, s25, 8
	s_add_i32 s33, s28, 8
	s_add_i32 s34, s25, 12
	s_add_i32 s35, s28, 12
	s_add_i32 s36, s25, 16
	s_add_i32 s37, s28, 16
	s_add_i32 s38, s25, 20
	s_add_i32 s39, s28, 20
	s_add_i32 s40, s25, 24
	s_add_i32 s41, s28, 24
	s_add_i32 s42, s25, 28
	s_add_i32 s43, s28, 28
	v_mad_i64_i32 v[24:25], s[18:19], v24, s8, v[14:15]
	v_mad_i64_i32 v[26:27], s[18:19], v13, s8, v[14:15]
	v_or_b32_e32 v13, s29, v3
	v_or_b32_e32 v28, s30, v12
	v_or_b32_e32 v34, s31, v3
	v_or_b32_e32 v32, s33, v12
	v_or_b32_e32 v38, s34, v3
	v_or_b32_e32 v36, s35, v12
	v_or_b32_e32 v42, s36, v3
	v_or_b32_e32 v40, s37, v12
	v_or_b32_e32 v46, s38, v3
	v_or_b32_e32 v44, s39, v12
	v_or_b32_e32 v50, s40, v3
	v_or_b32_e32 v48, s41, v12
	v_or_b32_e32 v54, s42, v3
	v_or_b32_e32 v52, s43, v12
	v_mad_i64_i32 v[28:29], s[18:19], v28, s8, v[14:15]
	v_mad_i64_i32 v[30:31], s[18:19], v13, s8, v[14:15]
	v_mad_i64_i32 v[32:33], s[18:19], v32, s8, v[14:15]
	v_mad_i64_i32 v[34:35], s[18:19], v34, s8, v[14:15]
	v_mad_i64_i32 v[36:37], s[18:19], v36, s8, v[14:15]
	v_mad_i64_i32 v[38:39], s[18:19], v38, s8, v[14:15]
	v_mad_i64_i32 v[40:41], s[18:19], v40, s8, v[14:15]
	v_mad_i64_i32 v[42:43], s[18:19], v42, s8, v[14:15]
	v_mad_i64_i32 v[44:45], s[18:19], v44, s8, v[14:15]
	v_mad_i64_i32 v[46:47], s[18:19], v46, s8, v[14:15]
	v_mad_i64_i32 v[48:49], s[18:19], v48, s8, v[14:15]
	v_mad_i64_i32 v[50:51], s[18:19], v50, s8, v[14:15]
	v_mad_i64_i32 v[52:53], s[18:19], v52, s8, v[14:15]
	v_mad_i64_i32 v[54:55], s[18:19], v54, s8, v[14:15]
	global_load_dword v13, v[24:25], off
	global_load_dword v56, v[26:27], off
	global_load_dword v57, v[28:29], off
	global_load_dword v58, v[30:31], off
	global_load_dword v59, v[32:33], off
	global_load_dword v60, v[34:35], off
	global_load_dword v61, v[36:37], off
	global_load_dword v62, v[38:39], off
	global_load_dword v63, v[40:41], off
	global_load_dword v64, v[42:43], off
	global_load_dword v65, v[44:45], off
	global_load_dword v66, v[46:47], off
	global_load_dword v67, v[48:49], off
	global_load_dword v68, v[50:51], off
	global_load_dword v69, v[52:53], off
	global_load_dword v70, v[54:55], off
	v_or_b32_e32 v26, s25, v1
	v_or_b32_e32 v24, s28, v2
	s_add_i32 s2, s2, 16
	s_add_i32 s12, s12, 16
	s_add_i32 s3, s3, -16
	v_mad_u64_u32 v[24:25], s[18:19], v24, s9, v[6:7]
	v_mad_u64_u32 v[26:27], s[18:19], v26, s9, v[6:7]
	v_or_b32_e32 v25, s29, v1
	v_or_b32_e32 v27, s30, v2
	v_or_b32_e32 v34, s31, v1
	v_or_b32_e32 v32, s33, v2
	v_or_b32_e32 v38, s34, v1
	v_or_b32_e32 v36, s35, v2
	v_or_b32_e32 v42, s36, v1
	v_or_b32_e32 v40, s37, v2
	v_or_b32_e32 v46, s38, v1
	v_or_b32_e32 v44, s39, v2
	v_or_b32_e32 v50, s40, v1
	v_or_b32_e32 v48, s41, v2
	v_or_b32_e32 v54, s42, v1
	v_or_b32_e32 v52, s43, v2
	s_cmp_lg_u32 s3, 0
	v_mad_u64_u32 v[28:29], s[18:19], v27, s9, v[6:7]
	v_mad_u64_u32 v[30:31], s[18:19], v25, s9, v[6:7]
	v_mad_u64_u32 v[32:33], s[18:19], v32, s9, v[6:7]
	v_mad_u64_u32 v[34:35], s[18:19], v34, s9, v[6:7]
	v_mad_u64_u32 v[36:37], s[18:19], v36, s9, v[6:7]
	v_mad_u64_u32 v[38:39], s[18:19], v38, s9, v[6:7]
	v_mad_u64_u32 v[40:41], s[18:19], v40, s9, v[6:7]
	v_mad_u64_u32 v[42:43], s[18:19], v42, s9, v[6:7]
	v_mad_u64_u32 v[44:45], s[18:19], v44, s9, v[6:7]
	v_mad_u64_u32 v[46:47], s[18:19], v46, s9, v[6:7]
	v_mad_u64_u32 v[48:49], s[18:19], v48, s9, v[6:7]
	v_mad_u64_u32 v[50:51], s[18:19], v50, s9, v[6:7]
	v_mad_u64_u32 v[52:53], s[18:19], v52, s9, v[6:7]
	v_mad_u64_u32 v[54:55], s[18:19], v54, s9, v[6:7]
	s_lshl_b32 s25, s12, 1
	s_lshl_b32 s28, s2, 1
	v_or_b32_e32 v193, s25, v3
	v_or_b32_e32 v194, s28, v12
	s_add_i32 s29, s25, 4
	s_add_i32 s30, s28, 4
	s_add_i32 s31, s25, 8
	s_add_i32 s33, s28, 8
	s_add_i32 s34, s25, 12
	s_add_i32 s35, s28, 12
	s_add_i32 s36, s25, 16
	s_add_i32 s37, s28, 16
	s_add_i32 s38, s25, 20
	s_add_i32 s39, s28, 20
	s_add_i32 s40, s25, 24
	s_add_i32 s41, s28, 24
	s_add_i32 s42, s25, 28
	s_add_i32 s43, s28, 28
	v_mad_i64_i32 v[194:195], s[18:19], v194, s8, v[14:15]
	v_mad_i64_i32 v[196:197], s[18:19], v193, s8, v[14:15]
	v_or_b32_e32 v193, s29, v3
	v_or_b32_e32 v198, s30, v12
	v_or_b32_e32 v204, s31, v3
	v_or_b32_e32 v202, s33, v12
	v_or_b32_e32 v208, s34, v3
	v_or_b32_e32 v206, s35, v12
	v_or_b32_e32 v212, s36, v3
	v_or_b32_e32 v210, s37, v12
	v_or_b32_e32 v216, s38, v3
	v_or_b32_e32 v214, s39, v12
	v_or_b32_e32 v220, s40, v3
	v_or_b32_e32 v218, s41, v12
	v_or_b32_e32 v224, s42, v3
	v_or_b32_e32 v222, s43, v12
	v_mad_i64_i32 v[198:199], s[18:19], v198, s8, v[14:15]
	v_mad_i64_i32 v[200:201], s[18:19], v193, s8, v[14:15]
	v_mad_i64_i32 v[202:203], s[18:19], v202, s8, v[14:15]
	v_mad_i64_i32 v[204:205], s[18:19], v204, s8, v[14:15]
	v_mad_i64_i32 v[206:207], s[18:19], v206, s8, v[14:15]
	v_mad_i64_i32 v[208:209], s[18:19], v208, s8, v[14:15]
	v_mad_i64_i32 v[210:211], s[18:19], v210, s8, v[14:15]
	v_mad_i64_i32 v[212:213], s[18:19], v212, s8, v[14:15]
	v_mad_i64_i32 v[214:215], s[18:19], v214, s8, v[14:15]
	v_mad_i64_i32 v[216:217], s[18:19], v216, s8, v[14:15]
	v_mad_i64_i32 v[218:219], s[18:19], v218, s8, v[14:15]
	v_mad_i64_i32 v[220:221], s[18:19], v220, s8, v[14:15]
	v_mad_i64_i32 v[222:223], s[18:19], v222, s8, v[14:15]
	v_mad_i64_i32 v[224:225], s[18:19], v224, s8, v[14:15]
	global_load_dword v193, v[194:195], off
	global_load_dword v226, v[196:197], off
	global_load_dword v227, v[198:199], off
	global_load_dword v228, v[200:201], off
	global_load_dword v229, v[202:203], off
	global_load_dword v230, v[204:205], off
	global_load_dword v231, v[206:207], off
	global_load_dword v232, v[208:209], off
	global_load_dword v233, v[210:211], off
	global_load_dword v234, v[212:213], off
	global_load_dword v235, v[214:215], off
	global_load_dword v236, v[216:217], off
	global_load_dword v237, v[218:219], off
	global_load_dword v238, v[220:221], off
	global_load_dword v239, v[222:223], off
	global_load_dword v240, v[224:225], off
	v_or_b32_e32 v196, s25, v1
	v_or_b32_e32 v194, s28, v2
	s_add_i32 s2, s2, 16
	s_add_i32 s12, s12, 16
	s_add_i32 s3, s3, -16
	v_mad_u64_u32 v[194:195], s[18:19], v194, s9, v[6:7]
	v_mad_u64_u32 v[196:197], s[18:19], v196, s9, v[6:7]
	v_or_b32_e32 v195, s29, v1
	v_or_b32_e32 v197, s30, v2
	v_or_b32_e32 v204, s31, v1
	v_or_b32_e32 v202, s33, v2
	v_or_b32_e32 v208, s34, v1
	v_or_b32_e32 v206, s35, v2
	v_or_b32_e32 v212, s36, v1
	v_or_b32_e32 v210, s37, v2
	v_or_b32_e32 v216, s38, v1
	v_or_b32_e32 v214, s39, v2
	v_or_b32_e32 v220, s40, v1
	v_or_b32_e32 v218, s41, v2
	v_or_b32_e32 v224, s42, v1
	v_or_b32_e32 v222, s43, v2
	s_cmp_lg_u32 s3, 0
	v_mad_u64_u32 v[198:199], s[18:19], v197, s9, v[6:7]
	v_mad_u64_u32 v[200:201], s[18:19], v195, s9, v[6:7]
	v_mad_u64_u32 v[202:203], s[18:19], v202, s9, v[6:7]
	v_mad_u64_u32 v[204:205], s[18:19], v204, s9, v[6:7]
	v_mad_u64_u32 v[206:207], s[18:19], v206, s9, v[6:7]
	v_mad_u64_u32 v[208:209], s[18:19], v208, s9, v[6:7]
	v_mad_u64_u32 v[210:211], s[18:19], v210, s9, v[6:7]
	v_mad_u64_u32 v[212:213], s[18:19], v212, s9, v[6:7]
	v_mad_u64_u32 v[214:215], s[18:19], v214, s9, v[6:7]
	v_mad_u64_u32 v[216:217], s[18:19], v216, s9, v[6:7]
	v_mad_u64_u32 v[218:219], s[18:19], v218, s9, v[6:7]
	v_mad_u64_u32 v[220:221], s[18:19], v220, s9, v[6:7]
	v_mad_u64_u32 v[222:223], s[18:19], v222, s9, v[6:7]
	v_mad_u64_u32 v[224:225], s[18:19], v224, s9, v[6:7]
	s_waitcnt vmcnt(31)
	ds_write_b32 v24, v13
	s_waitcnt vmcnt(30)
	ds_write_b32 v26, v56
	s_waitcnt vmcnt(29)
	ds_write_b32 v28, v57
	s_waitcnt vmcnt(28)
	ds_write_b32 v30, v58
	s_waitcnt vmcnt(27)
	ds_write_b32 v32, v59
	s_waitcnt vmcnt(26)
	ds_write_b32 v34, v60
	s_waitcnt vmcnt(25)
	ds_write_b32 v36, v61
	s_waitcnt vmcnt(24)
	ds_write_b32 v38, v62
	s_waitcnt vmcnt(23)
	ds_write_b32 v40, v63
	s_waitcnt vmcnt(22)
	ds_write_b32 v42, v64
	s_waitcnt vmcnt(21)
	ds_write_b32 v44, v65
	s_waitcnt vmcnt(20)
	ds_write_b32 v46, v66
	s_waitcnt vmcnt(19)
	ds_write_b32 v48, v67
	s_waitcnt vmcnt(18)
	ds_write_b32 v50, v68
	s_waitcnt vmcnt(17)
	ds_write_b32 v52, v69
	s_waitcnt vmcnt(16)
	ds_write_b32 v54, v70
	s_waitcnt vmcnt(15)
	ds_write_b32 v194, v193
	s_waitcnt vmcnt(14)
	ds_write_b32 v196, v226
	s_waitcnt vmcnt(13)
	ds_write_b32 v198, v227
	s_waitcnt vmcnt(12)
	ds_write_b32 v200, v228
	s_waitcnt vmcnt(11)
	ds_write_b32 v202, v229
	s_waitcnt vmcnt(10)
	ds_write_b32 v204, v230
	s_waitcnt vmcnt(9)
	ds_write_b32 v206, v231
	s_waitcnt vmcnt(8)
	ds_write_b32 v208, v232
	s_waitcnt vmcnt(7)
	ds_write_b32 v210, v233
	s_waitcnt vmcnt(6)
	ds_write_b32 v212, v234
	s_waitcnt vmcnt(5)
	ds_write_b32 v214, v235
	s_waitcnt vmcnt(4)
	ds_write_b32 v216, v236
	s_waitcnt vmcnt(3)
	ds_write_b32 v218, v237
	s_waitcnt vmcnt(2)
	ds_write_b32 v220, v238
	s_waitcnt vmcnt(1)
	ds_write_b32 v222, v239
	s_waitcnt vmcnt(0)
	ds_write_b32 v224, v240
	s_cbranch_scc1 .LBB0_278
	s_lshl_b32 s1, s1, 6
	s_and_b32 s1, s1, 0xffffff00
	s_and_b32 s2, s26, 0x60
	s_or_b32 s12, s1, s2
	v_or_b32_e32 v14, s12, v16
	v_readlane_b32 s2, v251, 41
	v_ashrrev_i32_e32 v15, 31, v14
	v_readlane_b32 s3, v251, 42
	s_waitcnt lgkmcnt(0)
	s_ashr_i32 s25, s24, 31
	s_nop 0
	v_lshl_add_u64 v[24:25], v[14:15], 2, s[2:3]
	global_load_dword v13, v[24:25], off
	ds_read2_b32 v[24:25], v18 offset1:33
	ds_read2_b32 v[26:27], v18 offset0:66 offset1:99
	ds_read2_b32 v[28:29], v18 offset0:132 offset1:165
	ds_read2_b32 v[30:31], v18 offset0:198 offset1:231
	ds_read2_b32 v[32:33], v21 offset0:8 offset1:41
	ds_read2_b32 v[34:35], v21 offset0:74 offset1:107
	ds_read2_b32 v[36:37], v21 offset0:140 offset1:173
	ds_read2_b32 v[38:39], v21 offset0:206 offset1:239
	ds_read2_b32 v[40:41], v22 offset0:16 offset1:49
	s_waitcnt vmcnt(0)
	v_max_f32_e32 v13, v13, v13
	v_max_f32_e32 v13, 0xda24260, v13
	v_div_scale_f32 v42, s[2:3], v13, v13, s14
	v_rcp_f32_e32 v43, v42
	v_div_scale_f32 v44, vcc, s14, v13, s14
	v_readlane_b32 s2, v252, 7
	v_fma_f32 v45, -v42, v43, 1.0
	v_fmac_f32_e32 v43, v45, v43
	v_mul_f32_e32 v45, v44, v43
	v_fma_f32 v46, -v42, v45, v44
	v_fmac_f32_e32 v45, v46, v43
	v_fma_f32 v42, -v42, v45, v44
	v_div_fmas_f32 v42, v42, v43, v45
	v_div_fixup_f32 v42, v42, v13, s14
	s_waitcnt lgkmcnt(8)
	v_mul_f32_e32 v25, v42, v25
	s_waitcnt lgkmcnt(6)
	v_mul_f32_e32 v29, v42, v29
	s_waitcnt lgkmcnt(4)
	v_mul_f32_e32 v33, v42, v33
	v_mul_f32_e32 v24, v24, v42
	v_mul_f32_e32 v26, v42, v26
	v_mul_f32_e32 v28, v42, v28
	v_mul_f32_e32 v32, v42, v32
	s_waitcnt lgkmcnt(3)
	v_mul_f32_e32 v34, v42, v34
	v_med3_f32 v25, v25, s15, v20
	v_med3_f32 v29, v29, s15, v20
	v_med3_f32 v33, v33, s15, v20
	v_mul_f32_e32 v27, v42, v27
	v_mul_f32_e32 v30, v42, v30
	v_mul_f32_e32 v35, v42, v35
	v_med3_f32 v24, v24, s15, v20
	v_med3_f32 v26, v26, s15, v20
	v_med3_f32 v28, v28, s15, v20
	v_med3_f32 v32, v32, s15, v20
	v_med3_f32 v34, v34, s15, v20
	v_rndne_f32_e32 v25, v25
	v_rndne_f32_e32 v29, v29
	v_rndne_f32_e32 v33, v33
	v_mul_f32_e32 v31, v42, v31
	v_med3_f32 v27, v27, s15, v20
	v_med3_f32 v30, v30, s15, v20
	v_med3_f32 v35, v35, s15, v20
	v_rndne_f32_e32 v24, v24
	v_rndne_f32_e32 v26, v26
	v_rndne_f32_e32 v28, v28
	v_rndne_f32_e32 v32, v32
	v_rndne_f32_e32 v34, v34
	v_cvt_i32_f32_e32 v25, v25
	v_cvt_i32_f32_e32 v29, v29
	v_cvt_i32_f32_e32 v33, v33
	v_med3_f32 v31, v31, s15, v20
	v_rndne_f32_e32 v27, v27
	v_rndne_f32_e32 v30, v30
	v_rndne_f32_e32 v35, v35
	v_cvt_i32_f32_e32 v24, v24
	v_cvt_i32_f32_sdwa v26, v26 dst_sel:WORD_1 dst_unused:UNUSED_PAD src0_sel:DWORD
	v_cvt_i32_f32_e32 v28, v28
	v_cvt_i32_f32_e32 v32, v32
	v_cvt_i32_f32_sdwa v34, v34 dst_sel:WORD_1 dst_unused:UNUSED_PAD src0_sel:DWORD
	s_waitcnt lgkmcnt(2)
	v_mul_f32_e32 v37, v42, v37
	v_rndne_f32_e32 v31, v31
	v_cvt_i32_f32_sdwa v27, v27 dst_sel:BYTE_3 dst_unused:UNUSED_PAD src0_sel:DWORD
	v_cvt_i32_f32_sdwa v30, v30 dst_sel:WORD_1 dst_unused:UNUSED_PAD src0_sel:DWORD
	v_cvt_i32_f32_sdwa v35, v35 dst_sel:BYTE_3 dst_unused:UNUSED_PAD src0_sel:DWORD
	v_mul_f32_e32 v36, v42, v36
	s_waitcnt lgkmcnt(1)
	v_mul_f32_e32 v38, v42, v38
	v_med3_f32 v37, v37, s15, v20
	v_cvt_i32_f32_sdwa v31, v31 dst_sel:BYTE_3 dst_unused:UNUSED_PAD src0_sel:DWORD
	v_mul_f32_e32 v39, v42, v39
	v_med3_f32 v36, v36, s15, v20
	v_med3_f32 v38, v38, s15, v20
	v_rndne_f32_e32 v37, v37
	v_lshlrev_b32_e32 v25, 8, v25
	v_lshlrev_b32_e32 v29, 8, v29
	v_lshlrev_b32_e32 v33, 8, v33
	v_med3_f32 v39, v39, s15, v20
	v_rndne_f32_e32 v36, v36
	v_rndne_f32_e32 v38, v38
	v_cvt_i32_f32_e32 v37, v37
	v_and_b32_e32 v26, 0xff0000, v26
	v_and_b32_e32 v34, 0xff0000, v34
	v_perm_b32 v24, v25, v24, s16
	v_perm_b32 v25, v29, v28, s16
	v_perm_b32 v28, v33, v32, s16
	v_rndne_f32_e32 v39, v39
	v_cvt_i32_f32_e32 v36, v36
	v_cvt_i32_f32_sdwa v38, v38 dst_sel:WORD_1 dst_unused:UNUSED_PAD src0_sel:DWORD
	v_and_b32_e32 v30, 0xff0000, v30
	v_or3_b32 v24, v24, v26, v27
	v_or3_b32 v26, v28, v34, v35
	ds_read2_b32 v[28:29], v22 offset0:82 offset1:115
	v_cvt_i32_f32_sdwa v39, v39 dst_sel:BYTE_3 dst_unused:UNUSED_PAD src0_sel:DWORD
	v_or3_b32 v25, v25, v30, v31
	s_waitcnt lgkmcnt(1)
	v_mul_f32_e32 v31, v42, v41
	v_med3_f32 v31, v31, s15, v20
	v_lshlrev_b32_e32 v37, 8, v37
	v_rndne_f32_e32 v31, v31
	v_perm_b32 v27, v37, v36, s16
	v_and_b32_e32 v30, 0xff0000, v38
	v_cvt_i32_f32_e32 v31, v31
	v_or3_b32 v27, v27, v30, v39
	v_mul_f32_e32 v30, v42, v40
	s_waitcnt lgkmcnt(0)
	v_mul_f32_e32 v28, v42, v28
	v_mul_f32_e32 v29, v42, v29
	v_med3_f32 v30, v30, s15, v20
	v_med3_f32 v28, v28, s15, v20
	v_rndne_f32_e32 v30, v30
	v_rndne_f32_e32 v28, v28
	v_med3_f32 v29, v29, s15, v20
	v_cvt_i32_f32_e32 v32, v30
	v_lshlrev_b32_e32 v33, 8, v31
	v_cvt_i32_f32_sdwa v28, v28 dst_sel:WORD_1 dst_unused:UNUSED_PAD src0_sel:DWORD
	v_rndne_f32_e32 v29, v29
	ds_read2_b32 v[30:31], v22 offset0:148 offset1:181
	v_cvt_i32_f32_sdwa v29, v29 dst_sel:BYTE_3 dst_unused:UNUSED_PAD src0_sel:DWORD
	v_perm_b32 v34, v33, v32, s16
	v_and_b32_e32 v28, 0xff0000, v28
	ds_read2_b32 v[32:33], v22 offset0:214 offset1:247
	v_or3_b32 v28, v34, v28, v29
	s_waitcnt lgkmcnt(1)
	v_mul_f32_e32 v29, v42, v30
	v_mul_f32_e32 v30, v42, v31
	v_med3_f32 v30, v30, s15, v20
	v_rndne_f32_e32 v30, v30
	v_cvt_i32_f32_e32 v30, v30
	v_med3_f32 v29, v29, s15, v20
	v_rndne_f32_e32 v29, v29
	s_waitcnt lgkmcnt(0)
	v_mul_f32_e32 v31, v42, v32
	v_cvt_i32_f32_e32 v29, v29
	v_mul_f32_e32 v32, v42, v33
	v_lshlrev_b32_e32 v33, 8, v30
	v_med3_f32 v30, v31, s15, v20
	v_rndne_f32_e32 v30, v30
	v_cvt_i32_f32_sdwa v34, v30 dst_sel:WORD_1 dst_unused:UNUSED_PAD src0_sel:DWORD
	v_med3_f32 v30, v32, s15, v20
	v_rndne_f32_e32 v30, v30
	v_perm_b32 v29, v33, v29, s16
	ds_read2_b32 v[32:33], v23 offset0:90 offset1:123
	v_cvt_i32_f32_sdwa v35, v30 dst_sel:BYTE_3 dst_unused:UNUSED_PAD src0_sel:DWORD
	ds_read2_b32 v[30:31], v23 offset0:24 offset1:57
	v_and_b32_e32 v34, 0xff0000, v34
	v_readlane_b32 s3, v252, 8
	s_waitcnt lgkmcnt(1)
	v_mul_f32_e32 v32, v42, v32
	v_med3_f32 v32, v32, s15, v20
	s_waitcnt lgkmcnt(0)
	v_mul_f32_e32 v31, v42, v31
	v_mul_f32_e32 v30, v42, v30
	v_mul_f32_e32 v33, v42, v33
	v_med3_f32 v31, v31, s15, v20
	v_rndne_f32_e32 v32, v32
	v_rndne_f32_e32 v31, v31
	v_med3_f32 v30, v30, s15, v20
	v_cvt_i32_f32_sdwa v36, v32 dst_sel:WORD_1 dst_unused:UNUSED_PAD src0_sel:DWORD
	v_med3_f32 v32, v33, s15, v20
	v_cvt_i32_f32_e32 v31, v31
	v_rndne_f32_e32 v30, v30
	v_rndne_f32_e32 v32, v32
	v_cvt_i32_f32_e32 v30, v30
	v_cvt_i32_f32_sdwa v37, v32 dst_sel:BYTE_3 dst_unused:UNUSED_PAD src0_sel:DWORD
	ds_read2_b32 v[32:33], v23 offset0:156 offset1:189
	v_or3_b32 v29, v29, v34, v35
	ds_read2_b32 v[34:35], v23 offset0:222 offset1:255
	v_lshlrev_b32_e32 v31, 8, v31
	v_perm_b32 v30, v31, v30, s16
	v_and_b32_e32 v31, 0xff0000, v36
	v_or3_b32 v30, v30, v31, v37
	s_waitcnt lgkmcnt(1)
	v_mul_f32_e32 v31, v42, v32
	v_mul_f32_e32 v32, v42, v33
	s_waitcnt lgkmcnt(0)
	v_mul_f32_e32 v33, v42, v34
	v_med3_f32 v32, v32, s15, v20
	v_mul_f32_e32 v34, v42, v35
	v_med3_f32 v31, v31, s15, v20
	v_rndne_f32_e32 v32, v32
	v_med3_f32 v33, v33, s15, v20
	v_rndne_f32_e32 v31, v31
	v_cvt_i32_f32_e32 v32, v32
	v_rndne_f32_e32 v33, v33
	v_med3_f32 v34, v34, s15, v20
	v_cvt_i32_f32_e32 v31, v31
	v_cvt_i32_f32_sdwa v33, v33 dst_sel:WORD_1 dst_unused:UNUSED_PAD src0_sel:DWORD
	v_rndne_f32_e32 v34, v34
	v_cvt_i32_f32_sdwa v34, v34 dst_sel:BYTE_3 dst_unused:UNUSED_PAD src0_sel:DWORD
	v_lshlrev_b32_e32 v32, 8, v32
	v_perm_b32 v31, v32, v31, s16
	v_and_b32_e32 v32, 0xff0000, v33
	v_or3_b32 v31, v31, v32, v34
	v_lshlrev_b64 v[32:33], 11, v[14:15]
	v_lshl_add_u64 v[32:33], s[2:3], 0, v[32:33]
	v_lshl_add_u64 v[32:33], v[32:33], 0, s[24:25]
	v_lshl_add_u64 v[32:33], v[32:33], 0, v[8:9]
	global_store_dwordx4 v[32:33], v[24:27], off
	global_store_dwordx4 v[32:33], v[28:31], off offset:16
	s_nop 0
	v_or_b32_e32 v24, s0, v17
	v_cmp_eq_u32_e64 s[0:1], 0, v24
	s_and_saveexec_b64 s[2:3], s[0:1]
	s_cbranch_execz .LBB0_281
	v_mul_f32_e32 v13, 0x3c010204, v13
	v_lshl_add_u64 v[14:15], v[14:15], 2, s[22:23]
	global_store_dword v[14:15], v13, off

.LBB0_282:
	s_lshl_b32 s19, s2, 1
	s_lshl_b32 s28, s3, 1
	v_or_b32_e32 v13, s19, v3
	v_or_b32_e32 v24, s28, v12
	s_add_i32 s29, s19, 4
	s_add_i32 s30, s28, 4
	s_add_i32 s31, s19, 8
	s_add_i32 s33, s28, 8
	s_add_i32 s34, s19, 12
	s_add_i32 s35, s28, 12
	s_add_i32 s36, s19, 16
	s_add_i32 s37, s28, 16
	s_add_i32 s38, s19, 20
	s_add_i32 s39, s28, 20
	s_add_i32 s40, s19, 24
	s_add_i32 s41, s28, 24
	s_add_i32 s42, s19, 28
	s_add_i32 s43, s28, 28
	v_mad_i64_i32 v[24:25], s[26:27], v24, s8, v[14:15]
	v_mad_i64_i32 v[26:27], s[26:27], v13, s8, v[14:15]
	v_or_b32_e32 v13, s29, v3
	v_or_b32_e32 v28, s30, v12
	v_or_b32_e32 v34, s31, v3
	v_or_b32_e32 v32, s33, v12
	v_or_b32_e32 v38, s34, v3
	v_or_b32_e32 v36, s35, v12
	v_or_b32_e32 v42, s36, v3
	v_or_b32_e32 v40, s37, v12
	v_or_b32_e32 v46, s38, v3
	v_or_b32_e32 v44, s39, v12
	v_or_b32_e32 v50, s40, v3
	v_or_b32_e32 v48, s41, v12
	v_or_b32_e32 v54, s42, v3
	v_or_b32_e32 v52, s43, v12
	v_mad_i64_i32 v[28:29], s[26:27], v28, s8, v[14:15]
	v_mad_i64_i32 v[30:31], s[26:27], v13, s8, v[14:15]
	v_mad_i64_i32 v[32:33], s[26:27], v32, s8, v[14:15]
	v_mad_i64_i32 v[34:35], s[26:27], v34, s8, v[14:15]
	v_mad_i64_i32 v[36:37], s[26:27], v36, s8, v[14:15]
	v_mad_i64_i32 v[38:39], s[26:27], v38, s8, v[14:15]
	v_mad_i64_i32 v[40:41], s[26:27], v40, s8, v[14:15]
	v_mad_i64_i32 v[42:43], s[26:27], v42, s8, v[14:15]
	v_mad_i64_i32 v[44:45], s[26:27], v44, s8, v[14:15]
	v_mad_i64_i32 v[46:47], s[26:27], v46, s8, v[14:15]
	v_mad_i64_i32 v[48:49], s[26:27], v48, s8, v[14:15]
	v_mad_i64_i32 v[50:51], s[26:27], v50, s8, v[14:15]
	v_mad_i64_i32 v[52:53], s[26:27], v52, s8, v[14:15]
	v_mad_i64_i32 v[54:55], s[26:27], v54, s8, v[14:15]
	global_load_dword v13, v[24:25], off
	global_load_dword v56, v[26:27], off
	global_load_dword v57, v[28:29], off
	global_load_dword v58, v[30:31], off
	global_load_dword v59, v[32:33], off
	global_load_dword v60, v[34:35], off
	global_load_dword v61, v[36:37], off
	global_load_dword v62, v[38:39], off
	global_load_dword v63, v[40:41], off
	global_load_dword v64, v[42:43], off
	global_load_dword v65, v[44:45], off
	global_load_dword v66, v[46:47], off
	global_load_dword v67, v[48:49], off
	global_load_dword v68, v[50:51], off
	global_load_dword v69, v[52:53], off
	global_load_dword v70, v[54:55], off
	v_or_b32_e32 v26, s19, v1
	v_or_b32_e32 v24, s28, v2
	s_add_i32 s3, s3, 16
	s_add_i32 s2, s2, 16
	s_add_i32 s18, s18, -16
	v_mad_u64_u32 v[24:25], s[26:27], v24, s9, v[6:7]
	v_mad_u64_u32 v[26:27], s[26:27], v26, s9, v[6:7]
	v_or_b32_e32 v25, s29, v1
	v_or_b32_e32 v27, s30, v2
	v_or_b32_e32 v34, s31, v1
	v_or_b32_e32 v32, s33, v2
	v_or_b32_e32 v38, s34, v1
	v_or_b32_e32 v36, s35, v2
	v_or_b32_e32 v42, s36, v1
	v_or_b32_e32 v40, s37, v2
	v_or_b32_e32 v46, s38, v1
	v_or_b32_e32 v44, s39, v2
	v_or_b32_e32 v50, s40, v1
	v_or_b32_e32 v48, s41, v2
	v_or_b32_e32 v54, s42, v1
	v_or_b32_e32 v52, s43, v2
	s_cmp_lg_u32 s18, 0
	v_mad_u64_u32 v[28:29], s[26:27], v27, s9, v[6:7]
	v_mad_u64_u32 v[30:31], s[26:27], v25, s9, v[6:7]
	v_mad_u64_u32 v[32:33], s[26:27], v32, s9, v[6:7]
	v_mad_u64_u32 v[34:35], s[26:27], v34, s9, v[6:7]
	v_mad_u64_u32 v[36:37], s[26:27], v36, s9, v[6:7]
	v_mad_u64_u32 v[38:39], s[26:27], v38, s9, v[6:7]
	v_mad_u64_u32 v[40:41], s[26:27], v40, s9, v[6:7]
	v_mad_u64_u32 v[42:43], s[26:27], v42, s9, v[6:7]
	v_mad_u64_u32 v[44:45], s[26:27], v44, s9, v[6:7]
	v_mad_u64_u32 v[46:47], s[26:27], v46, s9, v[6:7]
	v_mad_u64_u32 v[48:49], s[26:27], v48, s9, v[6:7]
	v_mad_u64_u32 v[50:51], s[26:27], v50, s9, v[6:7]
	v_mad_u64_u32 v[52:53], s[26:27], v52, s9, v[6:7]
	v_mad_u64_u32 v[54:55], s[26:27], v54, s9, v[6:7]
	s_lshl_b32 s19, s2, 1
	s_lshl_b32 s28, s3, 1
	v_or_b32_e32 v193, s19, v3
	v_or_b32_e32 v194, s28, v12
	s_add_i32 s29, s19, 4
	s_add_i32 s30, s28, 4
	s_add_i32 s31, s19, 8
	s_add_i32 s33, s28, 8
	s_add_i32 s34, s19, 12
	s_add_i32 s35, s28, 12
	s_add_i32 s36, s19, 16
	s_add_i32 s37, s28, 16
	s_add_i32 s38, s19, 20
	s_add_i32 s39, s28, 20
	s_add_i32 s40, s19, 24
	s_add_i32 s41, s28, 24
	s_add_i32 s42, s19, 28
	s_add_i32 s43, s28, 28
	v_mad_i64_i32 v[194:195], s[26:27], v194, s8, v[14:15]
	v_mad_i64_i32 v[196:197], s[26:27], v193, s8, v[14:15]
	v_or_b32_e32 v193, s29, v3
	v_or_b32_e32 v198, s30, v12
	v_or_b32_e32 v204, s31, v3
	v_or_b32_e32 v202, s33, v12
	v_or_b32_e32 v208, s34, v3
	v_or_b32_e32 v206, s35, v12
	v_or_b32_e32 v212, s36, v3
	v_or_b32_e32 v210, s37, v12
	v_or_b32_e32 v216, s38, v3
	v_or_b32_e32 v214, s39, v12
	v_or_b32_e32 v220, s40, v3
	v_or_b32_e32 v218, s41, v12
	v_or_b32_e32 v224, s42, v3
	v_or_b32_e32 v222, s43, v12
	v_mad_i64_i32 v[198:199], s[26:27], v198, s8, v[14:15]
	v_mad_i64_i32 v[200:201], s[26:27], v193, s8, v[14:15]
	v_mad_i64_i32 v[202:203], s[26:27], v202, s8, v[14:15]
	v_mad_i64_i32 v[204:205], s[26:27], v204, s8, v[14:15]
	v_mad_i64_i32 v[206:207], s[26:27], v206, s8, v[14:15]
	v_mad_i64_i32 v[208:209], s[26:27], v208, s8, v[14:15]
	v_mad_i64_i32 v[210:211], s[26:27], v210, s8, v[14:15]
	v_mad_i64_i32 v[212:213], s[26:27], v212, s8, v[14:15]
	v_mad_i64_i32 v[214:215], s[26:27], v214, s8, v[14:15]
	v_mad_i64_i32 v[216:217], s[26:27], v216, s8, v[14:15]
	v_mad_i64_i32 v[218:219], s[26:27], v218, s8, v[14:15]
	v_mad_i64_i32 v[220:221], s[26:27], v220, s8, v[14:15]
	v_mad_i64_i32 v[222:223], s[26:27], v222, s8, v[14:15]
	v_mad_i64_i32 v[224:225], s[26:27], v224, s8, v[14:15]
	global_load_dword v193, v[194:195], off
	global_load_dword v226, v[196:197], off
	global_load_dword v227, v[198:199], off
	global_load_dword v228, v[200:201], off
	global_load_dword v229, v[202:203], off
	global_load_dword v230, v[204:205], off
	global_load_dword v231, v[206:207], off
	global_load_dword v232, v[208:209], off
	global_load_dword v233, v[210:211], off
	global_load_dword v234, v[212:213], off
	global_load_dword v235, v[214:215], off
	global_load_dword v236, v[216:217], off
	global_load_dword v237, v[218:219], off
	global_load_dword v238, v[220:221], off
	global_load_dword v239, v[222:223], off
	global_load_dword v240, v[224:225], off
	v_or_b32_e32 v196, s19, v1
	v_or_b32_e32 v194, s28, v2
	s_add_i32 s3, s3, 16
	s_add_i32 s2, s2, 16
	s_add_i32 s18, s18, -16
	v_mad_u64_u32 v[194:195], s[26:27], v194, s9, v[6:7]
	v_mad_u64_u32 v[196:197], s[26:27], v196, s9, v[6:7]
	v_or_b32_e32 v195, s29, v1
	v_or_b32_e32 v197, s30, v2
	v_or_b32_e32 v204, s31, v1
	v_or_b32_e32 v202, s33, v2
	v_or_b32_e32 v208, s34, v1
	v_or_b32_e32 v206, s35, v2
	v_or_b32_e32 v212, s36, v1
	v_or_b32_e32 v210, s37, v2
	v_or_b32_e32 v216, s38, v1
	v_or_b32_e32 v214, s39, v2
	v_or_b32_e32 v220, s40, v1
	v_or_b32_e32 v218, s41, v2
	v_or_b32_e32 v224, s42, v1
	v_or_b32_e32 v222, s43, v2
	s_cmp_lg_u32 s18, 0
	v_mad_u64_u32 v[198:199], s[26:27], v197, s9, v[6:7]
	v_mad_u64_u32 v[200:201], s[26:27], v195, s9, v[6:7]
	v_mad_u64_u32 v[202:203], s[26:27], v202, s9, v[6:7]
	v_mad_u64_u32 v[204:205], s[26:27], v204, s9, v[6:7]
	v_mad_u64_u32 v[206:207], s[26:27], v206, s9, v[6:7]
	v_mad_u64_u32 v[208:209], s[26:27], v208, s9, v[6:7]
	v_mad_u64_u32 v[210:211], s[26:27], v210, s9, v[6:7]
	v_mad_u64_u32 v[212:213], s[26:27], v212, s9, v[6:7]
	v_mad_u64_u32 v[214:215], s[26:27], v214, s9, v[6:7]
	v_mad_u64_u32 v[216:217], s[26:27], v216, s9, v[6:7]
	v_mad_u64_u32 v[218:219], s[26:27], v218, s9, v[6:7]
	v_mad_u64_u32 v[220:221], s[26:27], v220, s9, v[6:7]
	v_mad_u64_u32 v[222:223], s[26:27], v222, s9, v[6:7]
	v_mad_u64_u32 v[224:225], s[26:27], v224, s9, v[6:7]
	s_waitcnt vmcnt(31)
	ds_write_b32 v24, v13
	s_waitcnt vmcnt(30)
	ds_write_b32 v26, v56
	s_waitcnt vmcnt(29)
	ds_write_b32 v28, v57
	s_waitcnt vmcnt(28)
	ds_write_b32 v30, v58
	s_waitcnt vmcnt(27)
	ds_write_b32 v32, v59
	s_waitcnt vmcnt(26)
	ds_write_b32 v34, v60
	s_waitcnt vmcnt(25)
	ds_write_b32 v36, v61
	s_waitcnt vmcnt(24)
	ds_write_b32 v38, v62
	s_waitcnt vmcnt(23)
	ds_write_b32 v40, v63
	s_waitcnt vmcnt(22)
	ds_write_b32 v42, v64
	s_waitcnt vmcnt(21)
	ds_write_b32 v44, v65
	s_waitcnt vmcnt(20)
	ds_write_b32 v46, v66
	s_waitcnt vmcnt(19)
	ds_write_b32 v48, v67
	s_waitcnt vmcnt(18)
	ds_write_b32 v50, v68
	s_waitcnt vmcnt(17)
	ds_write_b32 v52, v69
	s_waitcnt vmcnt(16)
	ds_write_b32 v54, v70
	s_waitcnt vmcnt(15)
	ds_write_b32 v194, v193
	s_waitcnt vmcnt(14)
	ds_write_b32 v196, v226
	s_waitcnt vmcnt(13)
	ds_write_b32 v198, v227
	s_waitcnt vmcnt(12)
	ds_write_b32 v200, v228
	s_waitcnt vmcnt(11)
	ds_write_b32 v202, v229
	s_waitcnt vmcnt(10)
	ds_write_b32 v204, v230
	s_waitcnt vmcnt(9)
	ds_write_b32 v206, v231
	s_waitcnt vmcnt(8)
	ds_write_b32 v208, v232
	s_waitcnt vmcnt(7)
	ds_write_b32 v210, v233
	s_waitcnt vmcnt(6)
	ds_write_b32 v212, v234
	s_waitcnt vmcnt(5)
	ds_write_b32 v214, v235
	s_waitcnt vmcnt(4)
	ds_write_b32 v216, v236
	s_waitcnt vmcnt(3)
	ds_write_b32 v218, v237
	s_waitcnt vmcnt(2)
	ds_write_b32 v220, v238
	s_waitcnt vmcnt(1)
	ds_write_b32 v222, v239
	s_waitcnt vmcnt(0)
	ds_write_b32 v224, v240
	s_cbranch_scc1 .LBB0_282
	v_or_b32_e32 v12, s12, v19
	v_readlane_b32 s2, v251, 41
	v_ashrrev_i32_e32 v13, 31, v12
	v_readlane_b32 s3, v251, 42
	s_waitcnt lgkmcnt(0)
	s_nop 1
	v_lshl_add_u64 v[14:15], v[12:13], 2, s[2:3]
	global_load_dword v3, v[14:15], off
	ds_read2_b32 v[14:15], v18 offset1:33
	ds_read2_b32 v[24:25], v18 offset0:66 offset1:99
	ds_read2_b32 v[26:27], v18 offset0:132 offset1:165
	ds_read2_b32 v[28:29], v18 offset0:198 offset1:231
	ds_read2_b32 v[30:31], v21 offset0:8 offset1:41
	ds_read2_b32 v[32:33], v21 offset0:74 offset1:107
	ds_read2_b32 v[34:35], v21 offset0:140 offset1:173
	ds_read2_b32 v[36:37], v21 offset0:206 offset1:239
	ds_read2_b32 v[38:39], v22 offset0:16 offset1:49
	s_waitcnt vmcnt(0)
	v_max_f32_e32 v3, v3, v3
	v_max_f32_e32 v3, 0xda24260, v3
	v_div_scale_f32 v40, s[2:3], v3, v3, s14
	v_rcp_f32_e32 v41, v40
	v_div_scale_f32 v42, vcc, s14, v3, s14
	v_readlane_b32 s2, v252, 7
	v_fma_f32 v43, -v40, v41, 1.0
	v_fmac_f32_e32 v41, v43, v41
	v_mul_f32_e32 v43, v42, v41
	v_fma_f32 v44, -v40, v43, v42
	v_fmac_f32_e32 v43, v44, v41
	v_fma_f32 v40, -v40, v43, v42
	v_div_fmas_f32 v40, v40, v41, v43
	v_div_fixup_f32 v40, v40, v3, s14
	s_waitcnt lgkmcnt(8)
	v_mul_f32_e32 v15, v40, v15
	s_waitcnt lgkmcnt(6)
	v_mul_f32_e32 v27, v40, v27
	v_mul_f32_e32 v14, v14, v40
	v_mul_f32_e32 v24, v40, v24
	v_mul_f32_e32 v26, v40, v26
	s_waitcnt lgkmcnt(5)
	v_mul_f32_e32 v28, v40, v28
	v_med3_f32 v15, v15, s15, v20
	v_med3_f32 v27, v27, s15, v20
	v_mul_f32_e32 v25, v40, v25
	v_mul_f32_e32 v29, v40, v29
	v_med3_f32 v14, v14, s15, v20
	v_med3_f32 v24, v24, s15, v20
	v_med3_f32 v26, v26, s15, v20
	v_med3_f32 v28, v28, s15, v20
	v_rndne_f32_e32 v15, v15
	v_rndne_f32_e32 v27, v27
	v_med3_f32 v25, v25, s15, v20
	v_med3_f32 v29, v29, s15, v20
	v_rndne_f32_e32 v14, v14
	v_rndne_f32_e32 v24, v24
	v_rndne_f32_e32 v26, v26
	v_rndne_f32_e32 v28, v28
	v_cvt_i32_f32_e32 v15, v15
	v_cvt_i32_f32_e32 v27, v27
	v_rndne_f32_e32 v25, v25
	v_rndne_f32_e32 v29, v29
	v_cvt_i32_f32_e32 v14, v14
	v_cvt_i32_f32_sdwa v24, v24 dst_sel:WORD_1 dst_unused:UNUSED_PAD src0_sel:DWORD
	v_cvt_i32_f32_e32 v26, v26
	v_cvt_i32_f32_sdwa v28, v28 dst_sel:WORD_1 dst_unused:UNUSED_PAD src0_sel:DWORD
	v_cvt_i32_f32_sdwa v25, v25 dst_sel:BYTE_3 dst_unused:UNUSED_PAD src0_sel:DWORD
	v_cvt_i32_f32_sdwa v29, v29 dst_sel:BYTE_3 dst_unused:UNUSED_PAD src0_sel:DWORD
	v_lshlrev_b32_e32 v15, 8, v15
	v_lshlrev_b32_e32 v27, 8, v27
	s_waitcnt lgkmcnt(4)
	v_mul_f32_e32 v31, v40, v31
	v_and_b32_e32 v24, 0xff0000, v24
	v_and_b32_e32 v28, 0xff0000, v28
	v_perm_b32 v14, v15, v14, s16
	v_perm_b32 v15, v27, v26, s16
	v_mul_f32_e32 v30, v40, v30
	s_waitcnt lgkmcnt(3)
	v_mul_f32_e32 v32, v40, v32
	s_waitcnt lgkmcnt(2)
	v_mul_f32_e32 v35, v40, v35
	v_med3_f32 v31, v31, s15, v20
	v_or3_b32 v24, v14, v24, v25
	v_or3_b32 v25, v15, v28, v29
	ds_read2_b32 v[14:15], v22 offset0:82 offset1:115
	v_mul_f32_e32 v33, v40, v33
	v_mul_f32_e32 v34, v40, v34
	s_waitcnt lgkmcnt(2)
	v_mul_f32_e32 v36, v40, v36
	v_med3_f32 v30, v30, s15, v20
	v_med3_f32 v32, v32, s15, v20
	v_med3_f32 v35, v35, s15, v20
	v_rndne_f32_e32 v31, v31
	v_mul_f32_e32 v37, v40, v37
	v_med3_f32 v33, v33, s15, v20
	v_med3_f32 v34, v34, s15, v20
	v_med3_f32 v36, v36, s15, v20
	v_rndne_f32_e32 v30, v30
	v_rndne_f32_e32 v32, v32
	v_rndne_f32_e32 v35, v35
	v_cvt_i32_f32_e32 v31, v31
	v_med3_f32 v37, v37, s15, v20
	v_rndne_f32_e32 v33, v33
	v_rndne_f32_e32 v34, v34
	v_rndne_f32_e32 v36, v36
	v_cvt_i32_f32_e32 v30, v30
	v_cvt_i32_f32_sdwa v32, v32 dst_sel:WORD_1 dst_unused:UNUSED_PAD src0_sel:DWORD
	v_cvt_i32_f32_e32 v35, v35
	v_rndne_f32_e32 v37, v37
	v_cvt_i32_f32_sdwa v33, v33 dst_sel:BYTE_3 dst_unused:UNUSED_PAD src0_sel:DWORD
	v_cvt_i32_f32_e32 v34, v34
	v_cvt_i32_f32_sdwa v36, v36 dst_sel:WORD_1 dst_unused:UNUSED_PAD src0_sel:DWORD
	v_cvt_i32_f32_sdwa v37, v37 dst_sel:BYTE_3 dst_unused:UNUSED_PAD src0_sel:DWORD
	s_waitcnt lgkmcnt(0)
	v_mul_f32_e32 v14, v40, v14
	v_lshlrev_b32_e32 v31, 8, v31
	v_med3_f32 v14, v14, s15, v20
	v_and_b32_e32 v32, 0xff0000, v32
	v_lshlrev_b32_e32 v35, 8, v35
	v_perm_b32 v26, v31, v30, s16
	v_mul_f32_e32 v15, v40, v15
	v_rndne_f32_e32 v14, v14
	v_perm_b32 v27, v35, v34, s16
	v_or3_b32 v26, v26, v32, v33
	v_and_b32_e32 v28, 0xff0000, v36
	v_mul_f32_e32 v29, v40, v39
	v_cvt_i32_f32_sdwa v32, v14 dst_sel:WORD_1 dst_unused:UNUSED_PAD src0_sel:DWORD
	v_med3_f32 v14, v15, s15, v20
	v_or3_b32 v27, v27, v28, v37
	v_mul_f32_e32 v28, v40, v38
	v_med3_f32 v29, v29, s15, v20
	v_rndne_f32_e32 v14, v14
	v_rndne_f32_e32 v29, v29
	v_med3_f32 v28, v28, s15, v20
	v_cvt_i32_f32_sdwa v33, v14 dst_sel:BYTE_3 dst_unused:UNUSED_PAD src0_sel:DWORD
	ds_read2_b32 v[14:15], v22 offset0:148 offset1:181
	v_cvt_i32_f32_e32 v29, v29
	v_rndne_f32_e32 v28, v28
	v_cvt_i32_f32_e32 v28, v28
	ds_read2_b32 v[30:31], v22 offset0:214 offset1:247
	v_lshlrev_b32_e32 v29, 8, v29
	s_waitcnt lgkmcnt(1)
	v_mul_f32_e32 v14, v40, v14
	v_mul_f32_e32 v15, v40, v15
	v_perm_b32 v28, v29, v28, s16
	v_and_b32_e32 v29, 0xff0000, v32
	v_med3_f32 v15, v15, s15, v20
	v_med3_f32 v14, v14, s15, v20
	v_or3_b32 v28, v28, v29, v33
	s_waitcnt lgkmcnt(0)
	v_mul_f32_e32 v29, v40, v30
	v_rndne_f32_e32 v15, v15
	v_rndne_f32_e32 v14, v14
	v_mul_f32_e32 v30, v40, v31
	v_cvt_i32_f32_e32 v15, v15
	v_cvt_i32_f32_e32 v31, v14
	v_med3_f32 v14, v29, s15, v20
	v_rndne_f32_e32 v14, v14
	v_cvt_i32_f32_sdwa v29, v14 dst_sel:WORD_1 dst_unused:UNUSED_PAD src0_sel:DWORD
	v_med3_f32 v14, v30, s15, v20
	v_rndne_f32_e32 v14, v14
	v_lshlrev_b32_e32 v32, 8, v15
	v_cvt_i32_f32_sdwa v33, v14 dst_sel:BYTE_3 dst_unused:UNUSED_PAD src0_sel:DWORD
	ds_read2_b32 v[14:15], v23 offset0:24 offset1:57
	v_perm_b32 v32, v32, v31, s16
	ds_read2_b32 v[30:31], v23 offset0:90 offset1:123
	v_and_b32_e32 v29, 0xff0000, v29
	v_or3_b32 v29, v32, v29, v33
	s_waitcnt lgkmcnt(1)
	v_mul_f32_e32 v14, v40, v14
	v_mul_f32_e32 v15, v40, v15
	v_med3_f32 v15, v15, s15, v20
	v_med3_f32 v14, v14, s15, v20
	s_waitcnt lgkmcnt(0)
	v_mul_f32_e32 v30, v40, v30
	v_rndne_f32_e32 v15, v15
	v_rndne_f32_e32 v14, v14
	v_cvt_i32_f32_e32 v15, v15
	v_cvt_i32_f32_e32 v32, v14
	v_med3_f32 v14, v30, s15, v20
	v_mul_f32_e32 v31, v40, v31
	v_rndne_f32_e32 v14, v14
	v_cvt_i32_f32_sdwa v30, v14 dst_sel:WORD_1 dst_unused:UNUSED_PAD src0_sel:DWORD
	v_med3_f32 v14, v31, s15, v20
	v_rndne_f32_e32 v14, v14
	v_lshlrev_b32_e32 v33, 8, v15
	v_cvt_i32_f32_sdwa v31, v14 dst_sel:BYTE_3 dst_unused:UNUSED_PAD src0_sel:DWORD
	ds_read2_b32 v[14:15], v23 offset0:156 offset1:189
	v_perm_b32 v34, v33, v32, s16
	ds_read2_b32 v[32:33], v23 offset0:222 offset1:255
	v_and_b32_e32 v30, 0xff0000, v30
	v_or3_b32 v30, v34, v30, v31
	s_waitcnt lgkmcnt(1)
	v_mul_f32_e32 v15, v40, v15
	v_mul_f32_e32 v14, v40, v14
	s_waitcnt lgkmcnt(0)
	v_mul_f32_e32 v31, v40, v32
	v_med3_f32 v15, v15, s15, v20
	v_mul_f32_e32 v32, v40, v33
	v_med3_f32 v14, v14, s15, v20
	v_rndne_f32_e32 v15, v15
	v_med3_f32 v31, v31, s15, v20
	v_rndne_f32_e32 v14, v14
	v_cvt_i32_f32_e32 v15, v15
	v_rndne_f32_e32 v31, v31
	v_med3_f32 v32, v32, s15, v20
	v_cvt_i32_f32_e32 v14, v14
	v_cvt_i32_f32_sdwa v31, v31 dst_sel:WORD_1 dst_unused:UNUSED_PAD src0_sel:DWORD
	v_rndne_f32_e32 v32, v32
	v_cvt_i32_f32_sdwa v32, v32 dst_sel:BYTE_3 dst_unused:UNUSED_PAD src0_sel:DWORD
	v_lshlrev_b32_e32 v15, 8, v15
	v_perm_b32 v14, v15, v14, s16
	v_and_b32_e32 v15, 0xff0000, v31
	v_or3_b32 v31, v14, v15, v32
	v_lshlrev_b64 v[14:15], 11, v[12:13]
	v_readlane_b32 s3, v252, 8
	s_nop 1
	v_lshl_add_u64 v[14:15], s[2:3], 0, v[14:15]
	v_lshl_add_u64 v[14:15], v[14:15], 0, s[24:25]
	v_lshl_add_u64 v[14:15], v[14:15], 0, v[8:9]
	global_store_dwordx4 v[14:15], v[24:27], off
	global_store_dwordx4 v[14:15], v[28:31], off offset:16
	s_and_saveexec_b64 s[2:3], s[0:1]
	s_cbranch_execz .LBB0_276
	v_mul_f32_e32 v3, 0x3c010204, v3
	v_lshl_add_u64 v[12:13], v[12:13], 2, s[22:23]
	global_store_dword v[12:13], v3, off
	s_branch .LBB0_276

.LBB0_289:
	s_lshl_b32 s17, s16, 1
	s_lshl_b32 s25, s15, 1
	v_or_b32_e32 v19, s17, v3
	v_or_b32_e32 v20, s25, v12
	s_add_i32 s27, s17, 4
	s_add_i32 s28, s25, 4
	s_add_i32 s29, s17, 8
	s_add_i32 s30, s25, 8
	s_add_i32 s31, s17, 12
	s_add_i32 s33, s25, 12
	s_add_i32 s34, s17, 16
	s_add_i32 s35, s25, 16
	s_add_i32 s36, s17, 20
	s_add_i32 s37, s25, 20
	s_add_i32 s38, s17, 24
	s_add_i32 s39, s25, 24
	s_add_i32 s40, s17, 28
	s_add_i32 s41, s25, 28
	v_mad_i64_i32 v[20:21], s[18:19], v20, s7, v[10:11]
	v_mad_i64_i32 v[22:23], s[18:19], v19, s7, v[10:11]
	v_or_b32_e32 v19, s27, v3
	v_or_b32_e32 v24, s28, v12
	v_or_b32_e32 v30, s29, v3
	v_or_b32_e32 v28, s30, v12
	v_or_b32_e32 v34, s31, v3
	v_or_b32_e32 v32, s33, v12
	v_or_b32_e32 v38, s34, v3
	v_or_b32_e32 v36, s35, v12
	v_or_b32_e32 v42, s36, v3
	v_or_b32_e32 v40, s37, v12
	v_or_b32_e32 v46, s38, v3
	v_or_b32_e32 v44, s39, v12
	v_or_b32_e32 v50, s40, v3
	v_or_b32_e32 v48, s41, v12
	v_mad_i64_i32 v[24:25], s[18:19], v24, s7, v[10:11]
	v_mad_i64_i32 v[26:27], s[18:19], v19, s7, v[10:11]
	v_mad_i64_i32 v[28:29], s[18:19], v28, s7, v[10:11]
	v_mad_i64_i32 v[30:31], s[18:19], v30, s7, v[10:11]
	v_mad_i64_i32 v[32:33], s[18:19], v32, s7, v[10:11]
	v_mad_i64_i32 v[34:35], s[18:19], v34, s7, v[10:11]
	v_mad_i64_i32 v[36:37], s[18:19], v36, s7, v[10:11]
	v_mad_i64_i32 v[38:39], s[18:19], v38, s7, v[10:11]
	v_mad_i64_i32 v[40:41], s[18:19], v40, s7, v[10:11]
	v_mad_i64_i32 v[42:43], s[18:19], v42, s7, v[10:11]
	v_mad_i64_i32 v[44:45], s[18:19], v44, s7, v[10:11]
	v_mad_i64_i32 v[46:47], s[18:19], v46, s7, v[10:11]
	v_mad_i64_i32 v[48:49], s[18:19], v48, s7, v[10:11]
	v_mad_i64_i32 v[50:51], s[18:19], v50, s7, v[10:11]
	global_load_dword v19, v[20:21], off
	global_load_dword v52, v[22:23], off
	global_load_dword v53, v[24:25], off
	global_load_dword v54, v[26:27], off
	global_load_dword v55, v[28:29], off
	global_load_dword v56, v[30:31], off
	global_load_dword v57, v[32:33], off
	global_load_dword v58, v[34:35], off
	global_load_dword v59, v[36:37], off
	global_load_dword v60, v[38:39], off
	global_load_dword v61, v[40:41], off
	global_load_dword v62, v[42:43], off
	global_load_dword v63, v[44:45], off
	global_load_dword v64, v[46:47], off
	global_load_dword v65, v[48:49], off
	global_load_dword v66, v[50:51], off
	v_or_b32_e32 v22, s17, v1
	v_or_b32_e32 v20, s25, v2
	s_add_i32 s15, s15, 16
	s_add_i32 s16, s16, 16
	s_add_i32 s3, s3, -16
	v_mad_u64_u32 v[20:21], s[18:19], v20, s8, v[8:9]
	v_mad_u64_u32 v[22:23], s[18:19], v22, s8, v[8:9]
	v_or_b32_e32 v21, s27, v1
	v_or_b32_e32 v23, s28, v2
	v_or_b32_e32 v30, s29, v1
	v_or_b32_e32 v28, s30, v2
	v_or_b32_e32 v34, s31, v1
	v_or_b32_e32 v32, s33, v2
	v_or_b32_e32 v38, s34, v1
	v_or_b32_e32 v36, s35, v2
	v_or_b32_e32 v42, s36, v1
	v_or_b32_e32 v40, s37, v2
	v_or_b32_e32 v46, s38, v1
	v_or_b32_e32 v44, s39, v2
	v_or_b32_e32 v50, s40, v1
	v_or_b32_e32 v48, s41, v2
	s_cmp_lg_u32 s3, 0
	v_mad_u64_u32 v[24:25], s[18:19], v23, s8, v[8:9]
	v_mad_u64_u32 v[26:27], s[18:19], v21, s8, v[8:9]
	v_mad_u64_u32 v[28:29], s[18:19], v28, s8, v[8:9]
	v_mad_u64_u32 v[30:31], s[18:19], v30, s8, v[8:9]
	v_mad_u64_u32 v[32:33], s[18:19], v32, s8, v[8:9]
	v_mad_u64_u32 v[34:35], s[18:19], v34, s8, v[8:9]
	v_mad_u64_u32 v[36:37], s[18:19], v36, s8, v[8:9]
	v_mad_u64_u32 v[38:39], s[18:19], v38, s8, v[8:9]
	v_mad_u64_u32 v[40:41], s[18:19], v40, s8, v[8:9]
	v_mad_u64_u32 v[42:43], s[18:19], v42, s8, v[8:9]
	v_mad_u64_u32 v[44:45], s[18:19], v44, s8, v[8:9]
	v_mad_u64_u32 v[46:47], s[18:19], v46, s8, v[8:9]
	v_mad_u64_u32 v[48:49], s[18:19], v48, s8, v[8:9]
	v_mad_u64_u32 v[50:51], s[18:19], v50, s8, v[8:9]
	s_lshl_b32 s17, s16, 1
	s_lshl_b32 s25, s15, 1
	v_or_b32_e32 v193, s17, v3
	v_or_b32_e32 v194, s25, v12
	s_add_i32 s27, s17, 4
	s_add_i32 s28, s25, 4
	s_add_i32 s29, s17, 8
	s_add_i32 s30, s25, 8
	s_add_i32 s31, s17, 12
	s_add_i32 s33, s25, 12
	s_add_i32 s34, s17, 16
	s_add_i32 s35, s25, 16
	s_add_i32 s36, s17, 20
	s_add_i32 s37, s25, 20
	s_add_i32 s38, s17, 24
	s_add_i32 s39, s25, 24
	s_add_i32 s40, s17, 28
	s_add_i32 s41, s25, 28
	v_mad_i64_i32 v[194:195], s[18:19], v194, s7, v[10:11]
	v_mad_i64_i32 v[196:197], s[18:19], v193, s7, v[10:11]
	v_or_b32_e32 v193, s27, v3
	v_or_b32_e32 v198, s28, v12
	v_or_b32_e32 v204, s29, v3
	v_or_b32_e32 v202, s30, v12
	v_or_b32_e32 v208, s31, v3
	v_or_b32_e32 v206, s33, v12
	v_or_b32_e32 v212, s34, v3
	v_or_b32_e32 v210, s35, v12
	v_or_b32_e32 v216, s36, v3
	v_or_b32_e32 v214, s37, v12
	v_or_b32_e32 v220, s38, v3
	v_or_b32_e32 v218, s39, v12
	v_or_b32_e32 v224, s40, v3
	v_or_b32_e32 v222, s41, v12
	v_mad_i64_i32 v[198:199], s[18:19], v198, s7, v[10:11]
	v_mad_i64_i32 v[200:201], s[18:19], v193, s7, v[10:11]
	v_mad_i64_i32 v[202:203], s[18:19], v202, s7, v[10:11]
	v_mad_i64_i32 v[204:205], s[18:19], v204, s7, v[10:11]
	v_mad_i64_i32 v[206:207], s[18:19], v206, s7, v[10:11]
	v_mad_i64_i32 v[208:209], s[18:19], v208, s7, v[10:11]
	v_mad_i64_i32 v[210:211], s[18:19], v210, s7, v[10:11]
	v_mad_i64_i32 v[212:213], s[18:19], v212, s7, v[10:11]
	v_mad_i64_i32 v[214:215], s[18:19], v214, s7, v[10:11]
	v_mad_i64_i32 v[216:217], s[18:19], v216, s7, v[10:11]
	v_mad_i64_i32 v[218:219], s[18:19], v218, s7, v[10:11]
	v_mad_i64_i32 v[220:221], s[18:19], v220, s7, v[10:11]
	v_mad_i64_i32 v[222:223], s[18:19], v222, s7, v[10:11]
	v_mad_i64_i32 v[224:225], s[18:19], v224, s7, v[10:11]
	global_load_dword v193, v[194:195], off
	global_load_dword v226, v[196:197], off
	global_load_dword v227, v[198:199], off
	global_load_dword v228, v[200:201], off
	global_load_dword v229, v[202:203], off
	global_load_dword v230, v[204:205], off
	global_load_dword v231, v[206:207], off
	global_load_dword v232, v[208:209], off
	global_load_dword v233, v[210:211], off
	global_load_dword v234, v[212:213], off
	global_load_dword v235, v[214:215], off
	global_load_dword v236, v[216:217], off
	global_load_dword v237, v[218:219], off
	global_load_dword v238, v[220:221], off
	global_load_dword v239, v[222:223], off
	global_load_dword v240, v[224:225], off
	v_or_b32_e32 v196, s17, v1
	v_or_b32_e32 v194, s25, v2
	s_add_i32 s15, s15, 16
	s_add_i32 s16, s16, 16
	s_add_i32 s3, s3, -16
	v_mad_u64_u32 v[194:195], s[18:19], v194, s8, v[8:9]
	v_mad_u64_u32 v[196:197], s[18:19], v196, s8, v[8:9]
	v_or_b32_e32 v195, s27, v1
	v_or_b32_e32 v197, s28, v2
	v_or_b32_e32 v204, s29, v1
	v_or_b32_e32 v202, s30, v2
	v_or_b32_e32 v208, s31, v1
	v_or_b32_e32 v206, s33, v2
	v_or_b32_e32 v212, s34, v1
	v_or_b32_e32 v210, s35, v2
	v_or_b32_e32 v216, s36, v1
	v_or_b32_e32 v214, s37, v2
	v_or_b32_e32 v220, s38, v1
	v_or_b32_e32 v218, s39, v2
	v_or_b32_e32 v224, s40, v1
	v_or_b32_e32 v222, s41, v2
	s_cmp_lg_u32 s3, 0
	v_mad_u64_u32 v[198:199], s[18:19], v197, s8, v[8:9]
	v_mad_u64_u32 v[200:201], s[18:19], v195, s8, v[8:9]
	v_mad_u64_u32 v[202:203], s[18:19], v202, s8, v[8:9]
	v_mad_u64_u32 v[204:205], s[18:19], v204, s8, v[8:9]
	v_mad_u64_u32 v[206:207], s[18:19], v206, s8, v[8:9]
	v_mad_u64_u32 v[208:209], s[18:19], v208, s8, v[8:9]
	v_mad_u64_u32 v[210:211], s[18:19], v210, s8, v[8:9]
	v_mad_u64_u32 v[212:213], s[18:19], v212, s8, v[8:9]
	v_mad_u64_u32 v[214:215], s[18:19], v214, s8, v[8:9]
	v_mad_u64_u32 v[216:217], s[18:19], v216, s8, v[8:9]
	v_mad_u64_u32 v[218:219], s[18:19], v218, s8, v[8:9]
	v_mad_u64_u32 v[220:221], s[18:19], v220, s8, v[8:9]
	v_mad_u64_u32 v[222:223], s[18:19], v222, s8, v[8:9]
	v_mad_u64_u32 v[224:225], s[18:19], v224, s8, v[8:9]
	s_waitcnt vmcnt(31)
	ds_write_b32 v20, v19
	s_waitcnt vmcnt(30)
	ds_write_b32 v22, v52
	s_waitcnt vmcnt(29)
	ds_write_b32 v24, v53
	s_waitcnt vmcnt(28)
	ds_write_b32 v26, v54
	s_waitcnt vmcnt(27)
	ds_write_b32 v28, v55
	s_waitcnt vmcnt(26)
	ds_write_b32 v30, v56
	s_waitcnt vmcnt(25)
	ds_write_b32 v32, v57
	s_waitcnt vmcnt(24)
	ds_write_b32 v34, v58
	s_waitcnt vmcnt(23)
	ds_write_b32 v36, v59
	s_waitcnt vmcnt(22)
	ds_write_b32 v38, v60
	s_waitcnt vmcnt(21)
	ds_write_b32 v40, v61
	s_waitcnt vmcnt(20)
	ds_write_b32 v42, v62
	s_waitcnt vmcnt(19)
	ds_write_b32 v44, v63
	s_waitcnt vmcnt(18)
	ds_write_b32 v46, v64
	s_waitcnt vmcnt(17)
	ds_write_b32 v48, v65
	s_waitcnt vmcnt(16)
	ds_write_b32 v50, v66
	s_waitcnt vmcnt(15)
	ds_write_b32 v194, v193
	s_waitcnt vmcnt(14)
	ds_write_b32 v196, v226
	s_waitcnt vmcnt(13)
	ds_write_b32 v198, v227
	s_waitcnt vmcnt(12)
	ds_write_b32 v200, v228
	s_waitcnt vmcnt(11)
	ds_write_b32 v202, v229
	s_waitcnt vmcnt(10)
	ds_write_b32 v204, v230
	s_waitcnt vmcnt(9)
	ds_write_b32 v206, v231
	s_waitcnt vmcnt(8)
	ds_write_b32 v208, v232
	s_waitcnt vmcnt(7)
	ds_write_b32 v210, v233
	s_waitcnt vmcnt(6)
	ds_write_b32 v212, v234
	s_waitcnt vmcnt(5)
	ds_write_b32 v214, v235
	s_waitcnt vmcnt(4)
	ds_write_b32 v216, v236
	s_waitcnt vmcnt(3)
	ds_write_b32 v218, v237
	s_waitcnt vmcnt(2)
	ds_write_b32 v220, v238
	s_waitcnt vmcnt(1)
	ds_write_b32 v222, v239
	s_waitcnt vmcnt(0)
	ds_write_b32 v224, v240
	s_cbranch_scc1 .LBB0_289
	v_or_b32_e32 v10, s26, v16
	v_ashrrev_i32_e32 v11, 31, v10
	s_waitcnt lgkmcnt(0)
	v_lshl_add_u64 v[20:21], v[10:11], 2, s[20:21]
	global_load_dword v3, v[20:21], off
	ds_read2_b32 v[20:21], v9 offset1:33
	ds_read2_b32 v[22:23], v9 offset0:66 offset1:99
	ds_read2_b32 v[24:25], v9 offset0:132 offset1:165
	ds_read2_b32 v[26:27], v9 offset0:198 offset1:231
	ds_read2_b32 v[28:29], v14 offset0:8 offset1:41
	ds_read2_b32 v[30:31], v14 offset0:74 offset1:107
	ds_read2_b32 v[32:33], v14 offset0:140 offset1:173
	ds_read2_b32 v[34:35], v14 offset0:206 offset1:239
	ds_read2_b32 v[36:37], v15 offset0:16 offset1:49
	s_ashr_i32 s25, s24, 31
	s_waitcnt vmcnt(0)
	v_max_f32_e32 v3, v3, v3
	v_max_f32_e32 v3, 0xda24260, v3
	v_div_scale_f32 v12, s[16:17], v3, v3, s9
	v_rcp_f32_e32 v19, v12
	v_div_scale_f32 v38, vcc, s9, v3, s9
	v_fma_f32 v39, -v12, v19, 1.0
	v_fmac_f32_e32 v19, v39, v19
	v_mul_f32_e32 v39, v38, v19
	v_fma_f32 v40, -v12, v39, v38
	v_fmac_f32_e32 v39, v40, v19
	v_fma_f32 v12, -v12, v39, v38
	v_div_fmas_f32 v12, v12, v19, v39
	v_div_fixup_f32 v12, v12, v3, s9
	s_waitcnt lgkmcnt(8)
	v_mul_f32_e32 v19, v20, v12
	v_mul_f32_e32 v20, v12, v21
	s_waitcnt lgkmcnt(7)
	v_mul_f32_e32 v21, v12, v22
	v_mul_f32_e32 v22, v12, v23
	s_waitcnt lgkmcnt(6)
	v_mul_f32_e32 v23, v12, v24
	v_mul_f32_e32 v24, v12, v25
	s_waitcnt lgkmcnt(5)
	v_mul_f32_e32 v25, v12, v26
	v_mul_f32_e32 v26, v12, v27
	s_waitcnt lgkmcnt(4)
	v_mul_f32_e32 v27, v12, v28
	v_mul_f32_e32 v28, v12, v29
	s_waitcnt lgkmcnt(3)
	v_mul_f32_e32 v29, v12, v30
	v_mul_f32_e32 v30, v12, v31
	s_waitcnt lgkmcnt(2)
	v_mul_f32_e32 v31, v12, v32
	v_mul_f32_e32 v32, v12, v33
	v_med3_f32 v20, v20, s12, v13
	v_med3_f32 v24, v24, s12, v13
	v_med3_f32 v28, v28, s12, v13
	s_waitcnt lgkmcnt(1)
	v_mul_f32_e32 v33, v12, v34
	v_med3_f32 v19, v19, s12, v13
	v_med3_f32 v21, v21, s12, v13
	v_med3_f32 v23, v23, s12, v13
	v_med3_f32 v25, v25, s12, v13
	v_med3_f32 v27, v27, s12, v13
	v_med3_f32 v29, v29, s12, v13
	v_med3_f32 v32, v32, s12, v13
	v_rndne_f32_e32 v20, v20
	v_rndne_f32_e32 v24, v24
	v_rndne_f32_e32 v28, v28
	v_mul_f32_e32 v34, v12, v35
	v_med3_f32 v22, v22, s12, v13
	v_med3_f32 v26, v26, s12, v13
	v_med3_f32 v30, v30, s12, v13
	v_med3_f32 v31, v31, s12, v13
	v_med3_f32 v33, v33, s12, v13
	v_rndne_f32_e32 v19, v19
	v_rndne_f32_e32 v21, v21
	v_rndne_f32_e32 v23, v23
	v_rndne_f32_e32 v25, v25
	v_rndne_f32_e32 v27, v27
	v_rndne_f32_e32 v29, v29
	v_rndne_f32_e32 v32, v32
	v_cvt_i32_f32_e32 v20, v20
	v_cvt_i32_f32_e32 v24, v24
	v_cvt_i32_f32_e32 v28, v28
	v_med3_f32 v34, v34, s12, v13
	v_rndne_f32_e32 v22, v22
	v_rndne_f32_e32 v26, v26
	v_rndne_f32_e32 v30, v30
	v_rndne_f32_e32 v31, v31
	v_rndne_f32_e32 v33, v33
	v_cvt_i32_f32_e32 v19, v19
	v_cvt_i32_f32_sdwa v21, v21 dst_sel:WORD_1 dst_unused:UNUSED_PAD src0_sel:DWORD
	v_cvt_i32_f32_e32 v23, v23
	v_cvt_i32_f32_sdwa v25, v25 dst_sel:WORD_1 dst_unused:UNUSED_PAD src0_sel:DWORD
	v_cvt_i32_f32_e32 v27, v27
	v_cvt_i32_f32_sdwa v29, v29 dst_sel:WORD_1 dst_unused:UNUSED_PAD src0_sel:DWORD
	v_cvt_i32_f32_e32 v32, v32
	v_rndne_f32_e32 v34, v34
	v_cvt_i32_f32_sdwa v22, v22 dst_sel:BYTE_3 dst_unused:UNUSED_PAD src0_sel:DWORD
	v_cvt_i32_f32_sdwa v26, v26 dst_sel:BYTE_3 dst_unused:UNUSED_PAD src0_sel:DWORD
	v_cvt_i32_f32_sdwa v30, v30 dst_sel:BYTE_3 dst_unused:UNUSED_PAD src0_sel:DWORD
	v_cvt_i32_f32_e32 v31, v31
	v_cvt_i32_f32_sdwa v33, v33 dst_sel:WORD_1 dst_unused:UNUSED_PAD src0_sel:DWORD
	v_cvt_i32_f32_sdwa v34, v34 dst_sel:BYTE_3 dst_unused:UNUSED_PAD src0_sel:DWORD
	v_lshlrev_b32_e32 v20, 8, v20
	v_lshlrev_b32_e32 v24, 8, v24
	v_lshlrev_b32_e32 v28, 8, v28
	v_and_b32_e32 v21, 0xff0000, v21
	v_and_b32_e32 v25, 0xff0000, v25
	v_and_b32_e32 v29, 0xff0000, v29
	v_lshlrev_b32_e32 v32, 8, v32
	v_perm_b32 v19, v20, v19, s14
	v_perm_b32 v23, v24, v23, s14
	v_perm_b32 v24, v28, v27, s14
	v_perm_b32 v27, v32, v31, s14
	v_or3_b32 v20, v19, v21, v22
	v_or3_b32 v21, v23, v25, v26
	v_or3_b32 v22, v24, v29, v30
	ds_read2_b32 v[24:25], v15 offset0:82 offset1:115
	v_and_b32_e32 v19, 0xff0000, v33
	s_waitcnt lgkmcnt(1)
	v_mul_f32_e32 v26, v12, v37
	v_or3_b32 v23, v27, v19, v34
	v_mul_f32_e32 v19, v12, v36
	v_med3_f32 v26, v26, s12, v13
	v_rndne_f32_e32 v26, v26
	v_med3_f32 v19, v19, s12, v13
	v_cvt_i32_f32_e32 v26, v26
	v_rndne_f32_e32 v19, v19
	v_cvt_i32_f32_e32 v19, v19
	s_waitcnt lgkmcnt(0)
	v_mul_f32_e32 v24, v12, v24
	v_mul_f32_e32 v25, v12, v25
	v_med3_f32 v24, v24, s12, v13
	v_lshlrev_b32_e32 v28, 8, v26
	v_rndne_f32_e32 v24, v24
	v_med3_f32 v25, v25, s12, v13
	v_cvt_i32_f32_sdwa v24, v24 dst_sel:WORD_1 dst_unused:UNUSED_PAD src0_sel:DWORD
	v_rndne_f32_e32 v25, v25
	ds_read2_b32 v[26:27], v15 offset0:148 offset1:181
	v_perm_b32 v19, v28, v19, s14
	ds_read2_b32 v[28:29], v15 offset0:214 offset1:247
	v_cvt_i32_f32_sdwa v25, v25 dst_sel:BYTE_3 dst_unused:UNUSED_PAD src0_sel:DWORD
	v_and_b32_e32 v24, 0xff0000, v24
	v_or3_b32 v24, v19, v24, v25
	s_waitcnt lgkmcnt(1)
	v_mul_f32_e32 v19, v12, v26
	s_waitcnt lgkmcnt(0)
	v_mul_f32_e32 v26, v12, v28
	v_mul_f32_e32 v25, v12, v27
	v_med3_f32 v26, v26, s12, v13
	v_mul_f32_e32 v27, v12, v29
	v_med3_f32 v25, v25, s12, v13
	v_rndne_f32_e32 v26, v26
	v_rndne_f32_e32 v25, v25
	v_med3_f32 v19, v19, s12, v13
	v_cvt_i32_f32_sdwa v30, v26 dst_sel:WORD_1 dst_unused:UNUSED_PAD src0_sel:DWORD
	v_med3_f32 v26, v27, s12, v13
	v_cvt_i32_f32_e32 v25, v25
	v_rndne_f32_e32 v19, v19
	v_rndne_f32_e32 v26, v26
	v_cvt_i32_f32_e32 v19, v19
	v_cvt_i32_f32_sdwa v31, v26 dst_sel:BYTE_3 dst_unused:UNUSED_PAD src0_sel:DWORD
	ds_read2_b32 v[26:27], v18 offset0:24 offset1:57
	ds_read2_b32 v[28:29], v18 offset0:90 offset1:123
	v_lshlrev_b32_e32 v25, 8, v25
	v_perm_b32 v19, v25, v19, s14
	v_and_b32_e32 v25, 0xff0000, v30
	v_or3_b32 v25, v19, v25, v31
	s_waitcnt lgkmcnt(1)
	v_mul_f32_e32 v19, v12, v26
	v_mul_f32_e32 v26, v12, v27
	s_waitcnt lgkmcnt(0)
	v_mul_f32_e32 v27, v12, v28
	v_mul_f32_e32 v28, v12, v29
	v_med3_f32 v26, v26, s12, v13
	v_med3_f32 v28, v28, s12, v13
	v_rndne_f32_e32 v26, v26
	v_med3_f32 v19, v19, s12, v13
	v_med3_f32 v27, v27, s12, v13
	v_rndne_f32_e32 v28, v28
	v_cvt_i32_f32_e32 v26, v26
	v_rndne_f32_e32 v19, v19
	v_rndne_f32_e32 v27, v27
	v_cvt_i32_f32_sdwa v32, v28 dst_sel:BYTE_3 dst_unused:UNUSED_PAD src0_sel:DWORD
	ds_read2_b32 v[28:29], v18 offset0:156 offset1:189
	v_cvt_i32_f32_e32 v19, v19
	v_cvt_i32_f32_sdwa v27, v27 dst_sel:WORD_1 dst_unused:UNUSED_PAD src0_sel:DWORD
	ds_read2_b32 v[30:31], v18 offset0:222 offset1:255
	v_lshlrev_b32_e32 v26, 8, v26
	v_perm_b32 v19, v26, v19, s14
	v_and_b32_e32 v26, 0xff0000, v27
	s_waitcnt lgkmcnt(1)
	v_mul_f32_e32 v27, v12, v29
	v_or3_b32 v26, v19, v26, v32
	v_mul_f32_e32 v19, v12, v28
	s_waitcnt lgkmcnt(0)
	v_mul_f32_e32 v28, v12, v30
	v_med3_f32 v27, v27, s12, v13
	v_med3_f32 v19, v19, s12, v13
	v_rndne_f32_e32 v27, v27
	v_med3_f32 v28, v28, s12, v13
	v_mul_f32_e32 v12, v12, v31
	v_rndne_f32_e32 v19, v19
	v_cvt_i32_f32_e32 v27, v27
	v_rndne_f32_e32 v28, v28
	v_cvt_i32_f32_e32 v19, v19
	v_cvt_i32_f32_sdwa v28, v28 dst_sel:WORD_1 dst_unused:UNUSED_PAD src0_sel:DWORD
	v_med3_f32 v12, v12, s12, v13
	v_rndne_f32_e32 v12, v12
	v_cvt_i32_f32_sdwa v12, v12 dst_sel:BYTE_3 dst_unused:UNUSED_PAD src0_sel:DWORD
	v_lshlrev_b32_e32 v27, 8, v27
	v_perm_b32 v19, v27, v19, s14
	v_and_b32_e32 v27, 0xff0000, v28
	v_lshlrev_b64 v[28:29], 11, v[10:11]
	v_lshl_add_u64 v[28:29], s[0:1], 0, v[28:29]
	v_or3_b32 v27, v19, v27, v12
	v_lshl_add_u64 v[28:29], v[28:29], 0, s[24:25]
	v_or_b32_e32 v12, s2, v17
	v_lshl_add_u64 v[28:29], v[28:29], 0, v[4:5]
	v_cmp_eq_u32_e32 vcc, 0, v12
	global_store_dwordx4 v[28:29], v[20:23], off
	global_store_dwordx4 v[28:29], v[24:27], off offset:16
	s_and_saveexec_b64 s[2:3], vcc
	s_cbranch_execz .LBB0_287
	v_mul_f32_e32 v3, 0x3c010204, v3
	v_lshl_add_u64 v[10:11], v[10:11], 2, s[10:11]
	global_store_dword v[10:11], v3, off
	s_branch .LBB0_287

.LBB0_1378:
	s_mul_hi_i32 s0, s9, 0x2e8ba2e9
	s_lshr_b32 s1, s0, 31
	s_ashr_i32 s0, s0, 5
	s_add_i32 s0, s0, s1
	s_mul_i32 s1, s0, 0xb0
	s_sub_i32 s1, s9, s1
	s_lshl_b32 s2, s1, 5
	s_lshl_b32 s4, s0, 6
	s_ashr_i32 s3, s2, 31
	v_lshl_add_u64 v[0:1], s[2:3], 2, v[14:15]
	v_or_b32_e32 v11, s4, v9
	v_or_b32_e32 v18, s4, v8
	s_mov_b32 s5, 1
	s_mov_b32 s6, 0
	s_mov_b32 s7, 32
	v_mad_i64_i32 v[232:233], s[12:13], v18, s82, v[0:1]
	v_mad_u64_u32 v[234:235], s[12:13], v8, s18, v[10:11]
	s_nop 4
	s_lshl_b32 s12, s82, 1
	s_ashr_i32 s13, s12, 31
	global_load_dword v200, v[232:233], off
	v_lshl_add_u64 v[232:233], v[232:233], 0, s[12:13]
	global_load_dword v201, v[232:233], off
	v_lshl_add_u64 v[232:233], v[232:233], 0, s[12:13]
	global_load_dword v202, v[232:233], off
	v_lshl_add_u64 v[232:233], v[232:233], 0, s[12:13]
	global_load_dword v203, v[232:233], off
	v_lshl_add_u64 v[232:233], v[232:233], 0, s[12:13]
	global_load_dword v204, v[232:233], off
	v_lshl_add_u64 v[232:233], v[232:233], 0, s[12:13]
	global_load_dword v205, v[232:233], off
	v_lshl_add_u64 v[232:233], v[232:233], 0, s[12:13]
	global_load_dword v206, v[232:233], off
	v_lshl_add_u64 v[232:233], v[232:233], 0, s[12:13]
	global_load_dword v207, v[232:233], off
	v_lshl_add_u64 v[232:233], v[232:233], 0, s[12:13]
	global_load_dword v208, v[232:233], off
	v_lshl_add_u64 v[232:233], v[232:233], 0, s[12:13]
	global_load_dword v209, v[232:233], off
	v_lshl_add_u64 v[232:233], v[232:233], 0, s[12:13]
	global_load_dword v210, v[232:233], off
	v_lshl_add_u64 v[232:233], v[232:233], 0, s[12:13]
	global_load_dword v211, v[232:233], off
	v_lshl_add_u64 v[232:233], v[232:233], 0, s[12:13]
	global_load_dword v212, v[232:233], off
	v_lshl_add_u64 v[232:233], v[232:233], 0, s[12:13]
	global_load_dword v213, v[232:233], off
	v_lshl_add_u64 v[232:233], v[232:233], 0, s[12:13]
	global_load_dword v214, v[232:233], off
	v_lshl_add_u64 v[232:233], v[232:233], 0, s[12:13]
	global_load_dword v215, v[232:233], off
	v_lshl_add_u64 v[232:233], v[232:233], 0, s[12:13]
	global_load_dword v216, v[232:233], off
	v_lshl_add_u64 v[232:233], v[232:233], 0, s[12:13]
	global_load_dword v217, v[232:233], off
	v_lshl_add_u64 v[232:233], v[232:233], 0, s[12:13]
	global_load_dword v218, v[232:233], off
	v_lshl_add_u64 v[232:233], v[232:233], 0, s[12:13]
	global_load_dword v219, v[232:233], off
	v_lshl_add_u64 v[232:233], v[232:233], 0, s[12:13]
	global_load_dword v220, v[232:233], off
	v_lshl_add_u64 v[232:233], v[232:233], 0, s[12:13]
	global_load_dword v221, v[232:233], off
	v_lshl_add_u64 v[232:233], v[232:233], 0, s[12:13]
	global_load_dword v222, v[232:233], off
	v_lshl_add_u64 v[232:233], v[232:233], 0, s[12:13]
	global_load_dword v223, v[232:233], off
	v_lshl_add_u64 v[232:233], v[232:233], 0, s[12:13]
	global_load_dword v224, v[232:233], off
	v_lshl_add_u64 v[232:233], v[232:233], 0, s[12:13]
	global_load_dword v225, v[232:233], off
	v_lshl_add_u64 v[232:233], v[232:233], 0, s[12:13]
	global_load_dword v226, v[232:233], off
	v_lshl_add_u64 v[232:233], v[232:233], 0, s[12:13]
	global_load_dword v227, v[232:233], off
	v_lshl_add_u64 v[232:233], v[232:233], 0, s[12:13]
	global_load_dword v228, v[232:233], off
	v_lshl_add_u64 v[232:233], v[232:233], 0, s[12:13]
	global_load_dword v229, v[232:233], off
	v_lshl_add_u64 v[232:233], v[232:233], 0, s[12:13]
	global_load_dword v230, v[232:233], off
	v_lshl_add_u64 v[232:233], v[232:233], 0, s[12:13]
	global_load_dword v231, v[232:233], off
	s_waitcnt vmcnt(31)
	ds_write_b32 v234, v200
	s_waitcnt vmcnt(30)
	ds_write_b32 v234, v201 offset:264
	s_waitcnt vmcnt(29)
	ds_write_b32 v234, v202 offset:528
	s_waitcnt vmcnt(28)
	ds_write_b32 v234, v203 offset:792
	s_waitcnt vmcnt(27)
	ds_write_b32 v234, v204 offset:1056
	s_waitcnt vmcnt(26)
	ds_write_b32 v234, v205 offset:1320
	s_waitcnt vmcnt(25)
	ds_write_b32 v234, v206 offset:1584
	s_waitcnt vmcnt(24)
	ds_write_b32 v234, v207 offset:1848
	s_waitcnt vmcnt(23)
	ds_write_b32 v234, v208 offset:2112
	s_waitcnt vmcnt(22)
	ds_write_b32 v234, v209 offset:2376
	s_waitcnt vmcnt(21)
	ds_write_b32 v234, v210 offset:2640
	s_waitcnt vmcnt(20)
	ds_write_b32 v234, v211 offset:2904
	s_waitcnt vmcnt(19)
	ds_write_b32 v234, v212 offset:3168
	s_waitcnt vmcnt(18)
	ds_write_b32 v234, v213 offset:3432
	s_waitcnt vmcnt(17)
	ds_write_b32 v234, v214 offset:3696
	s_waitcnt vmcnt(16)
	ds_write_b32 v234, v215 offset:3960
	s_waitcnt vmcnt(15)
	ds_write_b32 v234, v216 offset:4224
	s_waitcnt vmcnt(14)
	ds_write_b32 v234, v217 offset:4488
	s_waitcnt vmcnt(13)
	ds_write_b32 v234, v218 offset:4752
	s_waitcnt vmcnt(12)
	ds_write_b32 v234, v219 offset:5016
	s_waitcnt vmcnt(11)
	ds_write_b32 v234, v220 offset:5280
	s_waitcnt vmcnt(10)
	ds_write_b32 v234, v221 offset:5544
	s_waitcnt vmcnt(9)
	ds_write_b32 v234, v222 offset:5808
	s_waitcnt vmcnt(8)
	ds_write_b32 v234, v223 offset:6072
	s_waitcnt vmcnt(7)
	ds_write_b32 v234, v224 offset:6336
	s_waitcnt vmcnt(6)
	ds_write_b32 v234, v225 offset:6600
	s_waitcnt vmcnt(5)
	ds_write_b32 v234, v226 offset:6864
	s_waitcnt vmcnt(4)
	ds_write_b32 v234, v227 offset:7128
	s_waitcnt vmcnt(3)
	ds_write_b32 v234, v228 offset:7392
	s_waitcnt vmcnt(2)
	ds_write_b32 v234, v229 offset:7656
	s_waitcnt vmcnt(1)
	ds_write_b32 v234, v230 offset:7920
	s_waitcnt vmcnt(0)
	ds_write_b32 v234, v231 offset:8184
	s_lshl_b32 s1, s1, 6
	s_and_b32 s1, s1, 0xffffff00
	s_and_b32 s5, s2, 0x60
	s_or_b32 s10, s1, s5
	v_or_b32_e32 v20, s10, v23
	v_readlane_b32 s6, v253, 62
	v_ashrrev_i32_e32 v21, 31, v20
	v_readlane_b32 s7, v253, 63
	s_waitcnt lgkmcnt(0)
	v_add_u32_e32 v29, 0x400, v25
	v_add_u32_e32 v27, 0x800, v25
	v_lshl_add_u64 v[0:1], v[20:21], 2, s[6:7]
	global_load_dword v0, v[0:1], off
	ds_read2_b32 v[30:31], v27 offset0:148 offset1:181
	s_ashr_i32 s5, s4, 31
	s_waitcnt vmcnt(0)
	v_max_f32_e32 v0, v0, v0
	v_max_f32_e32 v19, 0xda24260, v0
	v_div_scale_f32 v0, s[6:7], v19, v19, s19
	v_rcp_f32_e32 v1, v0
	v_readlane_b32 s6, v252, 7
	v_readlane_b32 s7, v252, 8
	v_fma_f32 v2, -v0, v1, 1.0
	v_fmac_f32_e32 v1, v2, v1
	v_div_scale_f32 v2, vcc, s19, v19, s19
	v_mul_f32_e32 v3, v2, v1
	v_fma_f32 v4, -v0, v3, v2
	v_fmac_f32_e32 v3, v4, v1
	v_fma_f32 v0, -v0, v3, v2
	v_div_fmas_f32 v0, v0, v1, v3
	v_div_fixup_f32 v7, v0, v19, s19
	ds_read2_b32 v[0:1], v25 offset1:33
	s_waitcnt lgkmcnt(0)
	v_mul_f32_e32 v2, v0, v7
	v_mul_f32_e32 v3, v7, v1
	ds_read2_b32 v[0:1], v25 offset0:66 offset1:99
	v_med3_f32 v3, v3, s20, v199
	v_med3_f32 v2, v2, s20, v199
	v_rndne_f32_e32 v3, v3
	v_rndne_f32_e32 v2, v2
	s_waitcnt lgkmcnt(0)
	v_mul_f32_e32 v0, v7, v0
	v_mul_f32_e32 v1, v7, v1
	v_med3_f32 v0, v0, s20, v199
	v_cvt_i32_f32_e32 v3, v3
	v_rndne_f32_e32 v0, v0
	v_med3_f32 v1, v1, s20, v199
	v_cvt_i32_f32_e32 v2, v2
	v_cvt_i32_f32_sdwa v0, v0 dst_sel:WORD_1 dst_unused:UNUSED_PAD src0_sel:DWORD
	v_rndne_f32_e32 v1, v1
	v_cvt_i32_f32_sdwa v1, v1 dst_sel:BYTE_3 dst_unused:UNUSED_PAD src0_sel:DWORD
	v_lshlrev_b32_e32 v3, 8, v3
	v_perm_b32 v2, v3, v2, s21
	v_and_b32_e32 v0, 0xff0000, v0
	v_or3_b32 v0, v2, v0, v1
	ds_read2_b32 v[2:3], v25 offset0:132 offset1:165
	s_waitcnt lgkmcnt(0)
	v_mul_f32_e32 v1, v7, v2
	v_mul_f32_e32 v4, v7, v3
	ds_read2_b32 v[2:3], v25 offset0:198 offset1:231
	v_med3_f32 v4, v4, s20, v199
	v_med3_f32 v1, v1, s20, v199
	v_rndne_f32_e32 v4, v4
	v_rndne_f32_e32 v1, v1
	s_waitcnt lgkmcnt(0)
	v_mul_f32_e32 v2, v7, v2
	v_mul_f32_e32 v3, v7, v3
	v_med3_f32 v2, v2, s20, v199
	v_cvt_i32_f32_e32 v4, v4
	v_rndne_f32_e32 v2, v2
	v_med3_f32 v3, v3, s20, v199
	v_cvt_i32_f32_e32 v1, v1
	v_cvt_i32_f32_sdwa v2, v2 dst_sel:WORD_1 dst_unused:UNUSED_PAD src0_sel:DWORD
	v_rndne_f32_e32 v3, v3
	v_cvt_i32_f32_sdwa v3, v3 dst_sel:BYTE_3 dst_unused:UNUSED_PAD src0_sel:DWORD
	v_lshlrev_b32_e32 v4, 8, v4
	v_perm_b32 v1, v4, v1, s21
	v_and_b32_e32 v2, 0xff0000, v2
	v_or3_b32 v1, v1, v2, v3
	ds_read2_b32 v[2:3], v29 offset0:8 offset1:41
	s_waitcnt lgkmcnt(0)
	v_mul_f32_e32 v4, v7, v2
	v_mul_f32_e32 v5, v7, v3
	ds_read2_b32 v[2:3], v29 offset0:74 offset1:107
	v_med3_f32 v5, v5, s20, v199
	v_med3_f32 v4, v4, s20, v199
	v_rndne_f32_e32 v5, v5
	v_rndne_f32_e32 v4, v4
	s_waitcnt lgkmcnt(0)
	v_mul_f32_e32 v2, v7, v2
	v_mul_f32_e32 v3, v7, v3
	v_med3_f32 v2, v2, s20, v199
	v_cvt_i32_f32_e32 v5, v5
	v_rndne_f32_e32 v2, v2
	v_med3_f32 v3, v3, s20, v199
	v_cvt_i32_f32_e32 v4, v4
	v_cvt_i32_f32_sdwa v2, v2 dst_sel:WORD_1 dst_unused:UNUSED_PAD src0_sel:DWORD
	v_rndne_f32_e32 v3, v3
	v_cvt_i32_f32_sdwa v3, v3 dst_sel:BYTE_3 dst_unused:UNUSED_PAD src0_sel:DWORD
	v_lshlrev_b32_e32 v5, 8, v5
	v_perm_b32 v4, v5, v4, s21
	v_and_b32_e32 v2, 0xff0000, v2
	v_or3_b32 v2, v4, v2, v3
	ds_read2_b32 v[4:5], v29 offset0:140 offset1:173
	s_waitcnt lgkmcnt(0)
	v_mul_f32_e32 v3, v7, v4
	v_mul_f32_e32 v6, v7, v5
	ds_read2_b32 v[4:5], v29 offset0:206 offset1:239
	v_med3_f32 v6, v6, s20, v199
	v_med3_f32 v3, v3, s20, v199
	v_rndne_f32_e32 v6, v6
	v_rndne_f32_e32 v3, v3
	s_waitcnt lgkmcnt(0)
	v_mul_f32_e32 v4, v7, v4
	v_mul_f32_e32 v5, v7, v5
	v_med3_f32 v4, v4, s20, v199
	v_cvt_i32_f32_e32 v6, v6
	v_rndne_f32_e32 v4, v4
	v_med3_f32 v5, v5, s20, v199
	v_cvt_i32_f32_e32 v3, v3
	v_cvt_i32_f32_sdwa v4, v4 dst_sel:WORD_1 dst_unused:UNUSED_PAD src0_sel:DWORD
	v_rndne_f32_e32 v5, v5
	v_cvt_i32_f32_sdwa v5, v5 dst_sel:BYTE_3 dst_unused:UNUSED_PAD src0_sel:DWORD
	v_lshlrev_b32_e32 v6, 8, v6
	v_perm_b32 v3, v6, v3, s21
	v_and_b32_e32 v4, 0xff0000, v4
	v_or3_b32 v3, v3, v4, v5
	ds_read2_b32 v[4:5], v27 offset0:16 offset1:49
	s_waitcnt lgkmcnt(0)
	v_mul_f32_e32 v6, v7, v4
	v_mul_f32_e32 v28, v7, v5
	ds_read2_b32 v[4:5], v27 offset0:82 offset1:115
	v_med3_f32 v28, v28, s20, v199
	v_med3_f32 v6, v6, s20, v199
	v_rndne_f32_e32 v28, v28
	v_rndne_f32_e32 v6, v6
	s_waitcnt lgkmcnt(0)
	v_mul_f32_e32 v4, v7, v4
	v_mul_f32_e32 v5, v7, v5
	v_med3_f32 v4, v4, s20, v199
	v_cvt_i32_f32_e32 v28, v28
	v_rndne_f32_e32 v4, v4
	v_med3_f32 v5, v5, s20, v199
	v_cvt_i32_f32_e32 v6, v6
	v_cvt_i32_f32_sdwa v4, v4 dst_sel:WORD_1 dst_unused:UNUSED_PAD src0_sel:DWORD
	v_rndne_f32_e32 v5, v5
	v_cvt_i32_f32_sdwa v5, v5 dst_sel:BYTE_3 dst_unused:UNUSED_PAD src0_sel:DWORD
	v_lshlrev_b32_e32 v28, 8, v28
	v_perm_b32 v6, v28, v6, s21
	v_and_b32_e32 v4, 0xff0000, v4
	v_or3_b32 v4, v6, v4, v5
	v_mul_f32_e32 v6, v7, v31
	v_mul_f32_e32 v5, v7, v30
	v_med3_f32 v6, v6, s20, v199
	ds_read2_b32 v[30:31], v27 offset0:214 offset1:247
	v_med3_f32 v5, v5, s20, v199
	v_rndne_f32_e32 v6, v6
	v_rndne_f32_e32 v5, v5
	v_cvt_i32_f32_e32 v6, v6
	v_cvt_i32_f32_e32 v5, v5
	s_waitcnt lgkmcnt(0)
	v_mul_f32_e32 v28, v7, v30
	v_mul_f32_e32 v30, v7, v31
	v_lshlrev_b32_e32 v6, 8, v6
	v_perm_b32 v5, v6, v5, s21
	v_med3_f32 v6, v28, s20, v199
	v_rndne_f32_e32 v6, v6
	v_med3_f32 v28, v30, s20, v199
	v_cvt_i32_f32_sdwa v6, v6 dst_sel:WORD_1 dst_unused:UNUSED_PAD src0_sel:DWORD
	v_rndne_f32_e32 v28, v28
	v_cvt_i32_f32_sdwa v28, v28 dst_sel:BYTE_3 dst_unused:UNUSED_PAD src0_sel:DWORD
	v_and_b32_e32 v6, 0xff0000, v6
	v_or3_b32 v5, v5, v6, v28
	v_add_u32_e32 v28, 0xc00, v25
	ds_read2_b32 v[30:31], v28 offset0:24 offset1:57
	s_waitcnt lgkmcnt(0)
	v_mul_f32_e32 v6, v7, v30
	v_mul_f32_e32 v32, v7, v31
	ds_read2_b32 v[30:31], v28 offset0:90 offset1:123
	v_med3_f32 v32, v32, s20, v199
	v_med3_f32 v6, v6, s20, v199
	v_rndne_f32_e32 v32, v32
	v_rndne_f32_e32 v6, v6
	s_waitcnt lgkmcnt(0)
	v_mul_f32_e32 v30, v7, v30
	v_mul_f32_e32 v31, v7, v31
	v_med3_f32 v30, v30, s20, v199
	v_cvt_i32_f32_e32 v32, v32
	v_rndne_f32_e32 v30, v30
	v_med3_f32 v31, v31, s20, v199
	v_cvt_i32_f32_e32 v6, v6
	v_cvt_i32_f32_sdwa v30, v30 dst_sel:WORD_1 dst_unused:UNUSED_PAD src0_sel:DWORD
	v_rndne_f32_e32 v31, v31
	v_cvt_i32_f32_sdwa v31, v31 dst_sel:BYTE_3 dst_unused:UNUSED_PAD src0_sel:DWORD
	v_lshlrev_b32_e32 v32, 8, v32
	v_perm_b32 v6, v32, v6, s21
	v_and_b32_e32 v30, 0xff0000, v30
	v_or3_b32 v6, v6, v30, v31
	ds_read2_b32 v[30:31], v28 offset0:156 offset1:189
	s_waitcnt lgkmcnt(0)
	v_mul_f32_e32 v32, v7, v30
	v_mul_f32_e32 v33, v7, v31
	ds_read2_b32 v[30:31], v28 offset0:222 offset1:255
	s_waitcnt lgkmcnt(0)
	v_mul_f32_e32 v30, v7, v30
	v_mul_f32_e32 v7, v7, v31
	v_med3_f32 v31, v32, s20, v199
	v_med3_f32 v32, v33, s20, v199
	v_rndne_f32_e32 v32, v32
	v_med3_f32 v30, v30, s20, v199
	v_rndne_f32_e32 v31, v31
	v_cvt_i32_f32_e32 v32, v32
	v_rndne_f32_e32 v30, v30
	v_med3_f32 v7, v7, s20, v199
	v_cvt_i32_f32_e32 v31, v31
	v_cvt_i32_f32_sdwa v30, v30 dst_sel:WORD_1 dst_unused:UNUSED_PAD src0_sel:DWORD
	v_rndne_f32_e32 v7, v7
	v_cvt_i32_f32_sdwa v7, v7 dst_sel:BYTE_3 dst_unused:UNUSED_PAD src0_sel:DWORD
	v_lshlrev_b32_e32 v32, 8, v32
	v_perm_b32 v31, v32, v31, s21
	v_and_b32_e32 v30, 0xff0000, v30
	v_or3_b32 v7, v31, v30, v7
	v_lshlrev_b64 v[30:31], 11, v[20:21]
	v_lshl_add_u64 v[30:31], s[6:7], 0, v[30:31]
	v_lshl_add_u64 v[30:31], v[30:31], 0, s[4:5]
	v_lshl_add_u64 v[30:31], v[30:31], 0, v[148:149]
	global_store_dwordx4 v[30:31], v[0:3], off
	global_store_dwordx4 v[30:31], v[4:7], off offset:16
	s_nop 0
	v_or_b32_e32 v0, s0, v24
	v_cmp_eq_u32_e64 s[0:1], 0, v0
	s_and_saveexec_b64 s[6:7], s[0:1]
	s_cbranch_execz .LBB0_1382
	v_mul_f32_e32 v2, 0x3c010204, v19
	v_lshl_add_u64 v[0:1], v[20:21], 2, s[16:17]
	global_store_dword v[0:1], v2, off
.LBB0_1382:
	s_or_b64 exec, exec, s[6:7]
	s_waitcnt lgkmcnt(0)
	v_lshl_add_u64 v[0:1], s[2:3], 2, v[16:17]
	s_mov_b32 s2, 1
	s_mov_b32 s3, 0
	s_mov_b32 s6, 32
	v_mad_i64_i32 v[232:233], s[12:13], v18, s82, v[0:1]
	v_mad_u64_u32 v[234:235], s[12:13], v8, s18, v[10:11]
	s_nop 4
	s_lshl_b32 s12, s82, 1
	s_ashr_i32 s13, s12, 31
	global_load_dword v200, v[232:233], off
	v_lshl_add_u64 v[232:233], v[232:233], 0, s[12:13]
	global_load_dword v201, v[232:233], off
	v_lshl_add_u64 v[232:233], v[232:233], 0, s[12:13]
	global_load_dword v202, v[232:233], off
	v_lshl_add_u64 v[232:233], v[232:233], 0, s[12:13]
	global_load_dword v203, v[232:233], off
	v_lshl_add_u64 v[232:233], v[232:233], 0, s[12:13]
	global_load_dword v204, v[232:233], off
	v_lshl_add_u64 v[232:233], v[232:233], 0, s[12:13]
	global_load_dword v205, v[232:233], off
	v_lshl_add_u64 v[232:233], v[232:233], 0, s[12:13]
	global_load_dword v206, v[232:233], off
	v_lshl_add_u64 v[232:233], v[232:233], 0, s[12:13]
	global_load_dword v207, v[232:233], off
	v_lshl_add_u64 v[232:233], v[232:233], 0, s[12:13]
	global_load_dword v208, v[232:233], off
	v_lshl_add_u64 v[232:233], v[232:233], 0, s[12:13]
	global_load_dword v209, v[232:233], off
	v_lshl_add_u64 v[232:233], v[232:233], 0, s[12:13]
	global_load_dword v210, v[232:233], off
	v_lshl_add_u64 v[232:233], v[232:233], 0, s[12:13]
	global_load_dword v211, v[232:233], off
	v_lshl_add_u64 v[232:233], v[232:233], 0, s[12:13]
	global_load_dword v212, v[232:233], off
	v_lshl_add_u64 v[232:233], v[232:233], 0, s[12:13]
	global_load_dword v213, v[232:233], off
	v_lshl_add_u64 v[232:233], v[232:233], 0, s[12:13]
	global_load_dword v214, v[232:233], off
	v_lshl_add_u64 v[232:233], v[232:233], 0, s[12:13]
	global_load_dword v215, v[232:233], off
	v_lshl_add_u64 v[232:233], v[232:233], 0, s[12:13]
	global_load_dword v216, v[232:233], off
	v_lshl_add_u64 v[232:233], v[232:233], 0, s[12:13]
	global_load_dword v217, v[232:233], off
	v_lshl_add_u64 v[232:233], v[232:233], 0, s[12:13]
	global_load_dword v218, v[232:233], off
	v_lshl_add_u64 v[232:233], v[232:233], 0, s[12:13]
	global_load_dword v219, v[232:233], off
	v_lshl_add_u64 v[232:233], v[232:233], 0, s[12:13]
	global_load_dword v220, v[232:233], off
	v_lshl_add_u64 v[232:233], v[232:233], 0, s[12:13]
	global_load_dword v221, v[232:233], off
	v_lshl_add_u64 v[232:233], v[232:233], 0, s[12:13]
	global_load_dword v222, v[232:233], off
	v_lshl_add_u64 v[232:233], v[232:233], 0, s[12:13]
	global_load_dword v223, v[232:233], off
	v_lshl_add_u64 v[232:233], v[232:233], 0, s[12:13]
	global_load_dword v224, v[232:233], off
	v_lshl_add_u64 v[232:233], v[232:233], 0, s[12:13]
	global_load_dword v225, v[232:233], off
	v_lshl_add_u64 v[232:233], v[232:233], 0, s[12:13]
	global_load_dword v226, v[232:233], off
	v_lshl_add_u64 v[232:233], v[232:233], 0, s[12:13]
	global_load_dword v227, v[232:233], off
	v_lshl_add_u64 v[232:233], v[232:233], 0, s[12:13]
	global_load_dword v228, v[232:233], off
	v_lshl_add_u64 v[232:233], v[232:233], 0, s[12:13]
	global_load_dword v229, v[232:233], off
	v_lshl_add_u64 v[232:233], v[232:233], 0, s[12:13]
	global_load_dword v230, v[232:233], off
	v_lshl_add_u64 v[232:233], v[232:233], 0, s[12:13]
	global_load_dword v231, v[232:233], off
	s_waitcnt vmcnt(31)
	ds_write_b32 v234, v200
	s_waitcnt vmcnt(30)
	ds_write_b32 v234, v201 offset:264
	s_waitcnt vmcnt(29)
	ds_write_b32 v234, v202 offset:528
	s_waitcnt vmcnt(28)
	ds_write_b32 v234, v203 offset:792
	s_waitcnt vmcnt(27)
	ds_write_b32 v234, v204 offset:1056
	s_waitcnt vmcnt(26)
	ds_write_b32 v234, v205 offset:1320
	s_waitcnt vmcnt(25)
	ds_write_b32 v234, v206 offset:1584
	s_waitcnt vmcnt(24)
	ds_write_b32 v234, v207 offset:1848
	s_waitcnt vmcnt(23)
	ds_write_b32 v234, v208 offset:2112
	s_waitcnt vmcnt(22)
	ds_write_b32 v234, v209 offset:2376
	s_waitcnt vmcnt(21)
	ds_write_b32 v234, v210 offset:2640
	s_waitcnt vmcnt(20)
	ds_write_b32 v234, v211 offset:2904
	s_waitcnt vmcnt(19)
	ds_write_b32 v234, v212 offset:3168
	s_waitcnt vmcnt(18)
	ds_write_b32 v234, v213 offset:3432
	s_waitcnt vmcnt(17)
	ds_write_b32 v234, v214 offset:3696
	s_waitcnt vmcnt(16)
	ds_write_b32 v234, v215 offset:3960
	s_waitcnt vmcnt(15)
	ds_write_b32 v234, v216 offset:4224
	s_waitcnt vmcnt(14)
	ds_write_b32 v234, v217 offset:4488
	s_waitcnt vmcnt(13)
	ds_write_b32 v234, v218 offset:4752
	s_waitcnt vmcnt(12)
	ds_write_b32 v234, v219 offset:5016
	s_waitcnt vmcnt(11)
	ds_write_b32 v234, v220 offset:5280
	s_waitcnt vmcnt(10)
	ds_write_b32 v234, v221 offset:5544
	s_waitcnt vmcnt(9)
	ds_write_b32 v234, v222 offset:5808
	s_waitcnt vmcnt(8)
	ds_write_b32 v234, v223 offset:6072
	s_waitcnt vmcnt(7)
	ds_write_b32 v234, v224 offset:6336
	s_waitcnt vmcnt(6)
	ds_write_b32 v234, v225 offset:6600
	s_waitcnt vmcnt(5)
	ds_write_b32 v234, v226 offset:6864
	s_waitcnt vmcnt(4)
	ds_write_b32 v234, v227 offset:7128
	s_waitcnt vmcnt(3)
	ds_write_b32 v234, v228 offset:7392
	s_waitcnt vmcnt(2)
	ds_write_b32 v234, v229 offset:7656
	s_waitcnt vmcnt(1)
	ds_write_b32 v234, v230 offset:7920
	s_waitcnt vmcnt(0)
	ds_write_b32 v234, v231 offset:8184
	v_or_b32_e32 v18, s10, v26
	v_readlane_b32 s2, v253, 62
	v_ashrrev_i32_e32 v19, 31, v18
	v_readlane_b32 s3, v253, 63
	s_waitcnt lgkmcnt(0)
	s_nop 1
	v_lshl_add_u64 v[0:1], v[18:19], 2, s[2:3]
	global_load_dword v0, v[0:1], off
	s_waitcnt vmcnt(0)
	v_max_f32_e32 v0, v0, v0
	v_max_f32_e32 v11, 0xda24260, v0
	v_div_scale_f32 v0, s[2:3], v11, v11, s19
	v_rcp_f32_e32 v1, v0
	v_readlane_b32 s2, v252, 7
	v_readlane_b32 s3, v252, 8
	v_fma_f32 v2, -v0, v1, 1.0
	v_fmac_f32_e32 v1, v2, v1
	v_div_scale_f32 v2, vcc, s19, v11, s19
	v_mul_f32_e32 v3, v2, v1
	v_fma_f32 v4, -v0, v3, v2
	v_fmac_f32_e32 v3, v4, v1
	v_fma_f32 v0, -v0, v3, v2
	v_div_fmas_f32 v0, v0, v1, v3
	v_div_fixup_f32 v7, v0, v11, s19
	ds_read2_b32 v[0:1], v25 offset1:33
	s_waitcnt lgkmcnt(0)
	v_mul_f32_e32 v2, v0, v7
	v_mul_f32_e32 v3, v7, v1
	ds_read2_b32 v[0:1], v25 offset0:66 offset1:99
	v_med3_f32 v3, v3, s20, v199
	v_med3_f32 v2, v2, s20, v199
	v_rndne_f32_e32 v3, v3
	v_rndne_f32_e32 v2, v2
	s_waitcnt lgkmcnt(0)
	v_mul_f32_e32 v0, v7, v0
	v_mul_f32_e32 v1, v7, v1
	v_med3_f32 v0, v0, s20, v199
	v_cvt_i32_f32_e32 v3, v3
	v_rndne_f32_e32 v0, v0
	v_med3_f32 v1, v1, s20, v199
	v_cvt_i32_f32_e32 v2, v2
	v_cvt_i32_f32_sdwa v0, v0 dst_sel:WORD_1 dst_unused:UNUSED_PAD src0_sel:DWORD
	v_rndne_f32_e32 v1, v1
	v_cvt_i32_f32_sdwa v1, v1 dst_sel:BYTE_3 dst_unused:UNUSED_PAD src0_sel:DWORD
	v_lshlrev_b32_e32 v3, 8, v3
	v_perm_b32 v2, v3, v2, s21
	v_and_b32_e32 v0, 0xff0000, v0
	v_or3_b32 v0, v2, v0, v1
	ds_read2_b32 v[2:3], v25 offset0:132 offset1:165
	s_waitcnt lgkmcnt(0)
	v_mul_f32_e32 v1, v7, v2
	v_mul_f32_e32 v4, v7, v3
	ds_read2_b32 v[2:3], v25 offset0:198 offset1:231
	v_med3_f32 v4, v4, s20, v199
	v_med3_f32 v1, v1, s20, v199
	v_rndne_f32_e32 v4, v4
	v_rndne_f32_e32 v1, v1
	s_waitcnt lgkmcnt(0)
	v_mul_f32_e32 v2, v7, v2
	v_mul_f32_e32 v3, v7, v3
	v_med3_f32 v2, v2, s20, v199
	v_cvt_i32_f32_e32 v4, v4
	v_rndne_f32_e32 v2, v2
	v_med3_f32 v3, v3, s20, v199
	v_cvt_i32_f32_e32 v1, v1
	v_cvt_i32_f32_sdwa v2, v2 dst_sel:WORD_1 dst_unused:UNUSED_PAD src0_sel:DWORD
	v_rndne_f32_e32 v3, v3
	v_cvt_i32_f32_sdwa v3, v3 dst_sel:BYTE_3 dst_unused:UNUSED_PAD src0_sel:DWORD
	v_lshlrev_b32_e32 v4, 8, v4
	v_perm_b32 v1, v4, v1, s21
	v_and_b32_e32 v2, 0xff0000, v2
	v_or3_b32 v1, v1, v2, v3
	ds_read2_b32 v[2:3], v29 offset0:8 offset1:41
	s_waitcnt lgkmcnt(0)
	v_mul_f32_e32 v4, v7, v2
	v_mul_f32_e32 v5, v7, v3
	ds_read2_b32 v[2:3], v29 offset0:74 offset1:107
	v_med3_f32 v5, v5, s20, v199
	v_med3_f32 v4, v4, s20, v199
	v_rndne_f32_e32 v5, v5
	v_rndne_f32_e32 v4, v4
	s_waitcnt lgkmcnt(0)
	v_mul_f32_e32 v2, v7, v2
	v_mul_f32_e32 v3, v7, v3
	v_med3_f32 v2, v2, s20, v199
	v_cvt_i32_f32_e32 v5, v5
	v_rndne_f32_e32 v2, v2
	v_med3_f32 v3, v3, s20, v199
	v_cvt_i32_f32_e32 v4, v4
	v_cvt_i32_f32_sdwa v2, v2 dst_sel:WORD_1 dst_unused:UNUSED_PAD src0_sel:DWORD
	v_rndne_f32_e32 v3, v3
	v_cvt_i32_f32_sdwa v3, v3 dst_sel:BYTE_3 dst_unused:UNUSED_PAD src0_sel:DWORD
	v_lshlrev_b32_e32 v5, 8, v5
	v_perm_b32 v4, v5, v4, s21
	v_and_b32_e32 v2, 0xff0000, v2
	v_or3_b32 v2, v4, v2, v3
	ds_read2_b32 v[4:5], v29 offset0:140 offset1:173
	s_waitcnt lgkmcnt(0)
	v_mul_f32_e32 v3, v7, v4
	v_mul_f32_e32 v6, v7, v5
	ds_read2_b32 v[4:5], v29 offset0:206 offset1:239
	v_med3_f32 v6, v6, s20, v199
	v_med3_f32 v3, v3, s20, v199
	v_rndne_f32_e32 v6, v6
	v_rndne_f32_e32 v3, v3
	s_waitcnt lgkmcnt(0)
	v_mul_f32_e32 v4, v7, v4
	v_mul_f32_e32 v5, v7, v5
	v_med3_f32 v4, v4, s20, v199
	v_cvt_i32_f32_e32 v6, v6
	v_rndne_f32_e32 v4, v4
	v_med3_f32 v5, v5, s20, v199
	v_cvt_i32_f32_e32 v3, v3
	v_cvt_i32_f32_sdwa v4, v4 dst_sel:WORD_1 dst_unused:UNUSED_PAD src0_sel:DWORD
	v_rndne_f32_e32 v5, v5
	v_cvt_i32_f32_sdwa v5, v5 dst_sel:BYTE_3 dst_unused:UNUSED_PAD src0_sel:DWORD
	v_lshlrev_b32_e32 v6, 8, v6
	v_perm_b32 v3, v6, v3, s21
	v_and_b32_e32 v4, 0xff0000, v4
	v_or3_b32 v3, v3, v4, v5
	ds_read2_b32 v[4:5], v27 offset0:16 offset1:49
	s_waitcnt lgkmcnt(0)
	v_mul_f32_e32 v6, v7, v4
	v_mul_f32_e32 v20, v7, v5
	ds_read2_b32 v[4:5], v27 offset0:82 offset1:115
	v_med3_f32 v20, v20, s20, v199
	v_med3_f32 v6, v6, s20, v199
	v_rndne_f32_e32 v20, v20
	v_rndne_f32_e32 v6, v6
	v_cvt_i32_f32_e32 v20, v20
	v_cvt_i32_f32_e32 v6, v6
	s_waitcnt lgkmcnt(0)
	v_mul_f32_e32 v4, v7, v4
	v_mul_f32_e32 v5, v7, v5
	v_med3_f32 v4, v4, s20, v199
	v_lshlrev_b32_e32 v20, 8, v20
	v_rndne_f32_e32 v4, v4
	v_med3_f32 v5, v5, s20, v199
	v_perm_b32 v6, v20, v6, s21
	v_cvt_i32_f32_sdwa v4, v4 dst_sel:WORD_1 dst_unused:UNUSED_PAD src0_sel:DWORD
	v_rndne_f32_e32 v5, v5
	ds_read2_b32 v[20:21], v27 offset0:148 offset1:181
	v_cvt_i32_f32_sdwa v5, v5 dst_sel:BYTE_3 dst_unused:UNUSED_PAD src0_sel:DWORD
	v_and_b32_e32 v4, 0xff0000, v4
	v_or3_b32 v4, v6, v4, v5
	s_waitcnt lgkmcnt(0)
	v_mul_f32_e32 v6, v7, v21
	v_mul_f32_e32 v5, v7, v20
	v_med3_f32 v6, v6, s20, v199
	ds_read2_b32 v[20:21], v27 offset0:214 offset1:247
	v_med3_f32 v5, v5, s20, v199
	v_rndne_f32_e32 v6, v6
	v_rndne_f32_e32 v5, v5
	v_cvt_i32_f32_e32 v6, v6
	v_cvt_i32_f32_e32 v5, v5
	s_waitcnt lgkmcnt(0)
	v_mul_f32_e32 v20, v7, v20
	v_mul_f32_e32 v21, v7, v21
	v_lshlrev_b32_e32 v6, 8, v6
	v_perm_b32 v5, v6, v5, s21
	v_med3_f32 v6, v20, s20, v199
	v_rndne_f32_e32 v6, v6
	v_med3_f32 v20, v21, s20, v199
	v_cvt_i32_f32_sdwa v6, v6 dst_sel:WORD_1 dst_unused:UNUSED_PAD src0_sel:DWORD
	v_rndne_f32_e32 v20, v20
	v_cvt_i32_f32_sdwa v20, v20 dst_sel:BYTE_3 dst_unused:UNUSED_PAD src0_sel:DWORD
	v_and_b32_e32 v6, 0xff0000, v6
	v_or3_b32 v5, v5, v6, v20
	ds_read2_b32 v[20:21], v28 offset0:24 offset1:57
	s_waitcnt lgkmcnt(0)
	v_mul_f32_e32 v6, v7, v20
	v_mul_f32_e32 v27, v7, v21
	ds_read2_b32 v[20:21], v28 offset0:90 offset1:123
	v_med3_f32 v27, v27, s20, v199
	v_med3_f32 v6, v6, s20, v199
	v_rndne_f32_e32 v27, v27
	v_rndne_f32_e32 v6, v6
	s_waitcnt lgkmcnt(0)
	v_mul_f32_e32 v20, v7, v20
	v_mul_f32_e32 v21, v7, v21
	v_med3_f32 v20, v20, s20, v199
	v_cvt_i32_f32_e32 v27, v27
	v_rndne_f32_e32 v20, v20
	v_med3_f32 v21, v21, s20, v199
	v_cvt_i32_f32_e32 v6, v6
	v_cvt_i32_f32_sdwa v20, v20 dst_sel:WORD_1 dst_unused:UNUSED_PAD src0_sel:DWORD
	v_rndne_f32_e32 v21, v21
	v_cvt_i32_f32_sdwa v21, v21 dst_sel:BYTE_3 dst_unused:UNUSED_PAD src0_sel:DWORD
	v_lshlrev_b32_e32 v27, 8, v27
	v_perm_b32 v6, v27, v6, s21
	v_and_b32_e32 v20, 0xff0000, v20
	v_or3_b32 v6, v6, v20, v21
	ds_read2_b32 v[20:21], v28 offset0:156 offset1:189
	s_waitcnt lgkmcnt(0)
	v_mul_f32_e32 v27, v7, v20
	v_mul_f32_e32 v29, v7, v21
	ds_read2_b32 v[20:21], v28 offset0:222 offset1:255
	s_waitcnt lgkmcnt(0)
	v_mul_f32_e32 v20, v7, v20
	v_mul_f32_e32 v7, v7, v21
	v_med3_f32 v21, v27, s20, v199
	v_med3_f32 v27, v29, s20, v199
	v_rndne_f32_e32 v27, v27
	v_med3_f32 v20, v20, s20, v199
	v_rndne_f32_e32 v21, v21
	v_cvt_i32_f32_e32 v27, v27
	v_rndne_f32_e32 v20, v20
	v_med3_f32 v7, v7, s20, v199
	v_cvt_i32_f32_e32 v21, v21
	v_cvt_i32_f32_sdwa v20, v20 dst_sel:WORD_1 dst_unused:UNUSED_PAD src0_sel:DWORD
	v_rndne_f32_e32 v7, v7
	v_cvt_i32_f32_sdwa v7, v7 dst_sel:BYTE_3 dst_unused:UNUSED_PAD src0_sel:DWORD
	v_lshlrev_b32_e32 v27, 8, v27
	v_perm_b32 v21, v27, v21, s21
	v_and_b32_e32 v20, 0xff0000, v20
	v_or3_b32 v7, v21, v20, v7
	v_lshlrev_b64 v[20:21], 11, v[18:19]
	v_lshl_add_u64 v[20:21], s[2:3], 0, v[20:21]
	v_lshl_add_u64 v[20:21], v[20:21], 0, s[4:5]
	v_lshl_add_u64 v[20:21], v[20:21], 0, v[148:149]
	global_store_dwordx4 v[20:21], v[0:3], off
	global_store_dwordx4 v[20:21], v[4:7], off offset:16
	s_and_saveexec_b64 s[2:3], s[0:1]
	s_cbranch_execz .LBB0_1377
	v_mul_f32_e32 v2, 0x3c010204, v11
	v_lshl_add_u64 v[0:1], v[18:19], 2, s[16:17]
	global_store_dword v[0:1], v2, off
	s_branch .LBB0_1377

.LBB0_1387:
	s_ashr_i32 s0, s4, 31
	s_lshr_b32 s0, s0, 26
	s_add_i32 s0, s4, s0
	s_and_b32 s2, s0, 0xffffffc0
	s_sub_i32 s0, s4, s2
	s_lshl_b32 s0, s0, 5
	s_ashr_i32 s1, s0, 31
	v_lshl_add_u64 v[4:5], s[0:1], 2, v[0:1]
	v_or_b32_e32 v7, s2, v9
	v_or_b32_e32 v6, s2, v8
	s_mov_b32 s1, 1
	s_mov_b32 s3, 0
	s_mov_b32 s5, 32
	s_movk_i32 s10, 0x84
	v_mov_b32_e32 v232, v6
	v_ashrrev_i32_e32 v233, 31, v6
	v_lshlrev_b64 v[232:233], 13, v[232:233]
	v_lshl_add_u64 v[232:233], v[4:5], 0, v[232:233]
	v_mad_u64_u32 v[234:235], s[8:9], v8, s10, v[10:11]
	s_nop 4
	s_mov_b64 s[8:9], 0x4000
	global_load_dword v200, v[232:233], off
	v_lshl_add_u64 v[232:233], v[232:233], 0, s[8:9]
	global_load_dword v201, v[232:233], off
	v_lshl_add_u64 v[232:233], v[232:233], 0, s[8:9]
	global_load_dword v202, v[232:233], off
	v_lshl_add_u64 v[232:233], v[232:233], 0, s[8:9]
	global_load_dword v203, v[232:233], off
	v_lshl_add_u64 v[232:233], v[232:233], 0, s[8:9]
	global_load_dword v204, v[232:233], off
	v_lshl_add_u64 v[232:233], v[232:233], 0, s[8:9]
	global_load_dword v205, v[232:233], off
	v_lshl_add_u64 v[232:233], v[232:233], 0, s[8:9]
	global_load_dword v206, v[232:233], off
	v_lshl_add_u64 v[232:233], v[232:233], 0, s[8:9]
	global_load_dword v207, v[232:233], off
	v_lshl_add_u64 v[232:233], v[232:233], 0, s[8:9]
	global_load_dword v208, v[232:233], off
	v_lshl_add_u64 v[232:233], v[232:233], 0, s[8:9]
	global_load_dword v209, v[232:233], off
	v_lshl_add_u64 v[232:233], v[232:233], 0, s[8:9]
	global_load_dword v210, v[232:233], off
	v_lshl_add_u64 v[232:233], v[232:233], 0, s[8:9]
	global_load_dword v211, v[232:233], off
	v_lshl_add_u64 v[232:233], v[232:233], 0, s[8:9]
	global_load_dword v212, v[232:233], off
	v_lshl_add_u64 v[232:233], v[232:233], 0, s[8:9]
	global_load_dword v213, v[232:233], off
	v_lshl_add_u64 v[232:233], v[232:233], 0, s[8:9]
	global_load_dword v214, v[232:233], off
	v_lshl_add_u64 v[232:233], v[232:233], 0, s[8:9]
	global_load_dword v215, v[232:233], off
	v_lshl_add_u64 v[232:233], v[232:233], 0, s[8:9]
	global_load_dword v216, v[232:233], off
	v_lshl_add_u64 v[232:233], v[232:233], 0, s[8:9]
	global_load_dword v217, v[232:233], off
	v_lshl_add_u64 v[232:233], v[232:233], 0, s[8:9]
	global_load_dword v218, v[232:233], off
	v_lshl_add_u64 v[232:233], v[232:233], 0, s[8:9]
	global_load_dword v219, v[232:233], off
	v_lshl_add_u64 v[232:233], v[232:233], 0, s[8:9]
	global_load_dword v220, v[232:233], off
	v_lshl_add_u64 v[232:233], v[232:233], 0, s[8:9]
	global_load_dword v221, v[232:233], off
	v_lshl_add_u64 v[232:233], v[232:233], 0, s[8:9]
	global_load_dword v222, v[232:233], off
	v_lshl_add_u64 v[232:233], v[232:233], 0, s[8:9]
	global_load_dword v223, v[232:233], off
	v_lshl_add_u64 v[232:233], v[232:233], 0, s[8:9]
	global_load_dword v224, v[232:233], off
	v_lshl_add_u64 v[232:233], v[232:233], 0, s[8:9]
	global_load_dword v225, v[232:233], off
	v_lshl_add_u64 v[232:233], v[232:233], 0, s[8:9]
	global_load_dword v226, v[232:233], off
	v_lshl_add_u64 v[232:233], v[232:233], 0, s[8:9]
	global_load_dword v227, v[232:233], off
	v_lshl_add_u64 v[232:233], v[232:233], 0, s[8:9]
	global_load_dword v228, v[232:233], off
	v_lshl_add_u64 v[232:233], v[232:233], 0, s[8:9]
	global_load_dword v229, v[232:233], off
	v_lshl_add_u64 v[232:233], v[232:233], 0, s[8:9]
	global_load_dword v230, v[232:233], off
	v_lshl_add_u64 v[232:233], v[232:233], 0, s[8:9]
	global_load_dword v231, v[232:233], off
	s_waitcnt vmcnt(31)
	ds_write_b32 v234, v200
	s_waitcnt vmcnt(30)
	ds_write_b32 v234, v201 offset:264
	s_waitcnt vmcnt(29)
	ds_write_b32 v234, v202 offset:528
	s_waitcnt vmcnt(28)
	ds_write_b32 v234, v203 offset:792
	s_waitcnt vmcnt(27)
	ds_write_b32 v234, v204 offset:1056
	s_waitcnt vmcnt(26)
	ds_write_b32 v234, v205 offset:1320
	s_waitcnt vmcnt(25)
	ds_write_b32 v234, v206 offset:1584
	s_waitcnt vmcnt(24)
	ds_write_b32 v234, v207 offset:1848
	s_waitcnt vmcnt(23)
	ds_write_b32 v234, v208 offset:2112
	s_waitcnt vmcnt(22)
	ds_write_b32 v234, v209 offset:2376
	s_waitcnt vmcnt(21)
	ds_write_b32 v234, v210 offset:2640
	s_waitcnt vmcnt(20)
	ds_write_b32 v234, v211 offset:2904
	s_waitcnt vmcnt(19)
	ds_write_b32 v234, v212 offset:3168
	s_waitcnt vmcnt(18)
	ds_write_b32 v234, v213 offset:3432
	s_waitcnt vmcnt(17)
	ds_write_b32 v234, v214 offset:3696
	s_waitcnt vmcnt(16)
	ds_write_b32 v234, v215 offset:3960
	s_waitcnt vmcnt(15)
	ds_write_b32 v234, v216 offset:4224
	s_waitcnt vmcnt(14)
	ds_write_b32 v234, v217 offset:4488
	s_waitcnt vmcnt(13)
	ds_write_b32 v234, v218 offset:4752
	s_waitcnt vmcnt(12)
	ds_write_b32 v234, v219 offset:5016
	s_waitcnt vmcnt(11)
	ds_write_b32 v234, v220 offset:5280
	s_waitcnt vmcnt(10)
	ds_write_b32 v234, v221 offset:5544
	s_waitcnt vmcnt(9)
	ds_write_b32 v234, v222 offset:5808
	s_waitcnt vmcnt(8)
	ds_write_b32 v234, v223 offset:6072
	s_waitcnt vmcnt(7)
	ds_write_b32 v234, v224 offset:6336
	s_waitcnt vmcnt(6)
	ds_write_b32 v234, v225 offset:6600
	s_waitcnt vmcnt(5)
	ds_write_b32 v234, v226 offset:6864
	s_waitcnt vmcnt(4)
	ds_write_b32 v234, v227 offset:7128
	s_waitcnt vmcnt(3)
	ds_write_b32 v234, v228 offset:7392
	s_waitcnt vmcnt(2)
	ds_write_b32 v234, v229 offset:7656
	s_waitcnt vmcnt(1)
	ds_write_b32 v234, v230 offset:7920
	s_waitcnt vmcnt(0)
	ds_write_b32 v234, v231 offset:8184
	s_waitcnt lgkmcnt(0)
	ds_read2_b32 v[20:21], v12 offset0:33 offset1:41
	ds_read2_b32 v[24:25], v12 offset1:8
	ds_read2_b32 v[26:27], v12 offset0:66 offset1:74
	ds_read2_b32 v[28:29], v12 offset0:99 offset1:107
	ds_read2_b32 v[30:31], v12 offset0:132 offset1:140
	ds_read2_b32 v[32:33], v12 offset0:165 offset1:173
	ds_read2_b32 v[34:35], v12 offset0:198 offset1:206
	ds_read2_b32 v[36:37], v12 offset0:231 offset1:239
	v_or_b32_e32 v17, s0, v11
	s_movk_i32 s1, 0x1600
	s_ashr_i32 s3, s2, 31
	v_mul_lo_u32 v38, v17, s1
	v_lshl_add_u64 v[18:19], s[2:3], 1, v[2:3]
	v_ashrrev_i32_e32 v39, 31, v38
	v_or_b32_e32 v17, s0, v14
	s_waitcnt lgkmcnt(6)
	v_cvt_pk_bf16_f32 v4, v24, v20
	s_waitcnt lgkmcnt(4)
	v_cvt_pk_bf16_f32 v5, v26, v28
	s_waitcnt lgkmcnt(2)
	v_cvt_pk_bf16_f32 v6, v30, v32
	s_waitcnt lgkmcnt(0)
	v_cvt_pk_bf16_f32 v7, v34, v36
	v_lshl_add_u64 v[38:39], v[38:39], 1, v[18:19]
	v_mul_lo_u32 v20, v17, s1
	global_store_dwordx4 v[38:39], v[4:7], off
	v_or_b32_e32 v17, s0, v15
	v_mul_lo_u32 v38, v17, s1
	v_cvt_pk_bf16_f32 v4, v25, v21
	v_ashrrev_i32_e32 v21, 31, v20
	v_cvt_pk_bf16_f32 v5, v27, v29
	v_cvt_pk_bf16_f32 v6, v31, v33
	v_cvt_pk_bf16_f32 v7, v35, v37
	v_lshl_add_u64 v[20:21], v[20:21], 1, v[18:19]
	global_store_dwordx4 v[20:21], v[4:7], off
	ds_read2_b32 v[20:21], v12 offset0:49 offset1:57
	ds_read2_b32 v[24:25], v12 offset0:16 offset1:24
	ds_read2_b32 v[26:27], v12 offset0:82 offset1:90
	ds_read2_b32 v[28:29], v12 offset0:115 offset1:123
	ds_read2_b32 v[30:31], v12 offset0:148 offset1:156
	ds_read2_b32 v[32:33], v12 offset0:181 offset1:189
	ds_read2_b32 v[34:35], v12 offset0:214 offset1:222
	ds_read2_b32 v[36:37], v12 offset0:247 offset1:255
	v_ashrrev_i32_e32 v39, 31, v38
	v_or_b32_e32 v17, s0, v16
	s_waitcnt lgkmcnt(6)
	v_cvt_pk_bf16_f32 v4, v24, v20
	s_waitcnt lgkmcnt(4)
	v_cvt_pk_bf16_f32 v5, v26, v28
	s_waitcnt lgkmcnt(2)
	v_cvt_pk_bf16_f32 v6, v30, v32
	s_waitcnt lgkmcnt(0)
	v_cvt_pk_bf16_f32 v7, v34, v36
	v_lshl_add_u64 v[38:39], v[38:39], 1, v[18:19]
	v_mul_lo_u32 v20, v17, s1
	global_store_dwordx4 v[38:39], v[4:7], off
	v_readlane_b32 s0, v252, 5
	s_add_i32 s4, s4, s0
	v_cvt_pk_bf16_f32 v4, v25, v21
	v_ashrrev_i32_e32 v21, 31, v20
	v_cvt_pk_bf16_f32 v5, v27, v29
	v_cvt_pk_bf16_f32 v6, v31, v33
	v_cvt_pk_bf16_f32 v7, v35, v37
	v_lshl_add_u64 v[18:19], v[20:21], 1, v[18:19]
	global_store_dwordx4 v[18:19], v[4:7], off
	s_waitcnt lgkmcnt(0)
	s_cmpk_gt_i32 s4, 0x15ff
	v_readlane_b32 s1, v252, 6
	s_cbranch_scc0 .LBB0_1387
